# GEMM loops: redundant lgkmcnt(0) at MFMA-segment head removed; s_barrier issued before s_setprio 0 at segment end
# speedup vs baseline: 1.0275x; 1.0023x over previous
; #define PG8_STAGE(bufoff, gbase, voff) do { _Pragma("unroll") for (int _i = 0; _i < 2; ++_i) \
;         __builtin_amdgcn_global_load_lds((const unsigned*)((const char*)(gbase) + (voff)[_i]), (PG8_LAS unsigned*)(lds + (bufoff) + ldsw + _i * 8192), 16, 0, 0); } while (0)
; #define PG8_LDA(dst, b, h) do { _Pragma("unroll") for (int m = 0; m < 4; ++m) _Pragma("unroll") for (int k = 0; k < 2; ++k) dst[m][k] = *(const PG8_LAS bf16x8*)(lds + PG8_SA(b, h) + aoff + m * 2048 + k * 1024); } while (0)
; #define PG8_LDB(dst, b, h) do { _Pragma("unroll") for (int n = 0; n < 2; ++n) _Pragma("unroll") for (int k = 0; k < 2; ++k) dst[n][k] = *(const PG8_LAS bf16x8*)(lds + PG8_SB(b, h) + boff + n * 2048 + k * 1024); } while (0)
; #define PG8_MMA(ai, bj, At, Bt) do { __builtin_amdgcn_s_setprio(1); _Pragma("unroll") for (int m = 0; m < 4; ++m) _Pragma("unroll") for (int n = 0; n < 2; ++n) _Pragma("unroll") for (int k = 0; k < 2; ++k) \
;         acc[ai][bj][m][n] = __builtin_amdgcn_mfma_f32_16x16x32_bf16(Bt[n][k], At[m][k], acc[ai][bj][m][n], 0, 0, 0); __builtin_amdgcn_s_setprio(0); } while (0)
; #define PG8_WAIT_V(n) asm volatile("s_waitcnt vmcnt(" #n ")" ::: "memory")
; #define PG8_WAIT_L(n) asm volatile("s_waitcnt lgkmcnt(" #n ")" ::: "memory")
; #define PG8_BAR __builtin_amdgcn_s_barrier()
; #define PG8_SCHED __builtin_amdgcn_sched_barrier(0)
;     ...
;             const bool last = (t == nt - 2);
;             const char* a1 = PG8_KADV(cA, (size_t)(t + 1) * kstep);
;             const char* a2 = last ? nA : PG8_KADV(cA, (size_t)(t + 2) * kstep); const char* b2 = last ? nB : PG8_KADV(cB, (size_t)(t + 2) * kstep);
;             const char* a3 = PG8_KADV(a2, kstep); const char* b3 = PG8_KADV(b2, kstep);
;             if (last && has_next) S.a_ready(nxt);
;             if constexpr (SP2) {
;             PG8_LDB(B0, 0, 0); PG8_LDB(B1, 0, 1); PG8_SCHED; PG8_LDA(At, 0, 0); PG8_STAGE(PG8_SA(1, 1), a1 + hstep, voffA);
;             PG8_WAIT_V(8); PG8_WAIT_L(0); PG8_BAR; PG8_MMA(0, 0, At, B0); PG8_MMA(0, 1, At, B1); PG8_BAR; PG8_SCHED;
;             PG8_LDA(At, 0, 1); PG8_STAGE(PG8_SB(0, 0), b2, voffB); PG8_STAGE(PG8_SB(0, 1), b2 + hstep, voffB); PG8_STAGE(PG8_SA(0, 0), a2, voffA);
;             PG8_WAIT_V(8); PG8_WAIT_L(0); PG8_BAR; PG8_MMA(1, 0, At, B0); PG8_MMA(1, 1, At, B1); PG8_BAR; PG8_SCHED;
.LBB0_230:
	s_add_u32 s12, s80, 0xfff80080
	s_addc_u32 s13, s81, -1
	s_add_i32 s30, 0, 0x10000
	s_cmp_eq_u32 s28, 28
	s_cselect_b32 s85, s15, s13
	s_cselect_b32 s84, s20, s12
	s_cselect_b32 s83, s21, s25
	s_cselect_b32 s82, s22, s23
	s_add_i32 s12, 0, 0x14000
	v_add_u32_e32 v156, s30, v141
	v_add_u32_e32 v168, s12, v141
	ds_read_b128 v[144:147], v156
	ds_read_b128 v[148:151], v156 offset:1024
	ds_read_b128 v[152:155], v156 offset:2048
	ds_read_b128 v[156:159], v156 offset:3072
	ds_read_b128 v[160:163], v168
	ds_read_b128 v[164:167], v168 offset:1024
	ds_read_b128 v[182:185], v168 offset:2048
	ds_read_b128 v[186:189], v168 offset:3072
	s_add_i32 m0, s1, 0xc000
	ds_read_b128 v[190:193], v143
	ds_read_b128 v[194:197], v143 offset:1024
	ds_read_b128 v[198:201], v143 offset:2048
	ds_read_b128 v[202:205], v143 offset:3072
	ds_read_b128 v[206:209], v143 offset:4096
	ds_read_b128 v[210:213], v143 offset:5120
	ds_read_b128 v[214:217], v143 offset:6144
	ds_read_b128 v[218:221], v143 offset:7168
	global_load_lds_dwordx4 v136, s[80:81]
	s_add_i32 m0, s1, 0xe000
	s_nop 0
	global_load_lds_dwordx4 v138, s[80:81]
	s_waitcnt vmcnt(8)
	s_waitcnt lgkmcnt(0)
	s_barrier
	s_setprio 1
	v_mfma_f32_16x16x32_bf16 v[124:127], v[144:147], v[190:193], v[124:127]
	v_mfma_f32_16x16x32_bf16 v[124:127], v[148:151], v[194:197], v[124:127]
	v_mfma_f32_16x16x32_bf16 v[108:111], v[144:147], v[198:201], v[108:111]
	v_mfma_f32_16x16x32_bf16 v[108:111], v[148:151], v[202:205], v[108:111]
	v_mfma_f32_16x16x32_bf16 v[92:95], v[144:147], v[206:209], v[92:95]
	v_mfma_f32_16x16x32_bf16 v[92:95], v[148:151], v[210:213], v[92:95]
	v_mfma_f32_16x16x32_bf16 v[76:79], v[144:147], v[214:217], v[76:79]
	v_mfma_f32_16x16x32_bf16 v[76:79], v[148:151], v[218:221], v[76:79]
	v_mfma_f32_16x16x32_bf16 v[120:123], v[152:155], v[190:193], v[120:123]
	v_mfma_f32_16x16x32_bf16 v[120:123], v[156:159], v[194:197], v[120:123]
	v_mfma_f32_16x16x32_bf16 v[104:107], v[152:155], v[198:201], v[104:107]
	v_mfma_f32_16x16x32_bf16 v[104:107], v[156:159], v[202:205], v[104:107]
	v_mfma_f32_16x16x32_bf16 v[88:91], v[152:155], v[206:209], v[88:91]
	v_mfma_f32_16x16x32_bf16 v[88:91], v[156:159], v[210:213], v[88:91]
	v_mfma_f32_16x16x32_bf16 v[72:75], v[152:155], v[214:217], v[72:75]
	v_mfma_f32_16x16x32_bf16 v[72:75], v[156:159], v[218:221], v[72:75]
	s_setprio 0
	s_setprio 1
	v_mfma_f32_16x16x32_bf16 v[116:119], v[160:163], v[190:193], v[116:119]
	v_mfma_f32_16x16x32_bf16 v[116:119], v[164:167], v[194:197], v[116:119]
	v_mfma_f32_16x16x32_bf16 v[100:103], v[160:163], v[198:201], v[100:103]
	v_mfma_f32_16x16x32_bf16 v[100:103], v[164:167], v[202:205], v[100:103]
	v_mfma_f32_16x16x32_bf16 v[84:87], v[160:163], v[206:209], v[84:87]
	v_mfma_f32_16x16x32_bf16 v[84:87], v[164:167], v[210:213], v[84:87]
	v_mfma_f32_16x16x32_bf16 v[68:71], v[160:163], v[214:217], v[68:71]
	v_mfma_f32_16x16x32_bf16 v[68:71], v[164:167], v[218:221], v[68:71]
	v_mfma_f32_16x16x32_bf16 v[112:115], v[182:185], v[190:193], v[112:115]
	v_mfma_f32_16x16x32_bf16 v[112:115], v[186:189], v[194:197], v[112:115]
	v_mfma_f32_16x16x32_bf16 v[96:99], v[182:185], v[198:201], v[96:99]
	v_mfma_f32_16x16x32_bf16 v[96:99], v[186:189], v[202:205], v[96:99]
	v_mfma_f32_16x16x32_bf16 v[80:83], v[182:185], v[206:209], v[80:83]
	v_mfma_f32_16x16x32_bf16 v[80:83], v[186:189], v[210:213], v[80:83]
	v_mfma_f32_16x16x32_bf16 v[64:67], v[182:185], v[214:217], v[64:67]
	v_mfma_f32_16x16x32_bf16 v[64:67], v[186:189], v[218:221], v[64:67]
	s_barrier
	s_setprio 0
	s_add_i32 s13, s30, s0
	s_mov_b32 m0, s13
	ds_read_b128 v[190:193], v143 offset:16384
	ds_read_b128 v[194:197], v143 offset:17408
	ds_read_b128 v[198:201], v143 offset:18432
	ds_read_b128 v[202:205], v143 offset:19456
	ds_read_b128 v[206:209], v143 offset:20480
	ds_read_b128 v[210:213], v143 offset:21504
	ds_read_b128 v[214:217], v143 offset:22528
	ds_read_b128 v[218:221], v143 offset:23552
	global_load_lds_dwordx4 v132, s[82:83]
	s_add_i32 m0, s13, 0x2000
	s_add_u32 s42, s82, 0x80000
	s_addc_u32 s43, s83, 0
	s_add_i32 s12, s12, s0
	global_load_lds_dwordx4 v128, s[82:83]
	s_mov_b32 m0, s12
	s_nop 0
	global_load_lds_dwordx4 v132, s[42:43]
	s_add_i32 m0, s12, 0x2000
	s_nop 0
	global_load_lds_dwordx4 v128, s[42:43]
	s_mov_b32 m0, s1
	s_nop 0
	global_load_lds_dwordx4 v134, s[84:85]
	s_mov_b32 m0, s2
	s_nop 0
	global_load_lds_dwordx4 v130, s[84:85]
	s_waitcnt vmcnt(8)
	s_waitcnt lgkmcnt(0)
	s_barrier
	s_setprio 1
	v_mfma_f32_16x16x32_bf16 v[60:63], v[144:147], v[190:193], v[60:63]
	v_mfma_f32_16x16x32_bf16 v[60:63], v[148:151], v[194:197], v[60:63]
	v_mfma_f32_16x16x32_bf16 v[44:47], v[144:147], v[198:201], v[44:47]
	v_mfma_f32_16x16x32_bf16 v[44:47], v[148:151], v[202:205], v[44:47]
	v_mfma_f32_16x16x32_bf16 v[28:31], v[144:147], v[206:209], v[28:31]
	v_mfma_f32_16x16x32_bf16 v[28:31], v[148:151], v[210:213], v[28:31]
	v_mfma_f32_16x16x32_bf16 v[12:15], v[144:147], v[214:217], v[12:15]
	v_mfma_f32_16x16x32_bf16 v[12:15], v[148:151], v[218:221], v[12:15]
	v_mfma_f32_16x16x32_bf16 v[56:59], v[152:155], v[190:193], v[56:59]
	v_mfma_f32_16x16x32_bf16 v[56:59], v[156:159], v[194:197], v[56:59]
	v_mfma_f32_16x16x32_bf16 v[40:43], v[152:155], v[198:201], v[40:43]
	v_mfma_f32_16x16x32_bf16 v[40:43], v[156:159], v[202:205], v[40:43]
	v_mfma_f32_16x16x32_bf16 v[24:27], v[152:155], v[206:209], v[24:27]
	v_mfma_f32_16x16x32_bf16 v[24:27], v[156:159], v[210:213], v[24:27]
	v_mfma_f32_16x16x32_bf16 v[8:11], v[152:155], v[214:217], v[8:11]
	v_mfma_f32_16x16x32_bf16 v[8:11], v[156:159], v[218:221], v[8:11]
	s_setprio 0
	s_setprio 1
	v_mfma_f32_16x16x32_bf16 v[52:55], v[160:163], v[190:193], v[52:55]
	v_mfma_f32_16x16x32_bf16 v[52:55], v[164:167], v[194:197], v[52:55]
	v_mfma_f32_16x16x32_bf16 v[36:39], v[160:163], v[198:201], v[36:39]
	v_mfma_f32_16x16x32_bf16 v[36:39], v[164:167], v[202:205], v[36:39]
	v_mfma_f32_16x16x32_bf16 v[20:23], v[160:163], v[206:209], v[20:23]
	v_mfma_f32_16x16x32_bf16 v[20:23], v[164:167], v[210:213], v[20:23]
	v_mfma_f32_16x16x32_bf16 v[4:7], v[160:163], v[214:217], v[4:7]
	v_mfma_f32_16x16x32_bf16 v[4:7], v[164:167], v[218:221], v[4:7]
	v_mfma_f32_16x16x32_bf16 v[48:51], v[182:185], v[190:193], v[48:51]
	v_mfma_f32_16x16x32_bf16 v[48:51], v[186:189], v[194:197], v[48:51]
	v_mfma_f32_16x16x32_bf16 v[32:35], v[182:185], v[198:201], v[32:35]
	v_mfma_f32_16x16x32_bf16 v[32:35], v[186:189], v[202:205], v[32:35]
	v_mfma_f32_16x16x32_bf16 v[16:19], v[182:185], v[206:209], v[16:19]
	v_mfma_f32_16x16x32_bf16 v[16:19], v[186:189], v[210:213], v[16:19]
	v_mfma_f32_16x16x32_bf16 v[0:3], v[182:185], v[214:217], v[0:3]
	v_mfma_f32_16x16x32_bf16 v[0:3], v[186:189], v[218:221], v[0:3]
	s_barrier
; #define PG8_STAGE(bufoff, gbase, voff) do { _Pragma("unroll") for (int _i = 0; _i < 2; ++_i) \
;         __builtin_amdgcn_global_load_lds((const unsigned*)((const char*)(gbase) + (voff)[_i]), (PG8_LAS unsigned*)(lds + (bufoff) + ldsw + _i * 8192), 16, 0, 0); } while (0)
; #define PG8_LDA(dst, b, h) do { _Pragma("unroll") for (int m = 0; m < 4; ++m) _Pragma("unroll") for (int k = 0; k < 2; ++k) dst[m][k] = *(const PG8_LAS bf16x8*)(lds + PG8_SA(b, h) + aoff + m * 2048 + k * 1024); } while (0)
; #define PG8_LDB(dst, b, h) do { _Pragma("unroll") for (int n = 0; n < 2; ++n) _Pragma("unroll") for (int k = 0; k < 2; ++k) dst[n][k] = *(const PG8_LAS bf16x8*)(lds + PG8_SB(b, h) + boff + n * 2048 + k * 1024); } while (0)
; #define PG8_MMA(ai, bj, At, Bt) do { __builtin_amdgcn_s_setprio(1); _Pragma("unroll") for (int m = 0; m < 4; ++m) _Pragma("unroll") for (int n = 0; n < 2; ++n) _Pragma("unroll") for (int k = 0; k < 2; ++k) \
;         acc[ai][bj][m][n] = __builtin_amdgcn_mfma_f32_16x16x32_bf16(Bt[n][k], At[m][k], acc[ai][bj][m][n], 0, 0, 0); __builtin_amdgcn_s_setprio(0); } while (0)
; #define PG8_WAIT_V(n) asm volatile("s_waitcnt vmcnt(" #n ")" ::: "memory")
; #define PG8_WAIT_L(n) asm volatile("s_waitcnt lgkmcnt(" #n ")" ::: "memory")
; #define PG8_BAR __builtin_amdgcn_s_barrier()
; #define PG8_SCHED __builtin_amdgcn_sched_barrier(0)
;     ...
;             PG8_LDB(B0, 1, 0); PG8_LDB(B1, 1, 1); PG8_SCHED; PG8_LDA(At, 1, 0); PG8_STAGE(PG8_SA(0, 1), a2 + hstep, voffA);
;             PG8_WAIT_V(8); PG8_WAIT_L(0); PG8_BAR; PG8_MMA(0, 0, At, B0); PG8_MMA(0, 1, At, B1); PG8_BAR; PG8_SCHED;
;             PG8_LDA(At, 1, 1); PG8_STAGE(PG8_SB(1, 0), b3, voffB); PG8_STAGE(PG8_SB(1, 1), b3 + hstep, voffB); PG8_STAGE(PG8_SA(1, 0), a3, voffA);
;             PG8_WAIT_V(8); PG8_WAIT_L(0); PG8_BAR; PG8_MMA(1, 0, At, B0); PG8_MMA(1, 1, At, B1); PG8_BAR; PG8_SCHED;
	s_setprio 0
	s_add_i32 s12, 0, 0x18000
	s_add_i32 s13, 0, 0x1c000
	v_add_u32_e32 v156, s12, v141
	v_add_u32_e32 v168, s13, v141
	ds_read_b128 v[144:147], v156
	ds_read_b128 v[148:151], v156 offset:1024
	ds_read_b128 v[152:155], v156 offset:2048
	ds_read_b128 v[156:159], v156 offset:3072
	ds_read_b128 v[160:163], v168
	ds_read_b128 v[164:167], v168 offset:1024
	ds_read_b128 v[182:185], v168 offset:2048
	ds_read_b128 v[186:189], v168 offset:3072
	s_add_u32 s42, s84, 0x80000
	s_addc_u32 s43, s85, 0
	s_mov_b32 m0, s3
	ds_read_b128 v[190:193], v143 offset:32768
	ds_read_b128 v[194:197], v143 offset:33792
	ds_read_b128 v[198:201], v143 offset:34816
	ds_read_b128 v[202:205], v143 offset:35840
	ds_read_b128 v[206:209], v143 offset:36864
	ds_read_b128 v[210:213], v143 offset:37888
	ds_read_b128 v[214:217], v143 offset:38912
	ds_read_b128 v[218:221], v143 offset:39936
	global_load_lds_dwordx4 v134, s[42:43]
	s_mov_b32 m0, s8
	s_nop 0
	global_load_lds_dwordx4 v130, s[42:43]
	s_waitcnt vmcnt(8)
	s_waitcnt lgkmcnt(0)
	s_barrier
	s_setprio 1
	v_mfma_f32_16x16x32_bf16 v[124:127], v[144:147], v[190:193], v[124:127]
	v_mfma_f32_16x16x32_bf16 v[124:127], v[148:151], v[194:197], v[124:127]
	v_mfma_f32_16x16x32_bf16 v[108:111], v[144:147], v[198:201], v[108:111]
	v_mfma_f32_16x16x32_bf16 v[108:111], v[148:151], v[202:205], v[108:111]
	v_mfma_f32_16x16x32_bf16 v[92:95], v[144:147], v[206:209], v[92:95]
	v_mfma_f32_16x16x32_bf16 v[92:95], v[148:151], v[210:213], v[92:95]
	v_mfma_f32_16x16x32_bf16 v[76:79], v[144:147], v[214:217], v[76:79]
	v_mfma_f32_16x16x32_bf16 v[76:79], v[148:151], v[218:221], v[76:79]
	v_mfma_f32_16x16x32_bf16 v[120:123], v[152:155], v[190:193], v[120:123]
	v_mfma_f32_16x16x32_bf16 v[120:123], v[156:159], v[194:197], v[120:123]
	v_mfma_f32_16x16x32_bf16 v[104:107], v[152:155], v[198:201], v[104:107]
	v_mfma_f32_16x16x32_bf16 v[104:107], v[156:159], v[202:205], v[104:107]
	v_mfma_f32_16x16x32_bf16 v[88:91], v[152:155], v[206:209], v[88:91]
	v_mfma_f32_16x16x32_bf16 v[88:91], v[156:159], v[210:213], v[88:91]
	v_mfma_f32_16x16x32_bf16 v[72:75], v[152:155], v[214:217], v[72:75]
	v_mfma_f32_16x16x32_bf16 v[72:75], v[156:159], v[218:221], v[72:75]
	s_setprio 0
	s_setprio 1
	v_mfma_f32_16x16x32_bf16 v[116:119], v[160:163], v[190:193], v[116:119]
	v_mfma_f32_16x16x32_bf16 v[116:119], v[164:167], v[194:197], v[116:119]
	v_mfma_f32_16x16x32_bf16 v[100:103], v[160:163], v[198:201], v[100:103]
	v_mfma_f32_16x16x32_bf16 v[100:103], v[164:167], v[202:205], v[100:103]
	v_mfma_f32_16x16x32_bf16 v[84:87], v[160:163], v[206:209], v[84:87]
	v_mfma_f32_16x16x32_bf16 v[84:87], v[164:167], v[210:213], v[84:87]
	v_mfma_f32_16x16x32_bf16 v[68:71], v[160:163], v[214:217], v[68:71]
	v_mfma_f32_16x16x32_bf16 v[68:71], v[164:167], v[218:221], v[68:71]
	v_mfma_f32_16x16x32_bf16 v[112:115], v[182:185], v[190:193], v[112:115]
	v_mfma_f32_16x16x32_bf16 v[112:115], v[186:189], v[194:197], v[112:115]
	v_mfma_f32_16x16x32_bf16 v[96:99], v[182:185], v[198:201], v[96:99]
	v_mfma_f32_16x16x32_bf16 v[96:99], v[186:189], v[202:205], v[96:99]
	v_mfma_f32_16x16x32_bf16 v[80:83], v[182:185], v[206:209], v[80:83]
	v_mfma_f32_16x16x32_bf16 v[80:83], v[186:189], v[210:213], v[80:83]
	v_mfma_f32_16x16x32_bf16 v[64:67], v[182:185], v[214:217], v[64:67]
	v_mfma_f32_16x16x32_bf16 v[64:67], v[186:189], v[218:221], v[64:67]
	s_barrier
	s_setprio 0
	s_add_i32 s12, s12, s0
	s_mov_b32 m0, s12
	ds_read_b128 v[190:193], v143 offset:49152
	ds_read_b128 v[194:197], v143 offset:50176
	ds_read_b128 v[198:201], v143 offset:51200
	ds_read_b128 v[202:205], v143 offset:52224
	ds_read_b128 v[206:209], v143 offset:53248
	ds_read_b128 v[210:213], v143 offset:54272
	ds_read_b128 v[214:217], v143 offset:55296
	ds_read_b128 v[218:221], v143 offset:56320
	s_add_u32 s100, s82, s16
	s_addc_u32 s101, s83, s17
	global_load_lds_dwordx4 v132, s[100:101]
	s_add_i32 m0, s12, 0x2000
	s_add_u32 s42, s82, 0x80080
	s_addc_u32 s43, s83, 0
	s_add_i32 s12, s13, s0
	global_load_lds_dwordx4 v128, s[100:101]
	s_mov_b32 m0, s12
	s_nop 0
	global_load_lds_dwordx4 v132, s[42:43]
	s_add_i32 m0, s12, 0x2000
	s_nop 0
	global_load_lds_dwordx4 v128, s[42:43]
	s_mov_b32 m0, s9
	s_nop 0
	s_add_u32 s100, s84, s16
	s_addc_u32 s101, s85, s17
	global_load_lds_dwordx4 v134, s[100:101]
	s_mov_b32 m0, s10
	s_nop 0
	global_load_lds_dwordx4 v130, s[100:101]
	s_waitcnt vmcnt(8)
	s_waitcnt lgkmcnt(0)
	s_barrier
	s_setprio 1
	v_mfma_f32_16x16x32_bf16 v[60:63], v[144:147], v[190:193], v[60:63]
	v_mfma_f32_16x16x32_bf16 v[60:63], v[148:151], v[194:197], v[60:63]
	v_mfma_f32_16x16x32_bf16 v[44:47], v[144:147], v[198:201], v[44:47]
	v_mfma_f32_16x16x32_bf16 v[44:47], v[148:151], v[202:205], v[44:47]
	v_mfma_f32_16x16x32_bf16 v[28:31], v[144:147], v[206:209], v[28:31]
	v_mfma_f32_16x16x32_bf16 v[28:31], v[148:151], v[210:213], v[28:31]
	v_mfma_f32_16x16x32_bf16 v[12:15], v[144:147], v[214:217], v[12:15]
	v_mfma_f32_16x16x32_bf16 v[12:15], v[148:151], v[218:221], v[12:15]
	v_mfma_f32_16x16x32_bf16 v[56:59], v[152:155], v[190:193], v[56:59]
	v_mfma_f32_16x16x32_bf16 v[56:59], v[156:159], v[194:197], v[56:59]
	v_mfma_f32_16x16x32_bf16 v[40:43], v[152:155], v[198:201], v[40:43]
	v_mfma_f32_16x16x32_bf16 v[40:43], v[156:159], v[202:205], v[40:43]
	v_mfma_f32_16x16x32_bf16 v[24:27], v[152:155], v[206:209], v[24:27]
	v_mfma_f32_16x16x32_bf16 v[24:27], v[156:159], v[210:213], v[24:27]
	v_mfma_f32_16x16x32_bf16 v[8:11], v[152:155], v[214:217], v[8:11]
	v_mfma_f32_16x16x32_bf16 v[8:11], v[156:159], v[218:221], v[8:11]
	s_setprio 0
	s_setprio 1
	v_mfma_f32_16x16x32_bf16 v[52:55], v[160:163], v[190:193], v[52:55]
	v_mfma_f32_16x16x32_bf16 v[52:55], v[164:167], v[194:197], v[52:55]
	v_mfma_f32_16x16x32_bf16 v[36:39], v[160:163], v[198:201], v[36:39]
	v_mfma_f32_16x16x32_bf16 v[36:39], v[164:167], v[202:205], v[36:39]
	v_mfma_f32_16x16x32_bf16 v[20:23], v[160:163], v[206:209], v[20:23]
	v_mfma_f32_16x16x32_bf16 v[20:23], v[164:167], v[210:213], v[20:23]
	v_mfma_f32_16x16x32_bf16 v[4:7], v[160:163], v[214:217], v[4:7]
	v_mfma_f32_16x16x32_bf16 v[4:7], v[164:167], v[218:221], v[4:7]
	v_mfma_f32_16x16x32_bf16 v[48:51], v[182:185], v[190:193], v[48:51]
	v_mfma_f32_16x16x32_bf16 v[48:51], v[186:189], v[194:197], v[48:51]
	v_mfma_f32_16x16x32_bf16 v[32:35], v[182:185], v[198:201], v[32:35]
	v_mfma_f32_16x16x32_bf16 v[32:35], v[186:189], v[202:205], v[32:35]
	v_mfma_f32_16x16x32_bf16 v[16:19], v[182:185], v[206:209], v[16:19]
	v_mfma_f32_16x16x32_bf16 v[16:19], v[186:189], v[210:213], v[16:19]
	v_mfma_f32_16x16x32_bf16 v[0:3], v[182:185], v[214:217], v[0:3]
	v_mfma_f32_16x16x32_bf16 v[0:3], v[186:189], v[218:221], v[0:3]
	s_barrier
	s_setprio 0
	s_add_i32 s28, s28, 2
	s_add_u32 s80, s80, 0x100
	s_addc_u32 s81, s81, 0
	s_add_u32 s23, s23, 0x100
	s_addc_u32 s25, s25, 0
	s_cmp_gt_u32 s28, 29
	s_cbranch_scc0 .LBB0_230
	s_and_b64 vcc, exec, s[68:69]
	s_cbranch_vccz .LBB0_233
	s_barrier

; #define PG8_STAGE(bufoff, gbase, voff) do { _Pragma("unroll") for (int _i = 0; _i < 2; ++_i) \
;         __builtin_amdgcn_global_load_lds((const unsigned*)((const char*)(gbase) + (voff)[_i]), (PG8_LAS unsigned*)(lds + (bufoff) + ldsw + _i * 8192), 16, 0, 0); } while (0)
; #define PG8_LDA(dst, b, h) do { _Pragma("unroll") for (int m = 0; m < 4; ++m) _Pragma("unroll") for (int k = 0; k < 2; ++k) dst[m][k] = *(const PG8_LAS bf16x8*)(lds + PG8_SA(b, h) + aoff + m * 2048 + k * 1024); } while (0)
; #define PG8_LDB(dst, b, h) do { _Pragma("unroll") for (int n = 0; n < 2; ++n) _Pragma("unroll") for (int k = 0; k < 2; ++k) dst[n][k] = *(const PG8_LAS bf16x8*)(lds + PG8_SB(b, h) + boff + n * 2048 + k * 1024); } while (0)
; #define PG8_MMA(ai, bj, At, Bt) do { __builtin_amdgcn_s_setprio(1); _Pragma("unroll") for (int m = 0; m < 4; ++m) _Pragma("unroll") for (int n = 0; n < 2; ++n) _Pragma("unroll") for (int k = 0; k < 2; ++k) \
;         acc[ai][bj][m][n] = __builtin_amdgcn_mfma_f32_16x16x32_bf16(Bt[n][k], At[m][k], acc[ai][bj][m][n], 0, 0, 0); __builtin_amdgcn_s_setprio(0); } while (0)
; #define PG8_WAIT_V(n) asm volatile("s_waitcnt vmcnt(" #n ")" ::: "memory")
; #define PG8_WAIT_L(n) asm volatile("s_waitcnt lgkmcnt(" #n ")" ::: "memory")
; #define PG8_BAR __builtin_amdgcn_s_barrier()
; #define PG8_SCHED __builtin_amdgcn_sched_barrier(0)
;     ...
;             const bool last = (t == nt - 2);
;             const char* a1 = PG8_KADV(cA, (size_t)(t + 1) * kstep);
;             const char* a2 = last ? nA : PG8_KADV(cA, (size_t)(t + 2) * kstep); const char* b2 = last ? nB : PG8_KADV(cB, (size_t)(t + 2) * kstep);
;             const char* a3 = PG8_KADV(a2, kstep); const char* b3 = PG8_KADV(b2, kstep);
;             if (last && has_next) S.a_ready(nxt);
;             if constexpr (SP2) {
;             PG8_LDB(B0, 0, 0); PG8_LDB(B1, 0, 1); PG8_SCHED; PG8_LDA(At, 0, 0); PG8_STAGE(PG8_SA(1, 1), a1 + hstep, voffA);
;             PG8_WAIT_V(8); PG8_WAIT_L(0); PG8_BAR; PG8_MMA(0, 0, At, B0); PG8_MMA(0, 1, At, B1); PG8_BAR; PG8_SCHED;
;             PG8_LDA(At, 0, 1); PG8_STAGE(PG8_SB(0, 0), b2, voffB); PG8_STAGE(PG8_SB(0, 1), b2 + hstep, voffB); PG8_STAGE(PG8_SA(0, 0), a2, voffA);
;             PG8_WAIT_V(8); PG8_WAIT_L(0); PG8_BAR; PG8_MMA(1, 0, At, B0); PG8_MMA(1, 1, At, B1); PG8_BAR; PG8_SCHED;
.LBB0_313:
	s_add_u32 s78, s76, 0xffffff00
	s_addc_u32 s79, s77, -1
	s_add_i32 s12, 0, 0x10000
	s_cmpk_eq_i32 s3, 0x54
	s_cselect_b32 s83, s7, s79
	s_cselect_b32 s82, s6, s78
	s_cselect_b32 s81, s75, s30
	s_cselect_b32 s80, s74, s2
	s_add_i32 s13, 0, 0x14000
	v_add_u32_e32 v152, s12, v166
	v_add_u32_e32 v164, s13, v166
	ds_read_b128 v[128:131], v152
	ds_read_b128 v[132:135], v152 offset:1024
	ds_read_b128 v[148:151], v152 offset:2048
	ds_read_b128 v[152:155], v152 offset:3072
	ds_read_b128 v[156:159], v164
	ds_read_b128 v[160:163], v164 offset:1024
	ds_read_b128 v[170:173], v164 offset:2048
	ds_read_b128 v[178:181], v164 offset:3072
	s_add_i32 m0, s9, 0xc000
	ds_read_b128 v[184:187], v183
	ds_read_b128 v[188:191], v183 offset:1024
	ds_read_b128 v[192:195], v183 offset:2048
	ds_read_b128 v[196:199], v183 offset:3072
	ds_read_b128 v[200:203], v183 offset:4096
	ds_read_b128 v[204:207], v183 offset:5120
	ds_read_b128 v[208:211], v183 offset:6144
	ds_read_b128 v[212:215], v183 offset:7168
	global_load_lds_dwordx4 v144, s[76:77]
	s_add_i32 m0, s9, 0xe000
	s_nop 0
	global_load_lds_dwordx4 v146, s[76:77]
	s_waitcnt vmcnt(8)
	s_waitcnt lgkmcnt(0)
	s_barrier
	s_setprio 1
	v_mfma_f32_16x16x32_bf16 v[124:127], v[128:131], v[184:187], v[124:127]
	v_mfma_f32_16x16x32_bf16 v[124:127], v[132:135], v[188:191], v[124:127]
	v_mfma_f32_16x16x32_bf16 v[112:115], v[128:131], v[192:195], v[112:115]
	v_mfma_f32_16x16x32_bf16 v[112:115], v[132:135], v[196:199], v[112:115]
	v_mfma_f32_16x16x32_bf16 v[92:95], v[128:131], v[200:203], v[92:95]
	v_mfma_f32_16x16x32_bf16 v[92:95], v[132:135], v[204:207], v[92:95]
	v_mfma_f32_16x16x32_bf16 v[80:83], v[128:131], v[208:211], v[80:83]
	v_mfma_f32_16x16x32_bf16 v[80:83], v[132:135], v[212:215], v[80:83]
	v_mfma_f32_16x16x32_bf16 v[120:123], v[148:151], v[184:187], v[120:123]
	v_mfma_f32_16x16x32_bf16 v[120:123], v[152:155], v[188:191], v[120:123]
	v_mfma_f32_16x16x32_bf16 v[104:107], v[148:151], v[192:195], v[104:107]
	v_mfma_f32_16x16x32_bf16 v[104:107], v[152:155], v[196:199], v[104:107]
	v_mfma_f32_16x16x32_bf16 v[88:91], v[148:151], v[200:203], v[88:91]
	v_mfma_f32_16x16x32_bf16 v[88:91], v[152:155], v[204:207], v[88:91]
	v_mfma_f32_16x16x32_bf16 v[72:75], v[148:151], v[208:211], v[72:75]
	v_mfma_f32_16x16x32_bf16 v[72:75], v[152:155], v[212:215], v[72:75]
	s_setprio 0
	s_setprio 1
	v_mfma_f32_16x16x32_bf16 v[116:119], v[156:159], v[184:187], v[116:119]
	v_mfma_f32_16x16x32_bf16 v[116:119], v[160:163], v[188:191], v[116:119]
	v_mfma_f32_16x16x32_bf16 v[100:103], v[156:159], v[192:195], v[100:103]
	v_mfma_f32_16x16x32_bf16 v[100:103], v[160:163], v[196:199], v[100:103]
	v_mfma_f32_16x16x32_bf16 v[84:87], v[156:159], v[200:203], v[84:87]
	v_mfma_f32_16x16x32_bf16 v[84:87], v[160:163], v[204:207], v[84:87]
	v_mfma_f32_16x16x32_bf16 v[68:71], v[156:159], v[208:211], v[68:71]
	v_mfma_f32_16x16x32_bf16 v[68:71], v[160:163], v[212:215], v[68:71]
	v_mfma_f32_16x16x32_bf16 v[108:111], v[170:173], v[184:187], v[108:111]
	v_mfma_f32_16x16x32_bf16 v[108:111], v[178:181], v[188:191], v[108:111]
	v_mfma_f32_16x16x32_bf16 v[96:99], v[170:173], v[192:195], v[96:99]
	v_mfma_f32_16x16x32_bf16 v[96:99], v[178:181], v[196:199], v[96:99]
	v_mfma_f32_16x16x32_bf16 v[76:79], v[170:173], v[200:203], v[76:79]
	v_mfma_f32_16x16x32_bf16 v[76:79], v[178:181], v[204:207], v[76:79]
	v_mfma_f32_16x16x32_bf16 v[64:67], v[170:173], v[208:211], v[64:67]
	v_mfma_f32_16x16x32_bf16 v[64:67], v[178:181], v[212:215], v[64:67]
	s_barrier
	s_setprio 0
	s_add_i32 s12, s12, s8
	s_mov_b32 m0, s12
	ds_read_b128 v[184:187], v183 offset:16384
	ds_read_b128 v[188:191], v183 offset:17408
	ds_read_b128 v[192:195], v183 offset:18432
	ds_read_b128 v[196:199], v183 offset:19456
	ds_read_b128 v[200:203], v183 offset:20480
	ds_read_b128 v[204:207], v183 offset:21504
	ds_read_b128 v[208:211], v183 offset:22528
	ds_read_b128 v[212:215], v183 offset:23552
	global_load_lds_dwordx4 v138, s[80:81]
	s_add_i32 m0, s12, 0x2000
	s_add_u32 s42, s80, 0x160000
	s_addc_u32 s43, s81, 0
	s_add_i32 s12, s13, s8
	global_load_lds_dwordx4 v142, s[80:81]
	s_mov_b32 m0, s12
	s_nop 0
	global_load_lds_dwordx4 v138, s[42:43]
	s_add_i32 m0, s12, 0x2000
	s_nop 0
	global_load_lds_dwordx4 v142, s[42:43]
	s_mov_b32 m0, s9
	s_nop 0
	global_load_lds_dwordx4 v136, s[82:83]
	s_mov_b32 m0, s10
	s_nop 0
	global_load_lds_dwordx4 v140, s[82:83]
	s_waitcnt vmcnt(8)
	s_waitcnt lgkmcnt(0)
	s_barrier
	s_setprio 1
	v_mfma_f32_16x16x32_bf16 v[60:63], v[128:131], v[184:187], v[60:63]
	v_mfma_f32_16x16x32_bf16 v[60:63], v[132:135], v[188:191], v[60:63]
	v_mfma_f32_16x16x32_bf16 v[48:51], v[128:131], v[192:195], v[48:51]
	v_mfma_f32_16x16x32_bf16 v[48:51], v[132:135], v[196:199], v[48:51]
	v_mfma_f32_16x16x32_bf16 v[28:31], v[128:131], v[200:203], v[28:31]
	v_mfma_f32_16x16x32_bf16 v[28:31], v[132:135], v[204:207], v[28:31]
	v_mfma_f32_16x16x32_bf16 v[16:19], v[128:131], v[208:211], v[16:19]
	v_mfma_f32_16x16x32_bf16 v[16:19], v[132:135], v[212:215], v[16:19]
	v_mfma_f32_16x16x32_bf16 v[56:59], v[148:151], v[184:187], v[56:59]
	v_mfma_f32_16x16x32_bf16 v[56:59], v[152:155], v[188:191], v[56:59]
	v_mfma_f32_16x16x32_bf16 v[40:43], v[148:151], v[192:195], v[40:43]
	v_mfma_f32_16x16x32_bf16 v[40:43], v[152:155], v[196:199], v[40:43]
	v_mfma_f32_16x16x32_bf16 v[24:27], v[148:151], v[200:203], v[24:27]
	v_mfma_f32_16x16x32_bf16 v[24:27], v[152:155], v[204:207], v[24:27]
	v_mfma_f32_16x16x32_bf16 v[8:11], v[148:151], v[208:211], v[8:11]
	v_mfma_f32_16x16x32_bf16 v[8:11], v[152:155], v[212:215], v[8:11]
	s_setprio 0
	s_setprio 1
	v_mfma_f32_16x16x32_bf16 v[52:55], v[156:159], v[184:187], v[52:55]
	v_mfma_f32_16x16x32_bf16 v[52:55], v[160:163], v[188:191], v[52:55]
	v_mfma_f32_16x16x32_bf16 v[36:39], v[156:159], v[192:195], v[36:39]
	v_mfma_f32_16x16x32_bf16 v[36:39], v[160:163], v[196:199], v[36:39]
	v_mfma_f32_16x16x32_bf16 v[20:23], v[156:159], v[200:203], v[20:23]
	v_mfma_f32_16x16x32_bf16 v[20:23], v[160:163], v[204:207], v[20:23]
	v_mfma_f32_16x16x32_bf16 v[4:7], v[156:159], v[208:211], v[4:7]
	v_mfma_f32_16x16x32_bf16 v[4:7], v[160:163], v[212:215], v[4:7]
	v_mfma_f32_16x16x32_bf16 v[44:47], v[170:173], v[184:187], v[44:47]
	v_mfma_f32_16x16x32_bf16 v[44:47], v[178:181], v[188:191], v[44:47]
	v_mfma_f32_16x16x32_bf16 v[32:35], v[170:173], v[192:195], v[32:35]
	v_mfma_f32_16x16x32_bf16 v[32:35], v[178:181], v[196:199], v[32:35]
	v_mfma_f32_16x16x32_bf16 v[12:15], v[170:173], v[200:203], v[12:15]
	v_mfma_f32_16x16x32_bf16 v[12:15], v[178:181], v[204:207], v[12:15]
	v_mfma_f32_16x16x32_bf16 v[0:3], v[170:173], v[208:211], v[0:3]
	v_mfma_f32_16x16x32_bf16 v[0:3], v[178:181], v[212:215], v[0:3]
	s_barrier
; #define PG8_STAGE(bufoff, gbase, voff) do { _Pragma("unroll") for (int _i = 0; _i < 2; ++_i) \
;         __builtin_amdgcn_global_load_lds((const unsigned*)((const char*)(gbase) + (voff)[_i]), (PG8_LAS unsigned*)(lds + (bufoff) + ldsw + _i * 8192), 16, 0, 0); } while (0)
; #define PG8_LDA(dst, b, h) do { _Pragma("unroll") for (int m = 0; m < 4; ++m) _Pragma("unroll") for (int k = 0; k < 2; ++k) dst[m][k] = *(const PG8_LAS bf16x8*)(lds + PG8_SA(b, h) + aoff + m * 2048 + k * 1024); } while (0)
; #define PG8_LDB(dst, b, h) do { _Pragma("unroll") for (int n = 0; n < 2; ++n) _Pragma("unroll") for (int k = 0; k < 2; ++k) dst[n][k] = *(const PG8_LAS bf16x8*)(lds + PG8_SB(b, h) + boff + n * 2048 + k * 1024); } while (0)
; #define PG8_MMA(ai, bj, At, Bt) do { __builtin_amdgcn_s_setprio(1); _Pragma("unroll") for (int m = 0; m < 4; ++m) _Pragma("unroll") for (int n = 0; n < 2; ++n) _Pragma("unroll") for (int k = 0; k < 2; ++k) \
;         acc[ai][bj][m][n] = __builtin_amdgcn_mfma_f32_16x16x32_bf16(Bt[n][k], At[m][k], acc[ai][bj][m][n], 0, 0, 0); __builtin_amdgcn_s_setprio(0); } while (0)
; #define PG8_WAIT_V(n) asm volatile("s_waitcnt vmcnt(" #n ")" ::: "memory")
; #define PG8_WAIT_L(n) asm volatile("s_waitcnt lgkmcnt(" #n ")" ::: "memory")
; #define PG8_BAR __builtin_amdgcn_s_barrier()
; #define PG8_SCHED __builtin_amdgcn_sched_barrier(0)
;     ...
;         for (int t = 0; t < nt; t += 2) {
;     ...
;             PG8_LDB(B0, 1, 0); PG8_LDB(B1, 1, 1); PG8_SCHED; PG8_LDA(At, 1, 0); PG8_STAGE(PG8_SA(0, 1), a2 + hstep, voffA);
;             PG8_WAIT_V(8); PG8_WAIT_L(0); PG8_BAR; PG8_MMA(0, 0, At, B0); PG8_MMA(0, 1, At, B1); PG8_BAR; PG8_SCHED;
;             PG8_LDA(At, 1, 1); PG8_STAGE(PG8_SB(1, 0), b3, voffB); PG8_STAGE(PG8_SB(1, 1), b3 + hstep, voffB); PG8_STAGE(PG8_SA(1, 0), a3, voffA);
;             PG8_WAIT_V(8); PG8_WAIT_L(0); PG8_BAR; PG8_MMA(1, 0, At, B0); PG8_MMA(1, 1, At, B1); PG8_BAR; PG8_SCHED;
	s_setprio 0
	s_add_i32 s12, 0, 0x18000
	s_add_i32 s13, 0, 0x1c000
	v_add_u32_e32 v152, s12, v166
	v_add_u32_e32 v168, s13, v166
	ds_read_b128 v[128:131], v152
	ds_read_b128 v[132:135], v152 offset:1024
	ds_read_b128 v[148:151], v152 offset:2048
	ds_read_b128 v[152:155], v152 offset:3072
	ds_read_b128 v[156:159], v168
	ds_read_b128 v[160:163], v168 offset:1024
	ds_read_b128 v[170:173], v168 offset:2048
	ds_read_b128 v[178:181], v168 offset:3072
	s_add_u32 s42, s82, 0x160000
	s_addc_u32 s43, s83, 0
	s_mov_b32 m0, s18
	ds_read_b128 v[184:187], v183 offset:32768
	ds_read_b128 v[188:191], v183 offset:33792
	ds_read_b128 v[192:195], v183 offset:34816
	ds_read_b128 v[196:199], v183 offset:35840
	ds_read_b128 v[200:203], v183 offset:36864
	ds_read_b128 v[204:207], v183 offset:37888
	ds_read_b128 v[208:211], v183 offset:38912
	ds_read_b128 v[212:215], v183 offset:39936
	global_load_lds_dwordx4 v136, s[42:43]
	s_mov_b32 m0, s19
	s_nop 0
	global_load_lds_dwordx4 v140, s[42:43]
	s_waitcnt vmcnt(8)
	s_waitcnt lgkmcnt(0)
	s_barrier
	s_setprio 1
	v_mfma_f32_16x16x32_bf16 v[124:127], v[128:131], v[184:187], v[124:127]
	v_mfma_f32_16x16x32_bf16 v[124:127], v[132:135], v[188:191], v[124:127]
	v_mfma_f32_16x16x32_bf16 v[112:115], v[128:131], v[192:195], v[112:115]
	v_mfma_f32_16x16x32_bf16 v[112:115], v[132:135], v[196:199], v[112:115]
	v_mfma_f32_16x16x32_bf16 v[92:95], v[128:131], v[200:203], v[92:95]
	v_mfma_f32_16x16x32_bf16 v[92:95], v[132:135], v[204:207], v[92:95]
	v_mfma_f32_16x16x32_bf16 v[80:83], v[128:131], v[208:211], v[80:83]
	v_mfma_f32_16x16x32_bf16 v[80:83], v[132:135], v[212:215], v[80:83]
	v_mfma_f32_16x16x32_bf16 v[120:123], v[148:151], v[184:187], v[120:123]
	v_mfma_f32_16x16x32_bf16 v[120:123], v[152:155], v[188:191], v[120:123]
	v_mfma_f32_16x16x32_bf16 v[104:107], v[148:151], v[192:195], v[104:107]
	v_mfma_f32_16x16x32_bf16 v[104:107], v[152:155], v[196:199], v[104:107]
	v_mfma_f32_16x16x32_bf16 v[88:91], v[148:151], v[200:203], v[88:91]
	v_mfma_f32_16x16x32_bf16 v[88:91], v[152:155], v[204:207], v[88:91]
	v_mfma_f32_16x16x32_bf16 v[72:75], v[148:151], v[208:211], v[72:75]
	v_mfma_f32_16x16x32_bf16 v[72:75], v[152:155], v[212:215], v[72:75]
	s_setprio 0
	s_setprio 1
	v_mfma_f32_16x16x32_bf16 v[116:119], v[156:159], v[184:187], v[116:119]
	v_mfma_f32_16x16x32_bf16 v[116:119], v[160:163], v[188:191], v[116:119]
	v_mfma_f32_16x16x32_bf16 v[100:103], v[156:159], v[192:195], v[100:103]
	v_mfma_f32_16x16x32_bf16 v[100:103], v[160:163], v[196:199], v[100:103]
	v_mfma_f32_16x16x32_bf16 v[84:87], v[156:159], v[200:203], v[84:87]
	v_mfma_f32_16x16x32_bf16 v[84:87], v[160:163], v[204:207], v[84:87]
	v_mfma_f32_16x16x32_bf16 v[68:71], v[156:159], v[208:211], v[68:71]
	v_mfma_f32_16x16x32_bf16 v[68:71], v[160:163], v[212:215], v[68:71]
	v_mfma_f32_16x16x32_bf16 v[108:111], v[170:173], v[184:187], v[108:111]
	v_mfma_f32_16x16x32_bf16 v[108:111], v[178:181], v[188:191], v[108:111]
	v_mfma_f32_16x16x32_bf16 v[96:99], v[170:173], v[192:195], v[96:99]
	v_mfma_f32_16x16x32_bf16 v[96:99], v[178:181], v[196:199], v[96:99]
	v_mfma_f32_16x16x32_bf16 v[76:79], v[170:173], v[200:203], v[76:79]
	v_mfma_f32_16x16x32_bf16 v[76:79], v[178:181], v[204:207], v[76:79]
	v_mfma_f32_16x16x32_bf16 v[64:67], v[170:173], v[208:211], v[64:67]
	v_mfma_f32_16x16x32_bf16 v[64:67], v[178:181], v[212:215], v[64:67]
	s_barrier
	s_setprio 0
	s_add_i32 s12, s12, s8
	s_mov_b32 m0, s12
	ds_read_b128 v[184:187], v183 offset:49152
	ds_read_b128 v[188:191], v183 offset:50176
	ds_read_b128 v[192:195], v183 offset:51200
	ds_read_b128 v[196:199], v183 offset:52224
	ds_read_b128 v[200:203], v183 offset:53248
	ds_read_b128 v[204:207], v183 offset:54272
	ds_read_b128 v[208:211], v183 offset:55296
	ds_read_b128 v[212:215], v183 offset:56320
	s_add_u32 s100, s80, s38
	s_addc_u32 s101, s81, s39
	global_load_lds_dwordx4 v138, s[100:101]
	s_add_i32 m0, s12, 0x2000
	s_add_u32 s42, s80, 0x15ff80
	s_addc_u32 s43, s81, 0
	s_add_i32 s12, s13, s8
	global_load_lds_dwordx4 v142, s[100:101]
	s_mov_b32 m0, s12
	s_nop 0
	global_load_lds_dwordx4 v138, s[42:43]
	s_add_i32 m0, s12, 0x2000
	s_nop 0
	global_load_lds_dwordx4 v142, s[42:43]
	s_mov_b32 m0, s20
	s_nop 0
	s_add_u32 s100, s82, s38
	s_addc_u32 s101, s83, s39
	global_load_lds_dwordx4 v136, s[100:101]
	s_mov_b32 m0, s21
	s_nop 0
	global_load_lds_dwordx4 v140, s[100:101]
	s_waitcnt vmcnt(8)
	s_waitcnt lgkmcnt(0)
	s_barrier
	s_setprio 1
	v_mfma_f32_16x16x32_bf16 v[60:63], v[128:131], v[184:187], v[60:63]
	v_mfma_f32_16x16x32_bf16 v[60:63], v[132:135], v[188:191], v[60:63]
	v_mfma_f32_16x16x32_bf16 v[48:51], v[128:131], v[192:195], v[48:51]
	v_mfma_f32_16x16x32_bf16 v[48:51], v[132:135], v[196:199], v[48:51]
	v_mfma_f32_16x16x32_bf16 v[28:31], v[128:131], v[200:203], v[28:31]
	v_mfma_f32_16x16x32_bf16 v[28:31], v[132:135], v[204:207], v[28:31]
	v_mfma_f32_16x16x32_bf16 v[16:19], v[128:131], v[208:211], v[16:19]
	v_mfma_f32_16x16x32_bf16 v[16:19], v[132:135], v[212:215], v[16:19]
	v_mfma_f32_16x16x32_bf16 v[56:59], v[148:151], v[184:187], v[56:59]
	v_mfma_f32_16x16x32_bf16 v[56:59], v[152:155], v[188:191], v[56:59]
	v_mfma_f32_16x16x32_bf16 v[40:43], v[148:151], v[192:195], v[40:43]
	v_mfma_f32_16x16x32_bf16 v[40:43], v[152:155], v[196:199], v[40:43]
	v_mfma_f32_16x16x32_bf16 v[24:27], v[148:151], v[200:203], v[24:27]
	v_mfma_f32_16x16x32_bf16 v[24:27], v[152:155], v[204:207], v[24:27]
	v_mfma_f32_16x16x32_bf16 v[8:11], v[148:151], v[208:211], v[8:11]
	v_mfma_f32_16x16x32_bf16 v[8:11], v[152:155], v[212:215], v[8:11]
	s_setprio 0
	s_setprio 1
	v_mfma_f32_16x16x32_bf16 v[52:55], v[156:159], v[184:187], v[52:55]
	v_mfma_f32_16x16x32_bf16 v[52:55], v[160:163], v[188:191], v[52:55]
	v_mfma_f32_16x16x32_bf16 v[36:39], v[156:159], v[192:195], v[36:39]
	v_mfma_f32_16x16x32_bf16 v[36:39], v[160:163], v[196:199], v[36:39]
	v_mfma_f32_16x16x32_bf16 v[20:23], v[156:159], v[200:203], v[20:23]
	v_mfma_f32_16x16x32_bf16 v[20:23], v[160:163], v[204:207], v[20:23]
	v_mfma_f32_16x16x32_bf16 v[4:7], v[156:159], v[208:211], v[4:7]
	v_mfma_f32_16x16x32_bf16 v[4:7], v[160:163], v[212:215], v[4:7]
	v_mfma_f32_16x16x32_bf16 v[44:47], v[170:173], v[184:187], v[44:47]
	v_mfma_f32_16x16x32_bf16 v[44:47], v[178:181], v[188:191], v[44:47]
	v_mfma_f32_16x16x32_bf16 v[32:35], v[170:173], v[192:195], v[32:35]
	v_mfma_f32_16x16x32_bf16 v[32:35], v[178:181], v[196:199], v[32:35]
	v_mfma_f32_16x16x32_bf16 v[12:15], v[170:173], v[200:203], v[12:15]
	v_mfma_f32_16x16x32_bf16 v[12:15], v[178:181], v[204:207], v[12:15]
	v_mfma_f32_16x16x32_bf16 v[0:3], v[170:173], v[208:211], v[0:3]
	v_mfma_f32_16x16x32_bf16 v[0:3], v[178:181], v[212:215], v[0:3]
	s_barrier
	s_setprio 0
	s_add_i32 s3, s3, 2
	s_add_u32 s2, s2, 0xffffff00
	s_addc_u32 s30, s30, -1
	s_cmpk_gt_u32 s3, 0x55
	s_mov_b64 s[76:77], s[78:79]
	s_cbranch_scc0 .LBB0_313
	s_and_b64 vcc, exec, s[72:73]
	s_cbranch_vccz .LBB0_316
	s_barrier

; #define PG8_STAGE(bufoff, gbase, voff) do { _Pragma("unroll") for (int _i = 0; _i < 2; ++_i) \
;         __builtin_amdgcn_global_load_lds((const unsigned*)((const char*)(gbase) + (voff)[_i]), (PG8_LAS unsigned*)(lds + (bufoff) + ldsw + _i * 8192), 16, 0, 0); } while (0)
; #define PG8_LDA(dst, b, h) do { _Pragma("unroll") for (int m = 0; m < 4; ++m) _Pragma("unroll") for (int k = 0; k < 2; ++k) dst[m][k] = *(const PG8_LAS bf16x8*)(lds + PG8_SA(b, h) + aoff + m * 2048 + k * 1024); } while (0)
; #define PG8_LDB(dst, b, h) do { _Pragma("unroll") for (int n = 0; n < 2; ++n) _Pragma("unroll") for (int k = 0; k < 2; ++k) dst[n][k] = *(const PG8_LAS bf16x8*)(lds + PG8_SB(b, h) + boff + n * 2048 + k * 1024); } while (0)
; #define PG8_MMA(ai, bj, At, Bt) do { __builtin_amdgcn_s_setprio(1); _Pragma("unroll") for (int m = 0; m < 4; ++m) _Pragma("unroll") for (int n = 0; n < 2; ++n) _Pragma("unroll") for (int k = 0; k < 2; ++k) \
;         acc[ai][bj][m][n] = __builtin_amdgcn_mfma_f32_16x16x32_bf16(Bt[n][k], At[m][k], acc[ai][bj][m][n], 0, 0, 0); __builtin_amdgcn_s_setprio(0); } while (0)
; #define PG8_WAIT_V(n) asm volatile("s_waitcnt vmcnt(" #n ")" ::: "memory")
; #define PG8_WAIT_L(n) asm volatile("s_waitcnt lgkmcnt(" #n ")" ::: "memory")
; #define PG8_BAR __builtin_amdgcn_s_barrier()
; #define PG8_SCHED __builtin_amdgcn_sched_barrier(0)
;     ...
;             const bool last = (t == nt - 2);
;             const char* a1 = PG8_KADV(cA, (size_t)(t + 1) * kstep);
;             const char* a2 = last ? nA : PG8_KADV(cA, (size_t)(t + 2) * kstep); const char* b2 = last ? nB : PG8_KADV(cB, (size_t)(t + 2) * kstep);
;             const char* a3 = PG8_KADV(a2, kstep); const char* b3 = PG8_KADV(b2, kstep);
;             if (last && has_next) S.a_ready(nxt);
;             if constexpr (SP2) {
;             PG8_LDB(B0, 0, 0); PG8_LDB(B1, 0, 1); PG8_SCHED; PG8_LDA(At, 0, 0); PG8_STAGE(PG8_SA(1, 1), a1 + hstep, voffA);
;             PG8_WAIT_V(8); PG8_WAIT_L(0); PG8_BAR; PG8_MMA(0, 0, At, B0); PG8_MMA(0, 1, At, B1); PG8_BAR; PG8_SCHED;
;             PG8_LDA(At, 0, 1); PG8_STAGE(PG8_SB(0, 0), b2, voffB); PG8_STAGE(PG8_SB(0, 1), b2 + hstep, voffB); PG8_STAGE(PG8_SA(0, 0), a2, voffA);
;             PG8_WAIT_V(8); PG8_WAIT_L(0); PG8_BAR; PG8_MMA(1, 0, At, B0); PG8_MMA(1, 1, At, B1); PG8_BAR; PG8_SCHED;
.LBB0_343:
	s_add_u32 s78, s76, 0xffffff00
	s_addc_u32 s79, s77, -1
	s_add_i32 s12, 0, 0x10000
	s_cmpk_eq_i32 s3, 0x54
	s_cselect_b32 s83, s7, s79
	s_cselect_b32 s82, s6, s78
	s_cselect_b32 s81, s75, s30
	s_cselect_b32 s80, s74, s2
	s_add_i32 s13, 0, 0x14000
	v_add_u32_e32 v140, s12, v233
	v_add_u32_e32 v156, s13, v233
	ds_read_b128 v[128:131], v140
	ds_read_b128 v[132:135], v140 offset:1024
	ds_read_b128 v[136:139], v140 offset:2048
	ds_read_b128 v[140:143], v140 offset:3072
	ds_read_b128 v[144:147], v156
	ds_read_b128 v[148:151], v156 offset:1024
	ds_read_b128 v[152:155], v156 offset:2048
	ds_read_b128 v[156:159], v156 offset:3072
	s_add_i32 m0, s9, 0xc000
	ds_read_b128 v[160:163], v236
	ds_read_b128 v[164:167], v236 offset:1024
	ds_read_b128 v[194:197], v236 offset:2048
	ds_read_b128 v[198:201], v236 offset:3072
	ds_read_b128 v[202:205], v236 offset:4096
	ds_read_b128 v[206:209], v236 offset:5120
	ds_read_b128 v[210:213], v236 offset:6144
	ds_read_b128 v[214:217], v236 offset:7168
	global_load_lds_dwordx4 v190, s[76:77]
	s_add_i32 m0, s9, 0xe000
	s_nop 0
	global_load_lds_dwordx4 v192, s[76:77]
	s_waitcnt vmcnt(8)
	s_waitcnt lgkmcnt(0)
	s_barrier
	s_setprio 1
	v_mfma_f32_16x16x32_bf16 v[124:127], v[128:131], v[160:163], v[124:127]
	v_mfma_f32_16x16x32_bf16 v[124:127], v[132:135], v[164:167], v[124:127]
	v_mfma_f32_16x16x32_bf16 v[108:111], v[128:131], v[194:197], v[108:111]
	v_mfma_f32_16x16x32_bf16 v[108:111], v[132:135], v[198:201], v[108:111]
	v_mfma_f32_16x16x32_bf16 v[100:103], v[128:131], v[202:205], v[100:103]
	v_mfma_f32_16x16x32_bf16 v[100:103], v[132:135], v[206:209], v[100:103]
	v_mfma_f32_16x16x32_bf16 v[84:87], v[128:131], v[210:213], v[84:87]
	v_mfma_f32_16x16x32_bf16 v[84:87], v[132:135], v[214:217], v[84:87]
	v_mfma_f32_16x16x32_bf16 v[120:123], v[136:139], v[160:163], v[120:123]
	v_mfma_f32_16x16x32_bf16 v[120:123], v[140:143], v[164:167], v[120:123]
	v_mfma_f32_16x16x32_bf16 v[104:107], v[136:139], v[194:197], v[104:107]
	v_mfma_f32_16x16x32_bf16 v[104:107], v[140:143], v[198:201], v[104:107]
	v_mfma_f32_16x16x32_bf16 v[92:95], v[136:139], v[202:205], v[92:95]
	v_mfma_f32_16x16x32_bf16 v[92:95], v[140:143], v[206:209], v[92:95]
	v_mfma_f32_16x16x32_bf16 v[76:79], v[136:139], v[210:213], v[76:79]
	v_mfma_f32_16x16x32_bf16 v[76:79], v[140:143], v[214:217], v[76:79]
	s_setprio 0
	s_setprio 1
	v_mfma_f32_16x16x32_bf16 v[116:119], v[144:147], v[160:163], v[116:119]
	v_mfma_f32_16x16x32_bf16 v[116:119], v[148:151], v[164:167], v[116:119]
	v_mfma_f32_16x16x32_bf16 v[96:99], v[144:147], v[194:197], v[96:99]
	v_mfma_f32_16x16x32_bf16 v[96:99], v[148:151], v[198:201], v[96:99]
	v_mfma_f32_16x16x32_bf16 v[80:83], v[144:147], v[202:205], v[80:83]
	v_mfma_f32_16x16x32_bf16 v[80:83], v[148:151], v[206:209], v[80:83]
	v_mfma_f32_16x16x32_bf16 v[68:71], v[144:147], v[210:213], v[68:71]
	v_mfma_f32_16x16x32_bf16 v[68:71], v[148:151], v[214:217], v[68:71]
	v_mfma_f32_16x16x32_bf16 v[112:115], v[152:155], v[160:163], v[112:115]
	v_mfma_f32_16x16x32_bf16 v[112:115], v[156:159], v[164:167], v[112:115]
	v_mfma_f32_16x16x32_bf16 v[88:91], v[152:155], v[194:197], v[88:91]
	v_mfma_f32_16x16x32_bf16 v[88:91], v[156:159], v[198:201], v[88:91]
	v_mfma_f32_16x16x32_bf16 v[72:75], v[152:155], v[202:205], v[72:75]
	v_mfma_f32_16x16x32_bf16 v[72:75], v[156:159], v[206:209], v[72:75]
	v_mfma_f32_16x16x32_bf16 v[64:67], v[152:155], v[210:213], v[64:67]
	v_mfma_f32_16x16x32_bf16 v[64:67], v[156:159], v[214:217], v[64:67]
	s_barrier
	s_setprio 0
	s_add_i32 s12, s12, s8
	s_mov_b32 m0, s12
	ds_read_b128 v[160:163], v236 offset:16384
	ds_read_b128 v[164:167], v236 offset:17408
	ds_read_b128 v[194:197], v236 offset:18432
	ds_read_b128 v[198:201], v236 offset:19456
	ds_read_b128 v[202:205], v236 offset:20480
	ds_read_b128 v[206:209], v236 offset:21504
	ds_read_b128 v[210:213], v236 offset:22528
	ds_read_b128 v[214:217], v236 offset:23552
	global_load_lds_dwordx4 v184, s[80:81]
	s_add_i32 m0, s12, 0x2000
	s_add_u32 s42, s80, 0x160000
	s_addc_u32 s43, s81, 0
	s_add_i32 s12, s13, s8
	global_load_lds_dwordx4 v188, s[80:81]
	s_mov_b32 m0, s12
	s_nop 0
	global_load_lds_dwordx4 v184, s[42:43]
	s_add_i32 m0, s12, 0x2000
	s_nop 0
	global_load_lds_dwordx4 v188, s[42:43]
	s_mov_b32 m0, s9
	s_nop 0
	global_load_lds_dwordx4 v182, s[82:83]
	s_mov_b32 m0, s10
	s_nop 0
	global_load_lds_dwordx4 v186, s[82:83]
	s_waitcnt vmcnt(8)
	s_waitcnt lgkmcnt(0)
	s_barrier
	s_setprio 1
	v_mfma_f32_16x16x32_bf16 v[60:63], v[128:131], v[160:163], v[60:63]
	v_mfma_f32_16x16x32_bf16 v[60:63], v[132:135], v[164:167], v[60:63]
	v_mfma_f32_16x16x32_bf16 v[52:55], v[128:131], v[194:197], v[52:55]
	v_mfma_f32_16x16x32_bf16 v[52:55], v[132:135], v[198:201], v[52:55]
	v_mfma_f32_16x16x32_bf16 v[36:39], v[128:131], v[202:205], v[36:39]
	v_mfma_f32_16x16x32_bf16 v[36:39], v[132:135], v[206:209], v[36:39]
	v_mfma_f32_16x16x32_bf16 v[20:23], v[128:131], v[210:213], v[20:23]
	v_mfma_f32_16x16x32_bf16 v[20:23], v[132:135], v[214:217], v[20:23]
	v_mfma_f32_16x16x32_bf16 v[56:59], v[136:139], v[160:163], v[56:59]
	v_mfma_f32_16x16x32_bf16 v[56:59], v[140:143], v[164:167], v[56:59]
	v_mfma_f32_16x16x32_bf16 v[44:47], v[136:139], v[194:197], v[44:47]
	v_mfma_f32_16x16x32_bf16 v[44:47], v[140:143], v[198:201], v[44:47]
	v_mfma_f32_16x16x32_bf16 v[28:31], v[136:139], v[202:205], v[28:31]
	v_mfma_f32_16x16x32_bf16 v[28:31], v[140:143], v[206:209], v[28:31]
	v_mfma_f32_16x16x32_bf16 v[12:15], v[136:139], v[210:213], v[12:15]
	v_mfma_f32_16x16x32_bf16 v[12:15], v[140:143], v[214:217], v[12:15]
	s_setprio 0
	s_setprio 1
	v_mfma_f32_16x16x32_bf16 v[48:51], v[144:147], v[160:163], v[48:51]
	v_mfma_f32_16x16x32_bf16 v[48:51], v[148:151], v[164:167], v[48:51]
	v_mfma_f32_16x16x32_bf16 v[32:35], v[144:147], v[194:197], v[32:35]
	v_mfma_f32_16x16x32_bf16 v[32:35], v[148:151], v[198:201], v[32:35]
	v_mfma_f32_16x16x32_bf16 v[16:19], v[144:147], v[202:205], v[16:19]
	v_mfma_f32_16x16x32_bf16 v[16:19], v[148:151], v[206:209], v[16:19]
	v_mfma_f32_16x16x32_bf16 v[4:7], v[144:147], v[210:213], v[4:7]
	v_mfma_f32_16x16x32_bf16 v[4:7], v[148:151], v[214:217], v[4:7]
	v_mfma_f32_16x16x32_bf16 v[40:43], v[152:155], v[160:163], v[40:43]
	v_mfma_f32_16x16x32_bf16 v[40:43], v[156:159], v[164:167], v[40:43]
	v_mfma_f32_16x16x32_bf16 v[24:27], v[152:155], v[194:197], v[24:27]
	v_mfma_f32_16x16x32_bf16 v[24:27], v[156:159], v[198:201], v[24:27]
	v_mfma_f32_16x16x32_bf16 v[8:11], v[152:155], v[202:205], v[8:11]
	v_mfma_f32_16x16x32_bf16 v[8:11], v[156:159], v[206:209], v[8:11]
	v_mfma_f32_16x16x32_bf16 v[0:3], v[152:155], v[210:213], v[0:3]
	v_mfma_f32_16x16x32_bf16 v[0:3], v[156:159], v[214:217], v[0:3]
	s_barrier
; #define PG8_STAGE(bufoff, gbase, voff) do { _Pragma("unroll") for (int _i = 0; _i < 2; ++_i) \
;         __builtin_amdgcn_global_load_lds((const unsigned*)((const char*)(gbase) + (voff)[_i]), (PG8_LAS unsigned*)(lds + (bufoff) + ldsw + _i * 8192), 16, 0, 0); } while (0)
; #define PG8_LDA(dst, b, h) do { _Pragma("unroll") for (int m = 0; m < 4; ++m) _Pragma("unroll") for (int k = 0; k < 2; ++k) dst[m][k] = *(const PG8_LAS bf16x8*)(lds + PG8_SA(b, h) + aoff + m * 2048 + k * 1024); } while (0)
; #define PG8_LDB(dst, b, h) do { _Pragma("unroll") for (int n = 0; n < 2; ++n) _Pragma("unroll") for (int k = 0; k < 2; ++k) dst[n][k] = *(const PG8_LAS bf16x8*)(lds + PG8_SB(b, h) + boff + n * 2048 + k * 1024); } while (0)
; #define PG8_MMA(ai, bj, At, Bt) do { __builtin_amdgcn_s_setprio(1); _Pragma("unroll") for (int m = 0; m < 4; ++m) _Pragma("unroll") for (int n = 0; n < 2; ++n) _Pragma("unroll") for (int k = 0; k < 2; ++k) \
;         acc[ai][bj][m][n] = __builtin_amdgcn_mfma_f32_16x16x32_bf16(Bt[n][k], At[m][k], acc[ai][bj][m][n], 0, 0, 0); __builtin_amdgcn_s_setprio(0); } while (0)
; #define PG8_WAIT_V(n) asm volatile("s_waitcnt vmcnt(" #n ")" ::: "memory")
; #define PG8_WAIT_L(n) asm volatile("s_waitcnt lgkmcnt(" #n ")" ::: "memory")
; #define PG8_BAR __builtin_amdgcn_s_barrier()
; #define PG8_SCHED __builtin_amdgcn_sched_barrier(0)
;     ...
;         for (int t = 0; t < nt; t += 2) {
;     ...
;             PG8_LDB(B0, 1, 0); PG8_LDB(B1, 1, 1); PG8_SCHED; PG8_LDA(At, 1, 0); PG8_STAGE(PG8_SA(0, 1), a2 + hstep, voffA);
;             PG8_WAIT_V(8); PG8_WAIT_L(0); PG8_BAR; PG8_MMA(0, 0, At, B0); PG8_MMA(0, 1, At, B1); PG8_BAR; PG8_SCHED;
;             PG8_LDA(At, 1, 1); PG8_STAGE(PG8_SB(1, 0), b3, voffB); PG8_STAGE(PG8_SB(1, 1), b3 + hstep, voffB); PG8_STAGE(PG8_SA(1, 0), a3, voffA);
;             PG8_WAIT_V(8); PG8_WAIT_L(0); PG8_BAR; PG8_MMA(1, 0, At, B0); PG8_MMA(1, 1, At, B1); PG8_BAR; PG8_SCHED;
	s_setprio 0
	s_add_i32 s12, 0, 0x18000
	s_add_i32 s13, 0, 0x1c000
	v_add_u32_e32 v140, s12, v233
	v_add_u32_e32 v156, s13, v233
	ds_read_b128 v[128:131], v140
	ds_read_b128 v[132:135], v140 offset:1024
	ds_read_b128 v[136:139], v140 offset:2048
	ds_read_b128 v[140:143], v140 offset:3072
	ds_read_b128 v[144:147], v156
	ds_read_b128 v[148:151], v156 offset:1024
	ds_read_b128 v[152:155], v156 offset:2048
	ds_read_b128 v[156:159], v156 offset:3072
	s_add_u32 s42, s82, 0x160000
	s_addc_u32 s43, s83, 0
	s_mov_b32 m0, s18
	ds_read_b128 v[160:163], v236 offset:32768
	ds_read_b128 v[164:167], v236 offset:33792
	ds_read_b128 v[194:197], v236 offset:34816
	ds_read_b128 v[198:201], v236 offset:35840
	ds_read_b128 v[202:205], v236 offset:36864
	ds_read_b128 v[206:209], v236 offset:37888
	ds_read_b128 v[210:213], v236 offset:38912
	ds_read_b128 v[214:217], v236 offset:39936
	global_load_lds_dwordx4 v182, s[42:43]
	s_mov_b32 m0, s19
	s_nop 0
	global_load_lds_dwordx4 v186, s[42:43]
	s_waitcnt vmcnt(8)
	s_waitcnt lgkmcnt(0)
	s_barrier
	s_setprio 1
	v_mfma_f32_16x16x32_bf16 v[124:127], v[128:131], v[160:163], v[124:127]
	v_mfma_f32_16x16x32_bf16 v[124:127], v[132:135], v[164:167], v[124:127]
	v_mfma_f32_16x16x32_bf16 v[108:111], v[128:131], v[194:197], v[108:111]
	v_mfma_f32_16x16x32_bf16 v[108:111], v[132:135], v[198:201], v[108:111]
	v_mfma_f32_16x16x32_bf16 v[100:103], v[128:131], v[202:205], v[100:103]
	v_mfma_f32_16x16x32_bf16 v[100:103], v[132:135], v[206:209], v[100:103]
	v_mfma_f32_16x16x32_bf16 v[84:87], v[128:131], v[210:213], v[84:87]
	v_mfma_f32_16x16x32_bf16 v[84:87], v[132:135], v[214:217], v[84:87]
	v_mfma_f32_16x16x32_bf16 v[120:123], v[136:139], v[160:163], v[120:123]
	v_mfma_f32_16x16x32_bf16 v[120:123], v[140:143], v[164:167], v[120:123]
	v_mfma_f32_16x16x32_bf16 v[104:107], v[136:139], v[194:197], v[104:107]
	v_mfma_f32_16x16x32_bf16 v[104:107], v[140:143], v[198:201], v[104:107]
	v_mfma_f32_16x16x32_bf16 v[92:95], v[136:139], v[202:205], v[92:95]
	v_mfma_f32_16x16x32_bf16 v[92:95], v[140:143], v[206:209], v[92:95]
	v_mfma_f32_16x16x32_bf16 v[76:79], v[136:139], v[210:213], v[76:79]
	v_mfma_f32_16x16x32_bf16 v[76:79], v[140:143], v[214:217], v[76:79]
	s_setprio 0
	s_setprio 1
	v_mfma_f32_16x16x32_bf16 v[116:119], v[144:147], v[160:163], v[116:119]
	v_mfma_f32_16x16x32_bf16 v[116:119], v[148:151], v[164:167], v[116:119]
	v_mfma_f32_16x16x32_bf16 v[96:99], v[144:147], v[194:197], v[96:99]
	v_mfma_f32_16x16x32_bf16 v[96:99], v[148:151], v[198:201], v[96:99]
	v_mfma_f32_16x16x32_bf16 v[80:83], v[144:147], v[202:205], v[80:83]
	v_mfma_f32_16x16x32_bf16 v[80:83], v[148:151], v[206:209], v[80:83]
	v_mfma_f32_16x16x32_bf16 v[68:71], v[144:147], v[210:213], v[68:71]
	v_mfma_f32_16x16x32_bf16 v[68:71], v[148:151], v[214:217], v[68:71]
	v_mfma_f32_16x16x32_bf16 v[112:115], v[152:155], v[160:163], v[112:115]
	v_mfma_f32_16x16x32_bf16 v[112:115], v[156:159], v[164:167], v[112:115]
	v_mfma_f32_16x16x32_bf16 v[88:91], v[152:155], v[194:197], v[88:91]
	v_mfma_f32_16x16x32_bf16 v[88:91], v[156:159], v[198:201], v[88:91]
	v_mfma_f32_16x16x32_bf16 v[72:75], v[152:155], v[202:205], v[72:75]
	v_mfma_f32_16x16x32_bf16 v[72:75], v[156:159], v[206:209], v[72:75]
	v_mfma_f32_16x16x32_bf16 v[64:67], v[152:155], v[210:213], v[64:67]
	v_mfma_f32_16x16x32_bf16 v[64:67], v[156:159], v[214:217], v[64:67]
	s_barrier
	s_setprio 0
	s_add_i32 s12, s12, s8
	s_mov_b32 m0, s12
	ds_read_b128 v[160:163], v236 offset:49152
	ds_read_b128 v[164:167], v236 offset:50176
	ds_read_b128 v[194:197], v236 offset:51200
	ds_read_b128 v[198:201], v236 offset:52224
	ds_read_b128 v[202:205], v236 offset:53248
	ds_read_b128 v[206:209], v236 offset:54272
	ds_read_b128 v[210:213], v236 offset:55296
	ds_read_b128 v[214:217], v236 offset:56320
	s_add_u32 s100, s80, s38
	s_addc_u32 s101, s81, s39
	global_load_lds_dwordx4 v184, s[100:101]
	s_add_i32 m0, s12, 0x2000
	s_add_u32 s42, s80, 0x15ff80
	s_addc_u32 s43, s81, 0
	s_add_i32 s12, s13, s8
	global_load_lds_dwordx4 v188, s[100:101]
	s_mov_b32 m0, s12
	s_nop 0
	global_load_lds_dwordx4 v184, s[42:43]
	s_add_i32 m0, s12, 0x2000
	s_nop 0
	global_load_lds_dwordx4 v188, s[42:43]
	s_mov_b32 m0, s20
	s_nop 0
	s_add_u32 s100, s82, s38
	s_addc_u32 s101, s83, s39
	global_load_lds_dwordx4 v182, s[100:101]
	s_mov_b32 m0, s21
	s_nop 0
	global_load_lds_dwordx4 v186, s[100:101]
	s_waitcnt vmcnt(8)
	s_waitcnt lgkmcnt(0)
	s_barrier
	s_setprio 1
	v_mfma_f32_16x16x32_bf16 v[60:63], v[128:131], v[160:163], v[60:63]
	v_mfma_f32_16x16x32_bf16 v[60:63], v[132:135], v[164:167], v[60:63]
	v_mfma_f32_16x16x32_bf16 v[52:55], v[128:131], v[194:197], v[52:55]
	v_mfma_f32_16x16x32_bf16 v[52:55], v[132:135], v[198:201], v[52:55]
	v_mfma_f32_16x16x32_bf16 v[36:39], v[128:131], v[202:205], v[36:39]
	v_mfma_f32_16x16x32_bf16 v[36:39], v[132:135], v[206:209], v[36:39]
	v_mfma_f32_16x16x32_bf16 v[20:23], v[128:131], v[210:213], v[20:23]
	v_mfma_f32_16x16x32_bf16 v[20:23], v[132:135], v[214:217], v[20:23]
	v_mfma_f32_16x16x32_bf16 v[56:59], v[136:139], v[160:163], v[56:59]
	v_mfma_f32_16x16x32_bf16 v[56:59], v[140:143], v[164:167], v[56:59]
	v_mfma_f32_16x16x32_bf16 v[44:47], v[136:139], v[194:197], v[44:47]
	v_mfma_f32_16x16x32_bf16 v[44:47], v[140:143], v[198:201], v[44:47]
	v_mfma_f32_16x16x32_bf16 v[28:31], v[136:139], v[202:205], v[28:31]
	v_mfma_f32_16x16x32_bf16 v[28:31], v[140:143], v[206:209], v[28:31]
	v_mfma_f32_16x16x32_bf16 v[12:15], v[136:139], v[210:213], v[12:15]
	v_mfma_f32_16x16x32_bf16 v[12:15], v[140:143], v[214:217], v[12:15]
	s_setprio 0
	s_setprio 1
	v_mfma_f32_16x16x32_bf16 v[48:51], v[144:147], v[160:163], v[48:51]
	v_mfma_f32_16x16x32_bf16 v[48:51], v[148:151], v[164:167], v[48:51]
	v_mfma_f32_16x16x32_bf16 v[32:35], v[144:147], v[194:197], v[32:35]
	v_mfma_f32_16x16x32_bf16 v[32:35], v[148:151], v[198:201], v[32:35]
	v_mfma_f32_16x16x32_bf16 v[16:19], v[144:147], v[202:205], v[16:19]
	v_mfma_f32_16x16x32_bf16 v[16:19], v[148:151], v[206:209], v[16:19]
	v_mfma_f32_16x16x32_bf16 v[4:7], v[144:147], v[210:213], v[4:7]
	v_mfma_f32_16x16x32_bf16 v[4:7], v[148:151], v[214:217], v[4:7]
	v_mfma_f32_16x16x32_bf16 v[40:43], v[152:155], v[160:163], v[40:43]
	v_mfma_f32_16x16x32_bf16 v[40:43], v[156:159], v[164:167], v[40:43]
	v_mfma_f32_16x16x32_bf16 v[24:27], v[152:155], v[194:197], v[24:27]
	v_mfma_f32_16x16x32_bf16 v[24:27], v[156:159], v[198:201], v[24:27]
	v_mfma_f32_16x16x32_bf16 v[8:11], v[152:155], v[202:205], v[8:11]
	v_mfma_f32_16x16x32_bf16 v[8:11], v[156:159], v[206:209], v[8:11]
	v_mfma_f32_16x16x32_bf16 v[0:3], v[152:155], v[210:213], v[0:3]
	v_mfma_f32_16x16x32_bf16 v[0:3], v[156:159], v[214:217], v[0:3]
	s_barrier
	s_setprio 0
	s_add_i32 s3, s3, 2
	s_add_u32 s2, s2, 0xffffff00
	s_addc_u32 s30, s30, -1
	s_cmpk_gt_u32 s3, 0x55
	s_mov_b64 s[76:77], s[78:79]
	s_cbranch_scc0 .LBB0_343
	v_mov_b64_e32 v[234:235], 0x7f
	v_mov_b64_e32 v[174:175], 0x80
	v_mov_b64_e32 v[226:227], 0xb00
	s_and_b64 vcc, exec, s[72:73]
	s_cbranch_vccz .LBB0_346
	s_barrier

; #define PG8_STAGE(bufoff, gbase, voff) do { _Pragma("unroll") for (int _i = 0; _i < 2; ++_i) \
;         __builtin_amdgcn_global_load_lds((const unsigned*)((const char*)(gbase) + (voff)[_i]), (PG8_LAS unsigned*)(lds + (bufoff) + ldsw + _i * 8192), 16, 0, 0); } while (0)
; #define PG8_LDA(dst, b, h) do { _Pragma("unroll") for (int m = 0; m < 4; ++m) _Pragma("unroll") for (int k = 0; k < 2; ++k) dst[m][k] = *(const PG8_LAS bf16x8*)(lds + PG8_SA(b, h) + aoff + m * 2048 + k * 1024); } while (0)
; #define PG8_LDB(dst, b, h) do { _Pragma("unroll") for (int n = 0; n < 2; ++n) _Pragma("unroll") for (int k = 0; k < 2; ++k) dst[n][k] = *(const PG8_LAS bf16x8*)(lds + PG8_SB(b, h) + boff + n * 2048 + k * 1024); } while (0)
; #define PG8_MMA(ai, bj, At, Bt) do { __builtin_amdgcn_s_setprio(1); _Pragma("unroll") for (int m = 0; m < 4; ++m) _Pragma("unroll") for (int n = 0; n < 2; ++n) _Pragma("unroll") for (int k = 0; k < 2; ++k) \
;         acc[ai][bj][m][n] = __builtin_amdgcn_mfma_f32_16x16x32_bf16(Bt[n][k], At[m][k], acc[ai][bj][m][n], 0, 0, 0); __builtin_amdgcn_s_setprio(0); } while (0)
; #define PG8_WAIT_V(n) asm volatile("s_waitcnt vmcnt(" #n ")" ::: "memory")
; #define PG8_WAIT_L(n) asm volatile("s_waitcnt lgkmcnt(" #n ")" ::: "memory")
; #define PG8_BAR __builtin_amdgcn_s_barrier()
; #define PG8_SCHED __builtin_amdgcn_sched_barrier(0)
;     ...
;             const bool last = (t == nt - 2);
;             const char* a1 = PG8_KADV(cA, (size_t)(t + 1) * kstep);
;             const char* a2 = last ? nA : PG8_KADV(cA, (size_t)(t + 2) * kstep); const char* b2 = last ? nB : PG8_KADV(cB, (size_t)(t + 2) * kstep);
;             const char* a3 = PG8_KADV(a2, kstep); const char* b3 = PG8_KADV(b2, kstep);
;             if (last && has_next) S.a_ready(nxt);
;             if constexpr (SP2) {
;             PG8_LDB(B0, 0, 0); PG8_LDB(B1, 0, 1); PG8_SCHED; PG8_LDA(At, 0, 0); PG8_STAGE(PG8_SA(1, 1), a1 + hstep, voffA);
;             PG8_WAIT_V(8); PG8_WAIT_L(0); PG8_BAR; PG8_MMA(0, 0, At, B0); PG8_MMA(0, 1, At, B1); PG8_BAR; PG8_SCHED;
;             PG8_LDA(At, 0, 1); PG8_STAGE(PG8_SB(0, 0), b2, voffB); PG8_STAGE(PG8_SB(0, 1), b2 + hstep, voffB); PG8_STAGE(PG8_SA(0, 0), a2, voffA);
;             PG8_WAIT_V(8); PG8_WAIT_L(0); PG8_BAR; PG8_MMA(1, 0, At, B0); PG8_MMA(1, 1, At, B1); PG8_BAR; PG8_SCHED;
.LBB0_490:
	s_add_u32 s3, s86, 0xfff80080
	s_addc_u32 s12, s87, -1
	s_add_i32 s13, 0, 0x10000
	s_cmp_eq_u32 s2, 28
	s_cselect_b32 s91, s23, s12
	s_cselect_b32 s90, s25, s3
	s_cselect_b32 s89, s28, s40
	s_cselect_b32 s88, s30, s33
	s_add_i32 s3, 0, 0x14000
	v_add_u32_e32 v156, s13, v141
	v_add_u32_e32 v168, s3, v141
	ds_read_b128 v[144:147], v156
	ds_read_b128 v[148:151], v156 offset:1024
	ds_read_b128 v[152:155], v156 offset:2048
	ds_read_b128 v[156:159], v156 offset:3072
	ds_read_b128 v[160:163], v168
	ds_read_b128 v[164:167], v168 offset:1024
	ds_read_b128 v[170:173], v168 offset:2048
	ds_read_b128 v[178:181], v168 offset:3072
	s_add_i32 m0, s9, 0xc000
	ds_read_b128 v[182:185], v143
	ds_read_b128 v[186:189], v143 offset:1024
	ds_read_b128 v[190:193], v143 offset:2048
	ds_read_b128 v[194:197], v143 offset:3072
	ds_read_b128 v[198:201], v143 offset:4096
	ds_read_b128 v[202:205], v143 offset:5120
	ds_read_b128 v[206:209], v143 offset:6144
	ds_read_b128 v[210:213], v143 offset:7168
	global_load_lds_dwordx4 v136, s[86:87]
	s_add_i32 m0, s9, 0xe000
	s_nop 0
	global_load_lds_dwordx4 v138, s[86:87]
	s_waitcnt vmcnt(8)
	s_waitcnt lgkmcnt(0)
	s_barrier
	s_setprio 1
	v_mfma_f32_16x16x32_bf16 v[124:127], v[144:147], v[182:185], v[124:127]
	v_mfma_f32_16x16x32_bf16 v[124:127], v[148:151], v[186:189], v[124:127]
	v_mfma_f32_16x16x32_bf16 v[116:119], v[144:147], v[190:193], v[116:119]
	v_mfma_f32_16x16x32_bf16 v[116:119], v[148:151], v[194:197], v[116:119]
	v_mfma_f32_16x16x32_bf16 v[100:103], v[144:147], v[198:201], v[100:103]
	v_mfma_f32_16x16x32_bf16 v[100:103], v[148:151], v[202:205], v[100:103]
	v_mfma_f32_16x16x32_bf16 v[84:87], v[144:147], v[206:209], v[84:87]
	v_mfma_f32_16x16x32_bf16 v[84:87], v[148:151], v[210:213], v[84:87]
	v_mfma_f32_16x16x32_bf16 v[120:123], v[152:155], v[182:185], v[120:123]
	v_mfma_f32_16x16x32_bf16 v[120:123], v[156:159], v[186:189], v[120:123]
	v_mfma_f32_16x16x32_bf16 v[112:115], v[152:155], v[190:193], v[112:115]
	v_mfma_f32_16x16x32_bf16 v[112:115], v[156:159], v[194:197], v[112:115]
	v_mfma_f32_16x16x32_bf16 v[96:99], v[152:155], v[198:201], v[96:99]
	v_mfma_f32_16x16x32_bf16 v[96:99], v[156:159], v[202:205], v[96:99]
	v_mfma_f32_16x16x32_bf16 v[80:83], v[152:155], v[206:209], v[80:83]
	v_mfma_f32_16x16x32_bf16 v[80:83], v[156:159], v[210:213], v[80:83]
	s_setprio 0
	s_setprio 1
	v_mfma_f32_16x16x32_bf16 v[108:111], v[160:163], v[182:185], v[108:111]
	v_mfma_f32_16x16x32_bf16 v[108:111], v[164:167], v[186:189], v[108:111]
	v_mfma_f32_16x16x32_bf16 v[92:95], v[160:163], v[190:193], v[92:95]
	v_mfma_f32_16x16x32_bf16 v[92:95], v[164:167], v[194:197], v[92:95]
	v_mfma_f32_16x16x32_bf16 v[76:79], v[160:163], v[198:201], v[76:79]
	v_mfma_f32_16x16x32_bf16 v[76:79], v[164:167], v[202:205], v[76:79]
	v_mfma_f32_16x16x32_bf16 v[68:71], v[160:163], v[206:209], v[68:71]
	v_mfma_f32_16x16x32_bf16 v[68:71], v[164:167], v[210:213], v[68:71]
	v_mfma_f32_16x16x32_bf16 v[104:107], v[170:173], v[182:185], v[104:107]
	v_mfma_f32_16x16x32_bf16 v[104:107], v[178:181], v[186:189], v[104:107]
	v_mfma_f32_16x16x32_bf16 v[88:91], v[170:173], v[190:193], v[88:91]
	v_mfma_f32_16x16x32_bf16 v[88:91], v[178:181], v[194:197], v[88:91]
	v_mfma_f32_16x16x32_bf16 v[72:75], v[170:173], v[198:201], v[72:75]
	v_mfma_f32_16x16x32_bf16 v[72:75], v[178:181], v[202:205], v[72:75]
	v_mfma_f32_16x16x32_bf16 v[64:67], v[170:173], v[206:209], v[64:67]
	v_mfma_f32_16x16x32_bf16 v[64:67], v[178:181], v[210:213], v[64:67]
	s_barrier
	s_setprio 0
	s_add_i32 s12, s13, s8
	s_mov_b32 m0, s12
	ds_read_b128 v[182:185], v143 offset:16384
	ds_read_b128 v[186:189], v143 offset:17408
	ds_read_b128 v[190:193], v143 offset:18432
	ds_read_b128 v[194:197], v143 offset:19456
	ds_read_b128 v[198:201], v143 offset:20480
	ds_read_b128 v[202:205], v143 offset:21504
	ds_read_b128 v[206:209], v143 offset:22528
	ds_read_b128 v[210:213], v143 offset:23552
	global_load_lds_dwordx4 v130, s[88:89]
	s_add_i32 m0, s12, 0x2000
	s_add_u32 s42, s88, 0x80000
	s_addc_u32 s43, s89, 0
	s_add_i32 s3, s3, s8
	global_load_lds_dwordx4 v134, s[88:89]
	s_mov_b32 m0, s3
	s_nop 0
	global_load_lds_dwordx4 v130, s[42:43]
	s_add_i32 m0, s3, 0x2000
	s_nop 0
	global_load_lds_dwordx4 v134, s[42:43]
	s_mov_b32 m0, s9
	s_nop 0
	global_load_lds_dwordx4 v128, s[90:91]
	s_mov_b32 m0, s10
	s_nop 0
	global_load_lds_dwordx4 v132, s[90:91]
	s_waitcnt vmcnt(8)
	s_waitcnt lgkmcnt(0)
	s_barrier
	s_setprio 1
	v_mfma_f32_16x16x32_bf16 v[60:63], v[144:147], v[182:185], v[60:63]
	v_mfma_f32_16x16x32_bf16 v[60:63], v[148:151], v[186:189], v[60:63]
	v_mfma_f32_16x16x32_bf16 v[52:55], v[144:147], v[190:193], v[52:55]
	v_mfma_f32_16x16x32_bf16 v[52:55], v[148:151], v[194:197], v[52:55]
	v_mfma_f32_16x16x32_bf16 v[36:39], v[144:147], v[198:201], v[36:39]
	v_mfma_f32_16x16x32_bf16 v[36:39], v[148:151], v[202:205], v[36:39]
	v_mfma_f32_16x16x32_bf16 v[20:23], v[144:147], v[206:209], v[20:23]
	v_mfma_f32_16x16x32_bf16 v[20:23], v[148:151], v[210:213], v[20:23]
	v_mfma_f32_16x16x32_bf16 v[56:59], v[152:155], v[182:185], v[56:59]
	v_mfma_f32_16x16x32_bf16 v[56:59], v[156:159], v[186:189], v[56:59]
	v_mfma_f32_16x16x32_bf16 v[48:51], v[152:155], v[190:193], v[48:51]
	v_mfma_f32_16x16x32_bf16 v[48:51], v[156:159], v[194:197], v[48:51]
	v_mfma_f32_16x16x32_bf16 v[32:35], v[152:155], v[198:201], v[32:35]
	v_mfma_f32_16x16x32_bf16 v[32:35], v[156:159], v[202:205], v[32:35]
	v_mfma_f32_16x16x32_bf16 v[16:19], v[152:155], v[206:209], v[16:19]
	v_mfma_f32_16x16x32_bf16 v[16:19], v[156:159], v[210:213], v[16:19]
	s_setprio 0
	s_setprio 1
	v_mfma_f32_16x16x32_bf16 v[44:47], v[160:163], v[182:185], v[44:47]
	v_mfma_f32_16x16x32_bf16 v[44:47], v[164:167], v[186:189], v[44:47]
	v_mfma_f32_16x16x32_bf16 v[28:31], v[160:163], v[190:193], v[28:31]
	v_mfma_f32_16x16x32_bf16 v[28:31], v[164:167], v[194:197], v[28:31]
	v_mfma_f32_16x16x32_bf16 v[12:15], v[160:163], v[198:201], v[12:15]
	v_mfma_f32_16x16x32_bf16 v[12:15], v[164:167], v[202:205], v[12:15]
	v_mfma_f32_16x16x32_bf16 v[4:7], v[160:163], v[206:209], v[4:7]
	v_mfma_f32_16x16x32_bf16 v[4:7], v[164:167], v[210:213], v[4:7]
	v_mfma_f32_16x16x32_bf16 v[40:43], v[170:173], v[182:185], v[40:43]
	v_mfma_f32_16x16x32_bf16 v[40:43], v[178:181], v[186:189], v[40:43]
	v_mfma_f32_16x16x32_bf16 v[24:27], v[170:173], v[190:193], v[24:27]
	v_mfma_f32_16x16x32_bf16 v[24:27], v[178:181], v[194:197], v[24:27]
	v_mfma_f32_16x16x32_bf16 v[8:11], v[170:173], v[198:201], v[8:11]
	v_mfma_f32_16x16x32_bf16 v[8:11], v[178:181], v[202:205], v[8:11]
	v_mfma_f32_16x16x32_bf16 v[0:3], v[170:173], v[206:209], v[0:3]
	v_mfma_f32_16x16x32_bf16 v[0:3], v[178:181], v[210:213], v[0:3]
	s_barrier
; #define PG8_STAGE(bufoff, gbase, voff) do { _Pragma("unroll") for (int _i = 0; _i < 2; ++_i) \
;         __builtin_amdgcn_global_load_lds((const unsigned*)((const char*)(gbase) + (voff)[_i]), (PG8_LAS unsigned*)(lds + (bufoff) + ldsw + _i * 8192), 16, 0, 0); } while (0)
; #define PG8_LDA(dst, b, h) do { _Pragma("unroll") for (int m = 0; m < 4; ++m) _Pragma("unroll") for (int k = 0; k < 2; ++k) dst[m][k] = *(const PG8_LAS bf16x8*)(lds + PG8_SA(b, h) + aoff + m * 2048 + k * 1024); } while (0)
; #define PG8_LDB(dst, b, h) do { _Pragma("unroll") for (int n = 0; n < 2; ++n) _Pragma("unroll") for (int k = 0; k < 2; ++k) dst[n][k] = *(const PG8_LAS bf16x8*)(lds + PG8_SB(b, h) + boff + n * 2048 + k * 1024); } while (0)
; #define PG8_MMA(ai, bj, At, Bt) do { __builtin_amdgcn_s_setprio(1); _Pragma("unroll") for (int m = 0; m < 4; ++m) _Pragma("unroll") for (int n = 0; n < 2; ++n) _Pragma("unroll") for (int k = 0; k < 2; ++k) \
;         acc[ai][bj][m][n] = __builtin_amdgcn_mfma_f32_16x16x32_bf16(Bt[n][k], At[m][k], acc[ai][bj][m][n], 0, 0, 0); __builtin_amdgcn_s_setprio(0); } while (0)
; #define PG8_WAIT_V(n) asm volatile("s_waitcnt vmcnt(" #n ")" ::: "memory")
; #define PG8_WAIT_L(n) asm volatile("s_waitcnt lgkmcnt(" #n ")" ::: "memory")
; #define PG8_BAR __builtin_amdgcn_s_barrier()
; #define PG8_SCHED __builtin_amdgcn_sched_barrier(0)
;     ...
;         for (int t = 0; t < nt; t += 2) {
;     ...
;             PG8_LDB(B0, 1, 0); PG8_LDB(B1, 1, 1); PG8_SCHED; PG8_LDA(At, 1, 0); PG8_STAGE(PG8_SA(0, 1), a2 + hstep, voffA);
;             PG8_WAIT_V(8); PG8_WAIT_L(0); PG8_BAR; PG8_MMA(0, 0, At, B0); PG8_MMA(0, 1, At, B1); PG8_BAR; PG8_SCHED;
;             PG8_LDA(At, 1, 1); PG8_STAGE(PG8_SB(1, 0), b3, voffB); PG8_STAGE(PG8_SB(1, 1), b3 + hstep, voffB); PG8_STAGE(PG8_SA(1, 0), a3, voffA);
;             PG8_WAIT_V(8); PG8_WAIT_L(0); PG8_BAR; PG8_MMA(1, 0, At, B0); PG8_MMA(1, 1, At, B1); PG8_BAR; PG8_SCHED;
	s_setprio 0
	s_add_i32 s3, 0, 0x18000
	s_add_i32 s12, 0, 0x1c000
	v_add_u32_e32 v156, s3, v141
	v_add_u32_e32 v168, s12, v141
	ds_read_b128 v[144:147], v156
	ds_read_b128 v[148:151], v156 offset:1024
	ds_read_b128 v[152:155], v156 offset:2048
	ds_read_b128 v[156:159], v156 offset:3072
	ds_read_b128 v[160:163], v168
	ds_read_b128 v[164:167], v168 offset:1024
	ds_read_b128 v[170:173], v168 offset:2048
	ds_read_b128 v[178:181], v168 offset:3072
	s_add_u32 s42, s90, 0x80000
	s_addc_u32 s43, s91, 0
	s_mov_b32 m0, s18
	ds_read_b128 v[182:185], v143 offset:32768
	ds_read_b128 v[186:189], v143 offset:33792
	ds_read_b128 v[190:193], v143 offset:34816
	ds_read_b128 v[194:197], v143 offset:35840
	ds_read_b128 v[198:201], v143 offset:36864
	ds_read_b128 v[202:205], v143 offset:37888
	ds_read_b128 v[206:209], v143 offset:38912
	ds_read_b128 v[210:213], v143 offset:39936
	global_load_lds_dwordx4 v128, s[42:43]
	s_mov_b32 m0, s19
	s_nop 0
	global_load_lds_dwordx4 v132, s[42:43]
	s_waitcnt vmcnt(8)
	s_waitcnt lgkmcnt(0)
	s_barrier
	s_setprio 1
	v_mfma_f32_16x16x32_bf16 v[124:127], v[144:147], v[182:185], v[124:127]
	v_mfma_f32_16x16x32_bf16 v[124:127], v[148:151], v[186:189], v[124:127]
	v_mfma_f32_16x16x32_bf16 v[116:119], v[144:147], v[190:193], v[116:119]
	v_mfma_f32_16x16x32_bf16 v[116:119], v[148:151], v[194:197], v[116:119]
	v_mfma_f32_16x16x32_bf16 v[100:103], v[144:147], v[198:201], v[100:103]
	v_mfma_f32_16x16x32_bf16 v[100:103], v[148:151], v[202:205], v[100:103]
	v_mfma_f32_16x16x32_bf16 v[84:87], v[144:147], v[206:209], v[84:87]
	v_mfma_f32_16x16x32_bf16 v[84:87], v[148:151], v[210:213], v[84:87]
	v_mfma_f32_16x16x32_bf16 v[120:123], v[152:155], v[182:185], v[120:123]
	v_mfma_f32_16x16x32_bf16 v[120:123], v[156:159], v[186:189], v[120:123]
	v_mfma_f32_16x16x32_bf16 v[112:115], v[152:155], v[190:193], v[112:115]
	v_mfma_f32_16x16x32_bf16 v[112:115], v[156:159], v[194:197], v[112:115]
	v_mfma_f32_16x16x32_bf16 v[96:99], v[152:155], v[198:201], v[96:99]
	v_mfma_f32_16x16x32_bf16 v[96:99], v[156:159], v[202:205], v[96:99]
	v_mfma_f32_16x16x32_bf16 v[80:83], v[152:155], v[206:209], v[80:83]
	v_mfma_f32_16x16x32_bf16 v[80:83], v[156:159], v[210:213], v[80:83]
	s_setprio 0
	s_setprio 1
	v_mfma_f32_16x16x32_bf16 v[108:111], v[160:163], v[182:185], v[108:111]
	v_mfma_f32_16x16x32_bf16 v[108:111], v[164:167], v[186:189], v[108:111]
	v_mfma_f32_16x16x32_bf16 v[92:95], v[160:163], v[190:193], v[92:95]
	v_mfma_f32_16x16x32_bf16 v[92:95], v[164:167], v[194:197], v[92:95]
	v_mfma_f32_16x16x32_bf16 v[76:79], v[160:163], v[198:201], v[76:79]
	v_mfma_f32_16x16x32_bf16 v[76:79], v[164:167], v[202:205], v[76:79]
	v_mfma_f32_16x16x32_bf16 v[68:71], v[160:163], v[206:209], v[68:71]
	v_mfma_f32_16x16x32_bf16 v[68:71], v[164:167], v[210:213], v[68:71]
	v_mfma_f32_16x16x32_bf16 v[104:107], v[170:173], v[182:185], v[104:107]
	v_mfma_f32_16x16x32_bf16 v[104:107], v[178:181], v[186:189], v[104:107]
	v_mfma_f32_16x16x32_bf16 v[88:91], v[170:173], v[190:193], v[88:91]
	v_mfma_f32_16x16x32_bf16 v[88:91], v[178:181], v[194:197], v[88:91]
	v_mfma_f32_16x16x32_bf16 v[72:75], v[170:173], v[198:201], v[72:75]
	v_mfma_f32_16x16x32_bf16 v[72:75], v[178:181], v[202:205], v[72:75]
	v_mfma_f32_16x16x32_bf16 v[64:67], v[170:173], v[206:209], v[64:67]
	v_mfma_f32_16x16x32_bf16 v[64:67], v[178:181], v[210:213], v[64:67]
	s_barrier
	s_setprio 0
	s_add_i32 s3, s3, s8
	s_mov_b32 m0, s3
	ds_read_b128 v[182:185], v143 offset:49152
	ds_read_b128 v[186:189], v143 offset:50176
	ds_read_b128 v[190:193], v143 offset:51200
	ds_read_b128 v[194:197], v143 offset:52224
	ds_read_b128 v[198:201], v143 offset:53248
	ds_read_b128 v[202:205], v143 offset:54272
	ds_read_b128 v[206:209], v143 offset:55296
	ds_read_b128 v[210:213], v143 offset:56320
	s_add_u32 s100, s88, s16
	s_addc_u32 s101, s89, s17
	global_load_lds_dwordx4 v130, s[100:101]
	s_add_i32 m0, s3, 0x2000
	s_add_u32 s42, s88, 0x80080
	s_addc_u32 s43, s89, 0
	s_add_i32 s3, s12, s8
	global_load_lds_dwordx4 v134, s[100:101]
	s_mov_b32 m0, s3
	s_nop 0
	global_load_lds_dwordx4 v130, s[42:43]
	s_add_i32 m0, s3, 0x2000
	s_nop 0
	global_load_lds_dwordx4 v134, s[42:43]
	s_mov_b32 m0, s20
	s_nop 0
	s_add_u32 s100, s90, s16
	s_addc_u32 s101, s91, s17
	global_load_lds_dwordx4 v128, s[100:101]
	s_mov_b32 m0, s21
	s_nop 0
	global_load_lds_dwordx4 v132, s[100:101]
	s_waitcnt vmcnt(8)
	s_waitcnt lgkmcnt(0)
	s_barrier
	s_setprio 1
	v_mfma_f32_16x16x32_bf16 v[60:63], v[144:147], v[182:185], v[60:63]
	v_mfma_f32_16x16x32_bf16 v[60:63], v[148:151], v[186:189], v[60:63]
	v_mfma_f32_16x16x32_bf16 v[52:55], v[144:147], v[190:193], v[52:55]
	v_mfma_f32_16x16x32_bf16 v[52:55], v[148:151], v[194:197], v[52:55]
	v_mfma_f32_16x16x32_bf16 v[36:39], v[144:147], v[198:201], v[36:39]
	v_mfma_f32_16x16x32_bf16 v[36:39], v[148:151], v[202:205], v[36:39]
	v_mfma_f32_16x16x32_bf16 v[20:23], v[144:147], v[206:209], v[20:23]
	v_mfma_f32_16x16x32_bf16 v[20:23], v[148:151], v[210:213], v[20:23]
	v_mfma_f32_16x16x32_bf16 v[56:59], v[152:155], v[182:185], v[56:59]
	v_mfma_f32_16x16x32_bf16 v[56:59], v[156:159], v[186:189], v[56:59]
	v_mfma_f32_16x16x32_bf16 v[48:51], v[152:155], v[190:193], v[48:51]
	v_mfma_f32_16x16x32_bf16 v[48:51], v[156:159], v[194:197], v[48:51]
	v_mfma_f32_16x16x32_bf16 v[32:35], v[152:155], v[198:201], v[32:35]
	v_mfma_f32_16x16x32_bf16 v[32:35], v[156:159], v[202:205], v[32:35]
	v_mfma_f32_16x16x32_bf16 v[16:19], v[152:155], v[206:209], v[16:19]
	v_mfma_f32_16x16x32_bf16 v[16:19], v[156:159], v[210:213], v[16:19]
	s_setprio 0
	s_setprio 1
	v_mfma_f32_16x16x32_bf16 v[44:47], v[160:163], v[182:185], v[44:47]
	v_mfma_f32_16x16x32_bf16 v[44:47], v[164:167], v[186:189], v[44:47]
	v_mfma_f32_16x16x32_bf16 v[28:31], v[160:163], v[190:193], v[28:31]
	v_mfma_f32_16x16x32_bf16 v[28:31], v[164:167], v[194:197], v[28:31]
	v_mfma_f32_16x16x32_bf16 v[12:15], v[160:163], v[198:201], v[12:15]
	v_mfma_f32_16x16x32_bf16 v[12:15], v[164:167], v[202:205], v[12:15]
	v_mfma_f32_16x16x32_bf16 v[4:7], v[160:163], v[206:209], v[4:7]
	v_mfma_f32_16x16x32_bf16 v[4:7], v[164:167], v[210:213], v[4:7]
	v_mfma_f32_16x16x32_bf16 v[40:43], v[170:173], v[182:185], v[40:43]
	v_mfma_f32_16x16x32_bf16 v[40:43], v[178:181], v[186:189], v[40:43]
	v_mfma_f32_16x16x32_bf16 v[24:27], v[170:173], v[190:193], v[24:27]
	v_mfma_f32_16x16x32_bf16 v[24:27], v[178:181], v[194:197], v[24:27]
	v_mfma_f32_16x16x32_bf16 v[8:11], v[170:173], v[198:201], v[8:11]
	v_mfma_f32_16x16x32_bf16 v[8:11], v[178:181], v[202:205], v[8:11]
	v_mfma_f32_16x16x32_bf16 v[0:3], v[170:173], v[206:209], v[0:3]
	v_mfma_f32_16x16x32_bf16 v[0:3], v[178:181], v[210:213], v[0:3]
	s_barrier
	s_setprio 0
	s_add_i32 s2, s2, 2
	s_add_u32 s86, s86, 0x100
	s_addc_u32 s87, s87, 0
	s_add_u32 s33, s33, 0x100
	s_addc_u32 s40, s40, 0
	s_cmp_gt_u32 s2, 29
	s_cbranch_scc0 .LBB0_490
	s_and_b64 vcc, exec, s[74:75]
	s_cbranch_vccz .LBB0_493
	s_barrier

; #define PG8_STAGE(bufoff, gbase, voff) do { _Pragma("unroll") for (int _i = 0; _i < 2; ++_i) \
;         __builtin_amdgcn_global_load_lds((const unsigned*)((const char*)(gbase) + (voff)[_i]), (PG8_LAS unsigned*)(lds + (bufoff) + ldsw + _i * 8192), 16, 0, 0); } while (0)
; #define PG8_LDA(dst, b, h) do { _Pragma("unroll") for (int m = 0; m < 4; ++m) _Pragma("unroll") for (int k = 0; k < 2; ++k) dst[m][k] = *(const PG8_LAS bf16x8*)(lds + PG8_SA(b, h) + aoff + m * 2048 + k * 1024); } while (0)
; #define PG8_LDB(dst, b, h) do { _Pragma("unroll") for (int n = 0; n < 2; ++n) _Pragma("unroll") for (int k = 0; k < 2; ++k) dst[n][k] = *(const PG8_LAS bf16x8*)(lds + PG8_SB(b, h) + boff + n * 2048 + k * 1024); } while (0)
; #define PG8_MMA(ai, bj, At, Bt) do { __builtin_amdgcn_s_setprio(1); _Pragma("unroll") for (int m = 0; m < 4; ++m) _Pragma("unroll") for (int n = 0; n < 2; ++n) _Pragma("unroll") for (int k = 0; k < 2; ++k) \
;         acc[ai][bj][m][n] = __builtin_amdgcn_mfma_f32_16x16x32_bf16(Bt[n][k], At[m][k], acc[ai][bj][m][n], 0, 0, 0); __builtin_amdgcn_s_setprio(0); } while (0)
; #define PG8_WAIT_V(n) asm volatile("s_waitcnt vmcnt(" #n ")" ::: "memory")
; #define PG8_WAIT_L(n) asm volatile("s_waitcnt lgkmcnt(" #n ")" ::: "memory")
; #define PG8_BAR __builtin_amdgcn_s_barrier()
; #define PG8_SCHED __builtin_amdgcn_sched_barrier(0)
;     ...
;             const bool last = (t == nt - 2);
;             const char* a1 = PG8_KADV(cA, (size_t)(t + 1) * kstep);
;             const char* a2 = last ? nA : PG8_KADV(cA, (size_t)(t + 2) * kstep); const char* b2 = last ? nB : PG8_KADV(cB, (size_t)(t + 2) * kstep);
;             const char* a3 = PG8_KADV(a2, kstep); const char* b3 = PG8_KADV(b2, kstep);
;             if (last && has_next) S.a_ready(nxt);
;             if constexpr (SP2) {
;             PG8_LDB(B0, 0, 0); PG8_LDB(B1, 0, 1); PG8_SCHED; PG8_LDA(At, 0, 0); PG8_STAGE(PG8_SA(1, 1), a1 + hstep, voffA);
;             PG8_WAIT_V(8); PG8_WAIT_L(0); PG8_BAR; PG8_MMA(0, 0, At, B0); PG8_MMA(0, 1, At, B1); PG8_BAR; PG8_SCHED;
;             PG8_LDA(At, 0, 1); PG8_STAGE(PG8_SB(0, 0), b2, voffB); PG8_STAGE(PG8_SB(0, 1), b2 + hstep, voffB); PG8_STAGE(PG8_SA(0, 0), a2, voffA);
.LBB0_514:
	s_add_u32 s3, s86, 0xfff80080
	s_addc_u32 s12, s87, -1
	s_add_i32 s13, 0, 0x10000
	s_cmp_eq_u32 s2, 28
	s_cselect_b32 s91, s28, s12
	s_cselect_b32 s90, s30, s3
	s_cselect_b32 s89, s33, s43
	s_cselect_b32 s88, s40, s42
	s_add_i32 s3, 0, 0x14000
	v_add_u32_e32 v156, s13, v141
	v_add_u32_e32 v168, s3, v141
	ds_read_b128 v[144:147], v156
	ds_read_b128 v[148:151], v156 offset:1024
	ds_read_b128 v[152:155], v156 offset:2048
	ds_read_b128 v[156:159], v156 offset:3072
	ds_read_b128 v[160:163], v168
	ds_read_b128 v[164:167], v168 offset:1024
	ds_read_b128 v[170:173], v168 offset:2048
	ds_read_b128 v[178:181], v168 offset:3072
	s_add_i32 m0, s18, 0xc000
	ds_read_b128 v[182:185], v143
	ds_read_b128 v[186:189], v143 offset:1024
	ds_read_b128 v[190:193], v143 offset:2048
	ds_read_b128 v[194:197], v143 offset:3072
	ds_read_b128 v[198:201], v143 offset:4096
	ds_read_b128 v[202:205], v143 offset:5120
	ds_read_b128 v[206:209], v143 offset:6144
	ds_read_b128 v[210:213], v143 offset:7168
	global_load_lds_dwordx4 v136, s[86:87]
	s_add_i32 m0, s18, 0xe000
	s_nop 0
	global_load_lds_dwordx4 v138, s[86:87]
	s_waitcnt vmcnt(8)
	s_waitcnt lgkmcnt(0)
	s_barrier
	s_setprio 1
	v_mfma_f32_16x16x32_bf16 v[124:127], v[144:147], v[182:185], v[124:127]
	v_mfma_f32_16x16x32_bf16 v[124:127], v[148:151], v[186:189], v[124:127]
	v_mfma_f32_16x16x32_bf16 v[116:119], v[144:147], v[190:193], v[116:119]
	v_mfma_f32_16x16x32_bf16 v[116:119], v[148:151], v[194:197], v[116:119]
	v_mfma_f32_16x16x32_bf16 v[100:103], v[144:147], v[198:201], v[100:103]
	v_mfma_f32_16x16x32_bf16 v[100:103], v[148:151], v[202:205], v[100:103]
	v_mfma_f32_16x16x32_bf16 v[84:87], v[144:147], v[206:209], v[84:87]
	v_mfma_f32_16x16x32_bf16 v[84:87], v[148:151], v[210:213], v[84:87]
	v_mfma_f32_16x16x32_bf16 v[120:123], v[152:155], v[182:185], v[120:123]
	v_mfma_f32_16x16x32_bf16 v[120:123], v[156:159], v[186:189], v[120:123]
	v_mfma_f32_16x16x32_bf16 v[112:115], v[152:155], v[190:193], v[112:115]
	v_mfma_f32_16x16x32_bf16 v[112:115], v[156:159], v[194:197], v[112:115]
	v_mfma_f32_16x16x32_bf16 v[96:99], v[152:155], v[198:201], v[96:99]
	v_mfma_f32_16x16x32_bf16 v[96:99], v[156:159], v[202:205], v[96:99]
	v_mfma_f32_16x16x32_bf16 v[80:83], v[152:155], v[206:209], v[80:83]
	v_mfma_f32_16x16x32_bf16 v[80:83], v[156:159], v[210:213], v[80:83]
	s_setprio 0
	s_setprio 1
	v_mfma_f32_16x16x32_bf16 v[108:111], v[160:163], v[182:185], v[108:111]
	v_mfma_f32_16x16x32_bf16 v[108:111], v[164:167], v[186:189], v[108:111]
	v_mfma_f32_16x16x32_bf16 v[92:95], v[160:163], v[190:193], v[92:95]
	v_mfma_f32_16x16x32_bf16 v[92:95], v[164:167], v[194:197], v[92:95]
	v_mfma_f32_16x16x32_bf16 v[76:79], v[160:163], v[198:201], v[76:79]
	v_mfma_f32_16x16x32_bf16 v[76:79], v[164:167], v[202:205], v[76:79]
	v_mfma_f32_16x16x32_bf16 v[68:71], v[160:163], v[206:209], v[68:71]
	v_mfma_f32_16x16x32_bf16 v[68:71], v[164:167], v[210:213], v[68:71]
	v_mfma_f32_16x16x32_bf16 v[104:107], v[170:173], v[182:185], v[104:107]
	v_mfma_f32_16x16x32_bf16 v[104:107], v[178:181], v[186:189], v[104:107]
	v_mfma_f32_16x16x32_bf16 v[88:91], v[170:173], v[190:193], v[88:91]
	v_mfma_f32_16x16x32_bf16 v[88:91], v[178:181], v[194:197], v[88:91]
	v_mfma_f32_16x16x32_bf16 v[72:75], v[170:173], v[198:201], v[72:75]
	v_mfma_f32_16x16x32_bf16 v[72:75], v[178:181], v[202:205], v[72:75]
	v_mfma_f32_16x16x32_bf16 v[64:67], v[170:173], v[206:209], v[64:67]
	v_mfma_f32_16x16x32_bf16 v[64:67], v[178:181], v[210:213], v[64:67]
	s_barrier
	s_setprio 0
	s_add_i32 s12, s13, s10
	s_mov_b32 m0, s12
	ds_read_b128 v[182:185], v143 offset:16384
	ds_read_b128 v[186:189], v143 offset:17408
	ds_read_b128 v[190:193], v143 offset:18432
	ds_read_b128 v[194:197], v143 offset:19456
	ds_read_b128 v[198:201], v143 offset:20480
	ds_read_b128 v[202:205], v143 offset:21504
	ds_read_b128 v[206:209], v143 offset:22528
	ds_read_b128 v[210:213], v143 offset:23552
	global_load_lds_dwordx4 v130, s[88:89]
	s_add_i32 m0, s12, 0x2000
	s_add_u32 vcc_lo, s88, 0x80000
	v_lshl_add_u64 v[216:217], s[88:89], 0, v[134:135]
	s_addc_u32 vcc_hi, s89, 0
	s_add_i32 s3, s3, s10
	global_load_lds_dwordx4 v134, s[88:89]
	s_mov_b32 m0, s3
	v_lshl_add_u64 v[220:221], s[90:91], 0, v[132:133]
	global_load_lds_dwordx4 v130, vcc
	s_add_i32 m0, s3, 0x2000
	s_nop 0
	global_load_lds_dwordx4 v134, vcc
	v_lshl_add_u64 v[218:219], s[90:91], 0, v[128:129]
	s_mov_b32 m0, s18
	s_nop 0
	global_load_lds_dwordx4 v128, s[90:91]
	s_mov_b32 m0, s19
	s_nop 0
	global_load_lds_dwordx4 v132, s[90:91]
	s_waitcnt vmcnt(8)
	s_waitcnt lgkmcnt(0)
	s_barrier
; #define PG8_STAGE(bufoff, gbase, voff) do { _Pragma("unroll") for (int _i = 0; _i < 2; ++_i) \
;         __builtin_amdgcn_global_load_lds((const unsigned*)((const char*)(gbase) + (voff)[_i]), (PG8_LAS unsigned*)(lds + (bufoff) + ldsw + _i * 8192), 16, 0, 0); } while (0)
; #define PG8_LDA(dst, b, h) do { _Pragma("unroll") for (int m = 0; m < 4; ++m) _Pragma("unroll") for (int k = 0; k < 2; ++k) dst[m][k] = *(const PG8_LAS bf16x8*)(lds + PG8_SA(b, h) + aoff + m * 2048 + k * 1024); } while (0)
; #define PG8_LDB(dst, b, h) do { _Pragma("unroll") for (int n = 0; n < 2; ++n) _Pragma("unroll") for (int k = 0; k < 2; ++k) dst[n][k] = *(const PG8_LAS bf16x8*)(lds + PG8_SB(b, h) + boff + n * 2048 + k * 1024); } while (0)
; #define PG8_MMA(ai, bj, At, Bt) do { __builtin_amdgcn_s_setprio(1); _Pragma("unroll") for (int m = 0; m < 4; ++m) _Pragma("unroll") for (int n = 0; n < 2; ++n) _Pragma("unroll") for (int k = 0; k < 2; ++k) \
;         acc[ai][bj][m][n] = __builtin_amdgcn_mfma_f32_16x16x32_bf16(Bt[n][k], At[m][k], acc[ai][bj][m][n], 0, 0, 0); __builtin_amdgcn_s_setprio(0); } while (0)
; #define PG8_WAIT_V(n) asm volatile("s_waitcnt vmcnt(" #n ")" ::: "memory")
; #define PG8_WAIT_L(n) asm volatile("s_waitcnt lgkmcnt(" #n ")" ::: "memory")
; #define PG8_BAR __builtin_amdgcn_s_barrier()
; #define PG8_SCHED __builtin_amdgcn_sched_barrier(0)
;     ...
;             PG8_WAIT_V(8); PG8_WAIT_L(0); PG8_BAR; PG8_MMA(0, 0, At, B0); PG8_MMA(0, 1, At, B1); PG8_BAR; PG8_SCHED;
;             PG8_LDA(At, 0, 1); PG8_STAGE(PG8_SB(0, 0), b2, voffB); PG8_STAGE(PG8_SB(0, 1), b2 + hstep, voffB); PG8_STAGE(PG8_SA(0, 0), a2, voffA);
;             PG8_WAIT_V(8); PG8_WAIT_L(0); PG8_BAR; PG8_MMA(1, 0, At, B0); PG8_MMA(1, 1, At, B1); PG8_BAR; PG8_SCHED;
;             PG8_LDB(B0, 1, 0); PG8_LDB(B1, 1, 1); PG8_SCHED; PG8_LDA(At, 1, 0); PG8_STAGE(PG8_SA(0, 1), a2 + hstep, voffA);
;             PG8_WAIT_V(8); PG8_WAIT_L(0); PG8_BAR; PG8_MMA(0, 0, At, B0); PG8_MMA(0, 1, At, B1); PG8_BAR; PG8_SCHED;
	s_setprio 1
	v_mfma_f32_16x16x32_bf16 v[60:63], v[144:147], v[182:185], v[60:63]
	v_mfma_f32_16x16x32_bf16 v[60:63], v[148:151], v[186:189], v[60:63]
	v_mfma_f32_16x16x32_bf16 v[52:55], v[144:147], v[190:193], v[52:55]
	v_mfma_f32_16x16x32_bf16 v[52:55], v[148:151], v[194:197], v[52:55]
	v_mfma_f32_16x16x32_bf16 v[36:39], v[144:147], v[198:201], v[36:39]
	v_mfma_f32_16x16x32_bf16 v[36:39], v[148:151], v[202:205], v[36:39]
	v_mfma_f32_16x16x32_bf16 v[20:23], v[144:147], v[206:209], v[20:23]
	v_mfma_f32_16x16x32_bf16 v[20:23], v[148:151], v[210:213], v[20:23]
	v_mfma_f32_16x16x32_bf16 v[56:59], v[152:155], v[182:185], v[56:59]
	v_mfma_f32_16x16x32_bf16 v[56:59], v[156:159], v[186:189], v[56:59]
	v_mfma_f32_16x16x32_bf16 v[48:51], v[152:155], v[190:193], v[48:51]
	v_mfma_f32_16x16x32_bf16 v[48:51], v[156:159], v[194:197], v[48:51]
	v_mfma_f32_16x16x32_bf16 v[32:35], v[152:155], v[198:201], v[32:35]
	v_mfma_f32_16x16x32_bf16 v[32:35], v[156:159], v[202:205], v[32:35]
	v_mfma_f32_16x16x32_bf16 v[16:19], v[152:155], v[206:209], v[16:19]
	v_mfma_f32_16x16x32_bf16 v[16:19], v[156:159], v[210:213], v[16:19]
	s_setprio 0
	s_setprio 1
	v_mfma_f32_16x16x32_bf16 v[44:47], v[160:163], v[182:185], v[44:47]
	v_mfma_f32_16x16x32_bf16 v[44:47], v[164:167], v[186:189], v[44:47]
	v_mfma_f32_16x16x32_bf16 v[28:31], v[160:163], v[190:193], v[28:31]
	v_mfma_f32_16x16x32_bf16 v[28:31], v[164:167], v[194:197], v[28:31]
	v_mfma_f32_16x16x32_bf16 v[12:15], v[160:163], v[198:201], v[12:15]
	v_mfma_f32_16x16x32_bf16 v[12:15], v[164:167], v[202:205], v[12:15]
	v_mfma_f32_16x16x32_bf16 v[4:7], v[160:163], v[206:209], v[4:7]
	v_mfma_f32_16x16x32_bf16 v[4:7], v[164:167], v[210:213], v[4:7]
	v_mfma_f32_16x16x32_bf16 v[40:43], v[170:173], v[182:185], v[40:43]
	v_mfma_f32_16x16x32_bf16 v[40:43], v[178:181], v[186:189], v[40:43]
	v_mfma_f32_16x16x32_bf16 v[24:27], v[170:173], v[190:193], v[24:27]
	v_mfma_f32_16x16x32_bf16 v[24:27], v[178:181], v[194:197], v[24:27]
	v_mfma_f32_16x16x32_bf16 v[8:11], v[170:173], v[198:201], v[8:11]
	v_mfma_f32_16x16x32_bf16 v[8:11], v[178:181], v[202:205], v[8:11]
	v_mfma_f32_16x16x32_bf16 v[0:3], v[170:173], v[206:209], v[0:3]
	v_mfma_f32_16x16x32_bf16 v[0:3], v[178:181], v[210:213], v[0:3]
	s_barrier
	s_setprio 0
	s_add_i32 s3, 0, 0x18000
	s_add_i32 s12, 0, 0x1c000
	v_add_u32_e32 v156, s3, v141
	v_add_u32_e32 v168, s12, v141
	ds_read_b128 v[144:147], v156
	ds_read_b128 v[148:151], v156 offset:1024
	ds_read_b128 v[152:155], v156 offset:2048
	ds_read_b128 v[156:159], v156 offset:3072
	ds_read_b128 v[160:163], v168
	ds_read_b128 v[164:167], v168 offset:1024
	ds_read_b128 v[170:173], v168 offset:2048
	ds_read_b128 v[178:181], v168 offset:3072
	s_add_u32 s90, s90, 0x80000
	s_addc_u32 s91, s91, 0
	s_mov_b32 m0, s20
	ds_read_b128 v[182:185], v143 offset:32768
	ds_read_b128 v[186:189], v143 offset:33792
	ds_read_b128 v[190:193], v143 offset:34816
	ds_read_b128 v[194:197], v143 offset:35840
	ds_read_b128 v[198:201], v143 offset:36864
	ds_read_b128 v[202:205], v143 offset:37888
	ds_read_b128 v[206:209], v143 offset:38912
	ds_read_b128 v[210:213], v143 offset:39936
	global_load_lds_dwordx4 v128, s[90:91]
	s_mov_b32 m0, s21
	s_nop 0
	global_load_lds_dwordx4 v132, s[90:91]
	s_waitcnt vmcnt(8)
	s_waitcnt lgkmcnt(0)
	s_barrier
	s_setprio 1
	v_mfma_f32_16x16x32_bf16 v[124:127], v[144:147], v[182:185], v[124:127]
	v_mfma_f32_16x16x32_bf16 v[124:127], v[148:151], v[186:189], v[124:127]
	v_mfma_f32_16x16x32_bf16 v[116:119], v[144:147], v[190:193], v[116:119]
	v_mfma_f32_16x16x32_bf16 v[116:119], v[148:151], v[194:197], v[116:119]
	v_mfma_f32_16x16x32_bf16 v[100:103], v[144:147], v[198:201], v[100:103]
	v_mfma_f32_16x16x32_bf16 v[100:103], v[148:151], v[202:205], v[100:103]
	v_mfma_f32_16x16x32_bf16 v[84:87], v[144:147], v[206:209], v[84:87]
	v_mfma_f32_16x16x32_bf16 v[84:87], v[148:151], v[210:213], v[84:87]
	v_mfma_f32_16x16x32_bf16 v[120:123], v[152:155], v[182:185], v[120:123]
	v_mfma_f32_16x16x32_bf16 v[120:123], v[156:159], v[186:189], v[120:123]
	v_mfma_f32_16x16x32_bf16 v[112:115], v[152:155], v[190:193], v[112:115]
	v_mfma_f32_16x16x32_bf16 v[112:115], v[156:159], v[194:197], v[112:115]
	v_mfma_f32_16x16x32_bf16 v[96:99], v[152:155], v[198:201], v[96:99]
	v_mfma_f32_16x16x32_bf16 v[96:99], v[156:159], v[202:205], v[96:99]
	v_mfma_f32_16x16x32_bf16 v[80:83], v[152:155], v[206:209], v[80:83]
	v_mfma_f32_16x16x32_bf16 v[80:83], v[156:159], v[210:213], v[80:83]
	s_setprio 0
	s_setprio 1
	v_mfma_f32_16x16x32_bf16 v[108:111], v[160:163], v[182:185], v[108:111]
	v_mfma_f32_16x16x32_bf16 v[108:111], v[164:167], v[186:189], v[108:111]
	v_mfma_f32_16x16x32_bf16 v[92:95], v[160:163], v[190:193], v[92:95]
	v_mfma_f32_16x16x32_bf16 v[92:95], v[164:167], v[194:197], v[92:95]
	v_mfma_f32_16x16x32_bf16 v[76:79], v[160:163], v[198:201], v[76:79]
	v_mfma_f32_16x16x32_bf16 v[76:79], v[164:167], v[202:205], v[76:79]
	v_mfma_f32_16x16x32_bf16 v[68:71], v[160:163], v[206:209], v[68:71]
	v_mfma_f32_16x16x32_bf16 v[68:71], v[164:167], v[210:213], v[68:71]
	v_mfma_f32_16x16x32_bf16 v[104:107], v[170:173], v[182:185], v[104:107]
	v_mfma_f32_16x16x32_bf16 v[104:107], v[178:181], v[186:189], v[104:107]
	v_mfma_f32_16x16x32_bf16 v[88:91], v[170:173], v[190:193], v[88:91]
	v_mfma_f32_16x16x32_bf16 v[88:91], v[178:181], v[194:197], v[88:91]
	v_mfma_f32_16x16x32_bf16 v[72:75], v[170:173], v[198:201], v[72:75]
	v_mfma_f32_16x16x32_bf16 v[72:75], v[178:181], v[202:205], v[72:75]
	v_mfma_f32_16x16x32_bf16 v[64:67], v[170:173], v[206:209], v[64:67]
	v_mfma_f32_16x16x32_bf16 v[64:67], v[178:181], v[210:213], v[64:67]
	s_barrier
; #define PG8_STAGE(bufoff, gbase, voff) do { _Pragma("unroll") for (int _i = 0; _i < 2; ++_i) \
;         __builtin_amdgcn_global_load_lds((const unsigned*)((const char*)(gbase) + (voff)[_i]), (PG8_LAS unsigned*)(lds + (bufoff) + ldsw + _i * 8192), 16, 0, 0); } while (0)
; #define PG8_LDA(dst, b, h) do { _Pragma("unroll") for (int m = 0; m < 4; ++m) _Pragma("unroll") for (int k = 0; k < 2; ++k) dst[m][k] = *(const PG8_LAS bf16x8*)(lds + PG8_SA(b, h) + aoff + m * 2048 + k * 1024); } while (0)
; #define PG8_MMA(ai, bj, At, Bt) do { __builtin_amdgcn_s_setprio(1); _Pragma("unroll") for (int m = 0; m < 4; ++m) _Pragma("unroll") for (int n = 0; n < 2; ++n) _Pragma("unroll") for (int k = 0; k < 2; ++k) \
;         acc[ai][bj][m][n] = __builtin_amdgcn_mfma_f32_16x16x32_bf16(Bt[n][k], At[m][k], acc[ai][bj][m][n], 0, 0, 0); __builtin_amdgcn_s_setprio(0); } while (0)
; #define PG8_WAIT_V(n) asm volatile("s_waitcnt vmcnt(" #n ")" ::: "memory")
; #define PG8_WAIT_L(n) asm volatile("s_waitcnt lgkmcnt(" #n ")" ::: "memory")
; #define PG8_BAR __builtin_amdgcn_s_barrier()
; #define PG8_SCHED __builtin_amdgcn_sched_barrier(0)
;     ...
;         for (int t = 0; t < nt; t += 2) {
;     ...
;             PG8_LDA(At, 1, 1); PG8_STAGE(PG8_SB(1, 0), b3, voffB); PG8_STAGE(PG8_SB(1, 1), b3 + hstep, voffB); PG8_STAGE(PG8_SA(1, 0), a3, voffA);
;             PG8_WAIT_V(8); PG8_WAIT_L(0); PG8_BAR; PG8_MMA(1, 0, At, B0); PG8_MMA(1, 1, At, B1); PG8_BAR; PG8_SCHED;
	s_setprio 0
	s_add_i32 s3, s3, s10
	s_mov_b32 m0, s3
	ds_read_b128 v[182:185], v143 offset:49152
	ds_read_b128 v[186:189], v143 offset:50176
	ds_read_b128 v[190:193], v143 offset:51200
	ds_read_b128 v[194:197], v143 offset:52224
	ds_read_b128 v[198:201], v143 offset:53248
	ds_read_b128 v[202:205], v143 offset:54272
	ds_read_b128 v[206:209], v143 offset:55296
	ds_read_b128 v[210:213], v143 offset:56320
	s_add_u32 s100, s88, s16
	s_addc_u32 s101, s89, s17
	global_load_lds_dwordx4 v130, s[100:101]
	s_add_i32 m0, s3, 0x2000
	s_add_u32 s88, s88, 0x80080
	v_lshl_add_u64 v[214:215], v[216:217], 0, s[16:17]
	s_addc_u32 s89, s89, 0
	s_add_i32 s3, s12, s10
	global_load_lds_dwordx4 v[214:215], off
	s_mov_b32 m0, s3
	s_nop 0
	global_load_lds_dwordx4 v130, s[88:89]
	s_add_i32 m0, s3, 0x2000
	s_nop 0
	global_load_lds_dwordx4 v134, s[88:89]
	v_lshl_add_u64 v[214:215], v[218:219], 0, s[16:17]
	s_mov_b32 m0, s22
	s_nop 0
	global_load_lds_dwordx4 v[214:215], off
	v_lshl_add_u64 v[214:215], v[220:221], 0, s[16:17]
	s_mov_b32 m0, s23
	s_nop 0
	global_load_lds_dwordx4 v[214:215], off
	s_waitcnt vmcnt(8)
	s_waitcnt lgkmcnt(0)
	s_barrier
	s_setprio 1
	v_mfma_f32_16x16x32_bf16 v[60:63], v[144:147], v[182:185], v[60:63]
	v_mfma_f32_16x16x32_bf16 v[60:63], v[148:151], v[186:189], v[60:63]
	v_mfma_f32_16x16x32_bf16 v[52:55], v[144:147], v[190:193], v[52:55]
	v_mfma_f32_16x16x32_bf16 v[52:55], v[148:151], v[194:197], v[52:55]
	v_mfma_f32_16x16x32_bf16 v[36:39], v[144:147], v[198:201], v[36:39]
	v_mfma_f32_16x16x32_bf16 v[36:39], v[148:151], v[202:205], v[36:39]
	v_mfma_f32_16x16x32_bf16 v[20:23], v[144:147], v[206:209], v[20:23]
	v_mfma_f32_16x16x32_bf16 v[20:23], v[148:151], v[210:213], v[20:23]
	v_mfma_f32_16x16x32_bf16 v[56:59], v[152:155], v[182:185], v[56:59]
	v_mfma_f32_16x16x32_bf16 v[56:59], v[156:159], v[186:189], v[56:59]
	v_mfma_f32_16x16x32_bf16 v[48:51], v[152:155], v[190:193], v[48:51]
	v_mfma_f32_16x16x32_bf16 v[48:51], v[156:159], v[194:197], v[48:51]
	v_mfma_f32_16x16x32_bf16 v[32:35], v[152:155], v[198:201], v[32:35]
	v_mfma_f32_16x16x32_bf16 v[32:35], v[156:159], v[202:205], v[32:35]
	v_mfma_f32_16x16x32_bf16 v[16:19], v[152:155], v[206:209], v[16:19]
	v_mfma_f32_16x16x32_bf16 v[16:19], v[156:159], v[210:213], v[16:19]
	s_setprio 0
	s_setprio 1
	v_mfma_f32_16x16x32_bf16 v[44:47], v[160:163], v[182:185], v[44:47]
	v_mfma_f32_16x16x32_bf16 v[44:47], v[164:167], v[186:189], v[44:47]
	v_mfma_f32_16x16x32_bf16 v[28:31], v[160:163], v[190:193], v[28:31]
	v_mfma_f32_16x16x32_bf16 v[28:31], v[164:167], v[194:197], v[28:31]
	v_mfma_f32_16x16x32_bf16 v[12:15], v[160:163], v[198:201], v[12:15]
	v_mfma_f32_16x16x32_bf16 v[12:15], v[164:167], v[202:205], v[12:15]
	v_mfma_f32_16x16x32_bf16 v[4:7], v[160:163], v[206:209], v[4:7]
	v_mfma_f32_16x16x32_bf16 v[4:7], v[164:167], v[210:213], v[4:7]
	v_mfma_f32_16x16x32_bf16 v[40:43], v[170:173], v[182:185], v[40:43]
	v_mfma_f32_16x16x32_bf16 v[40:43], v[178:181], v[186:189], v[40:43]
	v_mfma_f32_16x16x32_bf16 v[24:27], v[170:173], v[190:193], v[24:27]
	v_mfma_f32_16x16x32_bf16 v[24:27], v[178:181], v[194:197], v[24:27]
	v_mfma_f32_16x16x32_bf16 v[8:11], v[170:173], v[198:201], v[8:11]
	v_mfma_f32_16x16x32_bf16 v[8:11], v[178:181], v[202:205], v[8:11]
	v_mfma_f32_16x16x32_bf16 v[0:3], v[170:173], v[206:209], v[0:3]
	v_mfma_f32_16x16x32_bf16 v[0:3], v[178:181], v[210:213], v[0:3]
	s_barrier
	s_setprio 0
	s_add_i32 s2, s2, 2
	s_add_u32 s86, s86, 0x100
	s_addc_u32 s87, s87, 0
	s_add_u32 s42, s42, 0x100
	s_addc_u32 s43, s43, 0
	s_cmp_gt_u32 s2, 29
	s_cbranch_scc0 .LBB0_514
	s_and_b64 vcc, exec, s[74:75]
	s_cbranch_vccz .LBB0_517
	s_barrier

; #define PG8_STAGE(bufoff, gbase, voff) do { _Pragma("unroll") for (int _i = 0; _i < 2; ++_i) \
;         __builtin_amdgcn_global_load_lds((const unsigned*)((const char*)(gbase) + (voff)[_i]), (PG8_LAS unsigned*)(lds + (bufoff) + ldsw + _i * 8192), 16, 0, 0); } while (0)
; #define PG8_LDA(dst, b, h) do { _Pragma("unroll") for (int m = 0; m < 4; ++m) _Pragma("unroll") for (int k = 0; k < 2; ++k) dst[m][k] = *(const PG8_LAS bf16x8*)(lds + PG8_SA(b, h) + aoff + m * 2048 + k * 1024); } while (0)
; #define PG8_LDB(dst, b, h) do { _Pragma("unroll") for (int n = 0; n < 2; ++n) _Pragma("unroll") for (int k = 0; k < 2; ++k) dst[n][k] = *(const PG8_LAS bf16x8*)(lds + PG8_SB(b, h) + boff + n * 2048 + k * 1024); } while (0)
; #define PG8_MMA(ai, bj, At, Bt) do { __builtin_amdgcn_s_setprio(1); _Pragma("unroll") for (int m = 0; m < 4; ++m) _Pragma("unroll") for (int n = 0; n < 2; ++n) _Pragma("unroll") for (int k = 0; k < 2; ++k) \
;         acc[ai][bj][m][n] = __builtin_amdgcn_mfma_f32_16x16x32_bf16(Bt[n][k], At[m][k], acc[ai][bj][m][n], 0, 0, 0); __builtin_amdgcn_s_setprio(0); } while (0)
; #define PG8_WAIT_V(n) asm volatile("s_waitcnt vmcnt(" #n ")" ::: "memory")
; #define PG8_WAIT_L(n) asm volatile("s_waitcnt lgkmcnt(" #n ")" ::: "memory")
; #define PG8_BAR __builtin_amdgcn_s_barrier()
; #define PG8_SCHED __builtin_amdgcn_sched_barrier(0)
;     ...
;             const bool last = (t == nt - 2);
;             const char* a1 = PG8_KADV(cA, (size_t)(t + 1) * kstep);
;             const char* a2 = last ? nA : PG8_KADV(cA, (size_t)(t + 2) * kstep); const char* b2 = last ? nB : PG8_KADV(cB, (size_t)(t + 2) * kstep);
;             const char* a3 = PG8_KADV(a2, kstep); const char* b3 = PG8_KADV(b2, kstep);
;             if (last && has_next) S.a_ready(nxt);
;             if constexpr (SP2) {
;             PG8_LDB(B0, 0, 0); PG8_LDB(B1, 0, 1); PG8_SCHED; PG8_LDA(At, 0, 0); PG8_STAGE(PG8_SA(1, 1), a1 + hstep, voffA);
;             PG8_WAIT_V(8); PG8_WAIT_L(0); PG8_BAR; PG8_MMA(0, 0, At, B0); PG8_MMA(0, 1, At, B1); PG8_BAR; PG8_SCHED;
;             PG8_LDA(At, 0, 1); PG8_STAGE(PG8_SB(0, 0), b2, voffB); PG8_STAGE(PG8_SB(0, 1), b2 + hstep, voffB); PG8_STAGE(PG8_SA(0, 0), a2, voffA);
.LBB0_541:
	s_add_u32 s3, s88, 0xfff80080
	s_addc_u32 s12, s89, -1
	s_add_i32 s13, 0, 0x10000
	s_cmp_eq_u32 s2, 28
	s_cselect_b32 s93, s15, s12
	s_cselect_b32 s92, s30, s3
	v_add_u32_e32 v140, s13, v142
	s_cselect_b32 s91, s33, s43
	s_cselect_b32 s90, s40, s42
	s_add_i32 s3, 0, 0x14000
	ds_read_b128 v[146:149], v140
	ds_read_b128 v[150:153], v140 offset:1024
	ds_read_b128 v[154:157], v140 offset:2048
	ds_read_b128 v[158:161], v140 offset:3072
	v_add_u32_e32 v140, s3, v142
	ds_read_b128 v[162:165], v140
	ds_read_b128 v[170:173], v140 offset:1024
	ds_read_b128 v[178:181], v140 offset:2048
	ds_read_b128 v[182:185], v140 offset:3072
	s_add_i32 m0, s21, 0xc000
	ds_read_b128 v[186:189], v145
	ds_read_b128 v[190:193], v145 offset:1024
	ds_read_b128 v[194:197], v145 offset:2048
	ds_read_b128 v[198:201], v145 offset:3072
	ds_read_b128 v[202:205], v145 offset:4096
	ds_read_b128 v[206:209], v145 offset:5120
	ds_read_b128 v[210:213], v145 offset:6144
	ds_read_b128 v[214:217], v145 offset:7168
	global_load_lds_dwordx4 v136, s[88:89]
	s_add_i32 m0, s21, 0xe000
	s_nop 0
	global_load_lds_dwordx4 v138, s[88:89]
	s_waitcnt vmcnt(8)
	s_waitcnt lgkmcnt(0)
	s_barrier
	s_setprio 1
	v_mfma_f32_16x16x32_bf16 v[124:127], v[146:149], v[186:189], v[124:127]
	v_mfma_f32_16x16x32_bf16 v[124:127], v[150:153], v[190:193], v[124:127]
	v_mfma_f32_16x16x32_bf16 v[116:119], v[146:149], v[194:197], v[116:119]
	v_mfma_f32_16x16x32_bf16 v[116:119], v[150:153], v[198:201], v[116:119]
	v_mfma_f32_16x16x32_bf16 v[100:103], v[146:149], v[202:205], v[100:103]
	v_mfma_f32_16x16x32_bf16 v[100:103], v[150:153], v[206:209], v[100:103]
	v_mfma_f32_16x16x32_bf16 v[84:87], v[146:149], v[210:213], v[84:87]
	v_mfma_f32_16x16x32_bf16 v[84:87], v[150:153], v[214:217], v[84:87]
	v_mfma_f32_16x16x32_bf16 v[120:123], v[154:157], v[186:189], v[120:123]
	v_mfma_f32_16x16x32_bf16 v[120:123], v[158:161], v[190:193], v[120:123]
	v_mfma_f32_16x16x32_bf16 v[112:115], v[154:157], v[194:197], v[112:115]
	v_mfma_f32_16x16x32_bf16 v[112:115], v[158:161], v[198:201], v[112:115]
	v_mfma_f32_16x16x32_bf16 v[96:99], v[154:157], v[202:205], v[96:99]
	v_mfma_f32_16x16x32_bf16 v[96:99], v[158:161], v[206:209], v[96:99]
	v_mfma_f32_16x16x32_bf16 v[80:83], v[154:157], v[210:213], v[80:83]
	v_mfma_f32_16x16x32_bf16 v[80:83], v[158:161], v[214:217], v[80:83]
	s_setprio 0
	s_setprio 1
	v_mfma_f32_16x16x32_bf16 v[108:111], v[162:165], v[186:189], v[108:111]
	v_mfma_f32_16x16x32_bf16 v[108:111], v[170:173], v[190:193], v[108:111]
	v_mfma_f32_16x16x32_bf16 v[92:95], v[162:165], v[194:197], v[92:95]
	v_mfma_f32_16x16x32_bf16 v[92:95], v[170:173], v[198:201], v[92:95]
	v_mfma_f32_16x16x32_bf16 v[76:79], v[162:165], v[202:205], v[76:79]
	v_mfma_f32_16x16x32_bf16 v[76:79], v[170:173], v[206:209], v[76:79]
	v_mfma_f32_16x16x32_bf16 v[68:71], v[162:165], v[210:213], v[68:71]
	v_mfma_f32_16x16x32_bf16 v[68:71], v[170:173], v[214:217], v[68:71]
	v_mfma_f32_16x16x32_bf16 v[104:107], v[178:181], v[186:189], v[104:107]
	v_mfma_f32_16x16x32_bf16 v[104:107], v[182:185], v[190:193], v[104:107]
	v_mfma_f32_16x16x32_bf16 v[88:91], v[178:181], v[194:197], v[88:91]
	v_mfma_f32_16x16x32_bf16 v[88:91], v[182:185], v[198:201], v[88:91]
	v_mfma_f32_16x16x32_bf16 v[72:75], v[178:181], v[202:205], v[72:75]
	v_mfma_f32_16x16x32_bf16 v[72:75], v[182:185], v[206:209], v[72:75]
	v_mfma_f32_16x16x32_bf16 v[64:67], v[178:181], v[210:213], v[64:67]
	v_mfma_f32_16x16x32_bf16 v[64:67], v[182:185], v[214:217], v[64:67]
	s_barrier
	s_setprio 0
	s_add_i32 s12, s13, s20
	s_mov_b32 m0, s12
	ds_read_b128 v[186:189], v145 offset:16384
	ds_read_b128 v[190:193], v145 offset:17408
	ds_read_b128 v[194:197], v145 offset:18432
	ds_read_b128 v[198:201], v145 offset:19456
	ds_read_b128 v[202:205], v145 offset:20480
	ds_read_b128 v[206:209], v145 offset:21504
	ds_read_b128 v[210:213], v145 offset:22528
	ds_read_b128 v[214:217], v145 offset:23552
	global_load_lds_dwordx4 v132, s[90:91]
	s_add_i32 m0, s12, 0x2000
	s_add_u32 vcc_lo, s90, 0x80000
	v_lshl_add_u64 v[218:219], s[90:91], 0, v[128:129]
	s_addc_u32 vcc_hi, s91, 0
	s_add_i32 s3, s3, s20
	global_load_lds_dwordx4 v128, s[90:91]
	s_mov_b32 m0, s3
	v_lshl_add_u64 v[222:223], s[92:93], 0, v[130:131]
	global_load_lds_dwordx4 v132, vcc
	s_add_i32 m0, s3, 0x2000
	s_nop 0
	global_load_lds_dwordx4 v128, vcc
	v_lshl_add_u64 v[220:221], s[92:93], 0, v[134:135]
	s_mov_b32 m0, s21
	s_nop 0
	global_load_lds_dwordx4 v134, s[92:93]
	s_mov_b32 m0, s22
	s_nop 0
	global_load_lds_dwordx4 v130, s[92:93]
	s_waitcnt vmcnt(8)
	s_waitcnt lgkmcnt(0)
	s_barrier
; #define PG8_STAGE(bufoff, gbase, voff) do { _Pragma("unroll") for (int _i = 0; _i < 2; ++_i) \
;         __builtin_amdgcn_global_load_lds((const unsigned*)((const char*)(gbase) + (voff)[_i]), (PG8_LAS unsigned*)(lds + (bufoff) + ldsw + _i * 8192), 16, 0, 0); } while (0)
; #define PG8_LDA(dst, b, h) do { _Pragma("unroll") for (int m = 0; m < 4; ++m) _Pragma("unroll") for (int k = 0; k < 2; ++k) dst[m][k] = *(const PG8_LAS bf16x8*)(lds + PG8_SA(b, h) + aoff + m * 2048 + k * 1024); } while (0)
; #define PG8_LDB(dst, b, h) do { _Pragma("unroll") for (int n = 0; n < 2; ++n) _Pragma("unroll") for (int k = 0; k < 2; ++k) dst[n][k] = *(const PG8_LAS bf16x8*)(lds + PG8_SB(b, h) + boff + n * 2048 + k * 1024); } while (0)
; #define PG8_MMA(ai, bj, At, Bt) do { __builtin_amdgcn_s_setprio(1); _Pragma("unroll") for (int m = 0; m < 4; ++m) _Pragma("unroll") for (int n = 0; n < 2; ++n) _Pragma("unroll") for (int k = 0; k < 2; ++k) \
;         acc[ai][bj][m][n] = __builtin_amdgcn_mfma_f32_16x16x32_bf16(Bt[n][k], At[m][k], acc[ai][bj][m][n], 0, 0, 0); __builtin_amdgcn_s_setprio(0); } while (0)
; #define PG8_WAIT_V(n) asm volatile("s_waitcnt vmcnt(" #n ")" ::: "memory")
; #define PG8_WAIT_L(n) asm volatile("s_waitcnt lgkmcnt(" #n ")" ::: "memory")
; #define PG8_BAR __builtin_amdgcn_s_barrier()
; #define PG8_SCHED __builtin_amdgcn_sched_barrier(0)
;     ...
;             PG8_WAIT_V(8); PG8_WAIT_L(0); PG8_BAR; PG8_MMA(0, 0, At, B0); PG8_MMA(0, 1, At, B1); PG8_BAR; PG8_SCHED;
;             PG8_LDA(At, 0, 1); PG8_STAGE(PG8_SB(0, 0), b2, voffB); PG8_STAGE(PG8_SB(0, 1), b2 + hstep, voffB); PG8_STAGE(PG8_SA(0, 0), a2, voffA);
;             PG8_WAIT_V(8); PG8_WAIT_L(0); PG8_BAR; PG8_MMA(1, 0, At, B0); PG8_MMA(1, 1, At, B1); PG8_BAR; PG8_SCHED;
;             PG8_LDB(B0, 1, 0); PG8_LDB(B1, 1, 1); PG8_SCHED; PG8_LDA(At, 1, 0); PG8_STAGE(PG8_SA(0, 1), a2 + hstep, voffA);
;             PG8_WAIT_V(8); PG8_WAIT_L(0); PG8_BAR; PG8_MMA(0, 0, At, B0); PG8_MMA(0, 1, At, B1); PG8_BAR; PG8_SCHED;
	s_setprio 1
	v_mfma_f32_16x16x32_bf16 v[60:63], v[146:149], v[186:189], v[60:63]
	v_mfma_f32_16x16x32_bf16 v[60:63], v[150:153], v[190:193], v[60:63]
	v_mfma_f32_16x16x32_bf16 v[52:55], v[146:149], v[194:197], v[52:55]
	v_mfma_f32_16x16x32_bf16 v[52:55], v[150:153], v[198:201], v[52:55]
	v_mfma_f32_16x16x32_bf16 v[36:39], v[146:149], v[202:205], v[36:39]
	v_mfma_f32_16x16x32_bf16 v[36:39], v[150:153], v[206:209], v[36:39]
	v_mfma_f32_16x16x32_bf16 v[20:23], v[146:149], v[210:213], v[20:23]
	v_mfma_f32_16x16x32_bf16 v[20:23], v[150:153], v[214:217], v[20:23]
	v_mfma_f32_16x16x32_bf16 v[56:59], v[154:157], v[186:189], v[56:59]
	v_mfma_f32_16x16x32_bf16 v[56:59], v[158:161], v[190:193], v[56:59]
	v_mfma_f32_16x16x32_bf16 v[48:51], v[154:157], v[194:197], v[48:51]
	v_mfma_f32_16x16x32_bf16 v[48:51], v[158:161], v[198:201], v[48:51]
	v_mfma_f32_16x16x32_bf16 v[32:35], v[154:157], v[202:205], v[32:35]
	v_mfma_f32_16x16x32_bf16 v[32:35], v[158:161], v[206:209], v[32:35]
	v_mfma_f32_16x16x32_bf16 v[16:19], v[154:157], v[210:213], v[16:19]
	v_mfma_f32_16x16x32_bf16 v[16:19], v[158:161], v[214:217], v[16:19]
	s_setprio 0
	s_setprio 1
	v_mfma_f32_16x16x32_bf16 v[44:47], v[162:165], v[186:189], v[44:47]
	v_mfma_f32_16x16x32_bf16 v[44:47], v[170:173], v[190:193], v[44:47]
	v_mfma_f32_16x16x32_bf16 v[28:31], v[162:165], v[194:197], v[28:31]
	v_mfma_f32_16x16x32_bf16 v[28:31], v[170:173], v[198:201], v[28:31]
	v_mfma_f32_16x16x32_bf16 v[12:15], v[162:165], v[202:205], v[12:15]
	v_mfma_f32_16x16x32_bf16 v[12:15], v[170:173], v[206:209], v[12:15]
	v_mfma_f32_16x16x32_bf16 v[4:7], v[162:165], v[210:213], v[4:7]
	v_mfma_f32_16x16x32_bf16 v[4:7], v[170:173], v[214:217], v[4:7]
	v_mfma_f32_16x16x32_bf16 v[40:43], v[178:181], v[186:189], v[40:43]
	v_mfma_f32_16x16x32_bf16 v[40:43], v[182:185], v[190:193], v[40:43]
	v_mfma_f32_16x16x32_bf16 v[24:27], v[178:181], v[194:197], v[24:27]
	v_mfma_f32_16x16x32_bf16 v[24:27], v[182:185], v[198:201], v[24:27]
	v_mfma_f32_16x16x32_bf16 v[8:11], v[178:181], v[202:205], v[8:11]
	v_mfma_f32_16x16x32_bf16 v[8:11], v[182:185], v[206:209], v[8:11]
	v_mfma_f32_16x16x32_bf16 v[0:3], v[178:181], v[210:213], v[0:3]
	v_mfma_f32_16x16x32_bf16 v[0:3], v[182:185], v[214:217], v[0:3]
	s_barrier
	s_setprio 0
	s_add_i32 s3, 0, 0x18000
	v_add_u32_e32 v140, s3, v142
	s_add_i32 s12, 0, 0x1c000
	ds_read_b128 v[146:149], v140
	ds_read_b128 v[150:153], v140 offset:1024
	ds_read_b128 v[154:157], v140 offset:2048
	ds_read_b128 v[158:161], v140 offset:3072
	v_add_u32_e32 v140, s12, v142
	ds_read_b128 v[162:165], v140
	ds_read_b128 v[170:173], v140 offset:1024
	ds_read_b128 v[178:181], v140 offset:2048
	ds_read_b128 v[182:185], v140 offset:3072
	s_add_u32 s92, s92, 0x80000
	s_addc_u32 s93, s93, 0
	s_mov_b32 m0, s23
	ds_read_b128 v[186:189], v145 offset:32768
	ds_read_b128 v[190:193], v145 offset:33792
	ds_read_b128 v[194:197], v145 offset:34816
	ds_read_b128 v[198:201], v145 offset:35840
	ds_read_b128 v[202:205], v145 offset:36864
	ds_read_b128 v[206:209], v145 offset:37888
	ds_read_b128 v[210:213], v145 offset:38912
	ds_read_b128 v[214:217], v145 offset:39936
	global_load_lds_dwordx4 v134, s[92:93]
	s_mov_b32 m0, s57
	s_nop 0
	global_load_lds_dwordx4 v130, s[92:93]
	s_waitcnt vmcnt(8)
	s_waitcnt lgkmcnt(0)
	s_barrier
	s_setprio 1
	v_mfma_f32_16x16x32_bf16 v[124:127], v[146:149], v[186:189], v[124:127]
	v_mfma_f32_16x16x32_bf16 v[124:127], v[150:153], v[190:193], v[124:127]
	v_mfma_f32_16x16x32_bf16 v[116:119], v[146:149], v[194:197], v[116:119]
	v_mfma_f32_16x16x32_bf16 v[116:119], v[150:153], v[198:201], v[116:119]
	v_mfma_f32_16x16x32_bf16 v[100:103], v[146:149], v[202:205], v[100:103]
	v_mfma_f32_16x16x32_bf16 v[100:103], v[150:153], v[206:209], v[100:103]
	v_mfma_f32_16x16x32_bf16 v[84:87], v[146:149], v[210:213], v[84:87]
	v_mfma_f32_16x16x32_bf16 v[84:87], v[150:153], v[214:217], v[84:87]
	v_mfma_f32_16x16x32_bf16 v[120:123], v[154:157], v[186:189], v[120:123]
	v_mfma_f32_16x16x32_bf16 v[120:123], v[158:161], v[190:193], v[120:123]
	v_mfma_f32_16x16x32_bf16 v[112:115], v[154:157], v[194:197], v[112:115]
	v_mfma_f32_16x16x32_bf16 v[112:115], v[158:161], v[198:201], v[112:115]
	v_mfma_f32_16x16x32_bf16 v[96:99], v[154:157], v[202:205], v[96:99]
	v_mfma_f32_16x16x32_bf16 v[96:99], v[158:161], v[206:209], v[96:99]
	v_mfma_f32_16x16x32_bf16 v[80:83], v[154:157], v[210:213], v[80:83]
	v_mfma_f32_16x16x32_bf16 v[80:83], v[158:161], v[214:217], v[80:83]
	s_setprio 0
	s_setprio 1
	v_mfma_f32_16x16x32_bf16 v[108:111], v[162:165], v[186:189], v[108:111]
	v_mfma_f32_16x16x32_bf16 v[108:111], v[170:173], v[190:193], v[108:111]
	v_mfma_f32_16x16x32_bf16 v[92:95], v[162:165], v[194:197], v[92:95]
	v_mfma_f32_16x16x32_bf16 v[92:95], v[170:173], v[198:201], v[92:95]
	v_mfma_f32_16x16x32_bf16 v[76:79], v[162:165], v[202:205], v[76:79]
	v_mfma_f32_16x16x32_bf16 v[76:79], v[170:173], v[206:209], v[76:79]
	v_mfma_f32_16x16x32_bf16 v[68:71], v[162:165], v[210:213], v[68:71]
	v_mfma_f32_16x16x32_bf16 v[68:71], v[170:173], v[214:217], v[68:71]
	v_mfma_f32_16x16x32_bf16 v[104:107], v[178:181], v[186:189], v[104:107]
	v_mfma_f32_16x16x32_bf16 v[104:107], v[182:185], v[190:193], v[104:107]
	v_mfma_f32_16x16x32_bf16 v[88:91], v[178:181], v[194:197], v[88:91]
	v_mfma_f32_16x16x32_bf16 v[88:91], v[182:185], v[198:201], v[88:91]
	v_mfma_f32_16x16x32_bf16 v[72:75], v[178:181], v[202:205], v[72:75]
	v_mfma_f32_16x16x32_bf16 v[72:75], v[182:185], v[206:209], v[72:75]
	v_mfma_f32_16x16x32_bf16 v[64:67], v[178:181], v[210:213], v[64:67]
	v_mfma_f32_16x16x32_bf16 v[64:67], v[182:185], v[214:217], v[64:67]
	s_barrier
; #define PG8_STAGE(bufoff, gbase, voff) do { _Pragma("unroll") for (int _i = 0; _i < 2; ++_i) \
;         __builtin_amdgcn_global_load_lds((const unsigned*)((const char*)(gbase) + (voff)[_i]), (PG8_LAS unsigned*)(lds + (bufoff) + ldsw + _i * 8192), 16, 0, 0); } while (0)
; #define PG8_LDA(dst, b, h) do { _Pragma("unroll") for (int m = 0; m < 4; ++m) _Pragma("unroll") for (int k = 0; k < 2; ++k) dst[m][k] = *(const PG8_LAS bf16x8*)(lds + PG8_SA(b, h) + aoff + m * 2048 + k * 1024); } while (0)
; #define PG8_MMA(ai, bj, At, Bt) do { __builtin_amdgcn_s_setprio(1); _Pragma("unroll") for (int m = 0; m < 4; ++m) _Pragma("unroll") for (int n = 0; n < 2; ++n) _Pragma("unroll") for (int k = 0; k < 2; ++k) \
;         acc[ai][bj][m][n] = __builtin_amdgcn_mfma_f32_16x16x32_bf16(Bt[n][k], At[m][k], acc[ai][bj][m][n], 0, 0, 0); __builtin_amdgcn_s_setprio(0); } while (0)
; #define PG8_WAIT_V(n) asm volatile("s_waitcnt vmcnt(" #n ")" ::: "memory")
; #define PG8_WAIT_L(n) asm volatile("s_waitcnt lgkmcnt(" #n ")" ::: "memory")
; #define PG8_BAR __builtin_amdgcn_s_barrier()
; #define PG8_SCHED __builtin_amdgcn_sched_barrier(0)
;     ...
;         for (int t = 0; t < nt; t += 2) {
;     ...
;             PG8_LDA(At, 1, 1); PG8_STAGE(PG8_SB(1, 0), b3, voffB); PG8_STAGE(PG8_SB(1, 1), b3 + hstep, voffB); PG8_STAGE(PG8_SA(1, 0), a3, voffA);
;             PG8_WAIT_V(8); PG8_WAIT_L(0); PG8_BAR; PG8_MMA(1, 0, At, B0); PG8_MMA(1, 1, At, B1); PG8_BAR; PG8_SCHED;
	s_setprio 0
	s_add_i32 s3, s3, s20
	s_mov_b32 m0, s3
	ds_read_b128 v[186:189], v145 offset:49152
	ds_read_b128 v[190:193], v145 offset:50176
	ds_read_b128 v[194:197], v145 offset:51200
	ds_read_b128 v[198:201], v145 offset:52224
	ds_read_b128 v[202:205], v145 offset:53248
	ds_read_b128 v[206:209], v145 offset:54272
	ds_read_b128 v[210:213], v145 offset:55296
	ds_read_b128 v[214:217], v145 offset:56320
	s_add_u32 s100, s90, s16
	s_addc_u32 s101, s91, s17
	global_load_lds_dwordx4 v132, s[100:101]
	s_add_i32 m0, s3, 0x2000
	s_add_u32 s90, s90, 0x80080
	v_lshl_add_u64 v[166:167], v[218:219], 0, s[16:17]
	s_addc_u32 s91, s91, 0
	s_add_i32 s3, s12, s20
	global_load_lds_dwordx4 v[166:167], off
	s_mov_b32 m0, s3
	s_nop 0
	global_load_lds_dwordx4 v132, s[90:91]
	s_add_i32 m0, s3, 0x2000
	s_nop 0
	global_load_lds_dwordx4 v128, s[90:91]
	v_lshl_add_u64 v[166:167], v[220:221], 0, s[16:17]
	s_mov_b32 m0, s59
	s_nop 0
	global_load_lds_dwordx4 v[166:167], off
	v_lshl_add_u64 v[166:167], v[222:223], 0, s[16:17]
	s_mov_b32 m0, s8
	s_nop 0
	global_load_lds_dwordx4 v[166:167], off
	s_waitcnt vmcnt(8)
	s_waitcnt lgkmcnt(0)
	s_barrier
	s_setprio 1
	v_mfma_f32_16x16x32_bf16 v[60:63], v[146:149], v[186:189], v[60:63]
	v_mfma_f32_16x16x32_bf16 v[60:63], v[150:153], v[190:193], v[60:63]
	v_mfma_f32_16x16x32_bf16 v[52:55], v[146:149], v[194:197], v[52:55]
	v_mfma_f32_16x16x32_bf16 v[52:55], v[150:153], v[198:201], v[52:55]
	v_mfma_f32_16x16x32_bf16 v[36:39], v[146:149], v[202:205], v[36:39]
	v_mfma_f32_16x16x32_bf16 v[36:39], v[150:153], v[206:209], v[36:39]
	v_mfma_f32_16x16x32_bf16 v[20:23], v[146:149], v[210:213], v[20:23]
	v_mfma_f32_16x16x32_bf16 v[20:23], v[150:153], v[214:217], v[20:23]
	v_mfma_f32_16x16x32_bf16 v[56:59], v[154:157], v[186:189], v[56:59]
	v_mfma_f32_16x16x32_bf16 v[56:59], v[158:161], v[190:193], v[56:59]
	v_mfma_f32_16x16x32_bf16 v[48:51], v[154:157], v[194:197], v[48:51]
	v_mfma_f32_16x16x32_bf16 v[48:51], v[158:161], v[198:201], v[48:51]
	v_mfma_f32_16x16x32_bf16 v[32:35], v[154:157], v[202:205], v[32:35]
	v_mfma_f32_16x16x32_bf16 v[32:35], v[158:161], v[206:209], v[32:35]
	v_mfma_f32_16x16x32_bf16 v[16:19], v[154:157], v[210:213], v[16:19]
	v_mfma_f32_16x16x32_bf16 v[16:19], v[158:161], v[214:217], v[16:19]
	s_setprio 0
	s_setprio 1
	v_mfma_f32_16x16x32_bf16 v[44:47], v[162:165], v[186:189], v[44:47]
	v_mfma_f32_16x16x32_bf16 v[44:47], v[170:173], v[190:193], v[44:47]
	v_mfma_f32_16x16x32_bf16 v[28:31], v[162:165], v[194:197], v[28:31]
	v_mfma_f32_16x16x32_bf16 v[28:31], v[170:173], v[198:201], v[28:31]
	v_mfma_f32_16x16x32_bf16 v[12:15], v[162:165], v[202:205], v[12:15]
	v_mfma_f32_16x16x32_bf16 v[12:15], v[170:173], v[206:209], v[12:15]
	v_mfma_f32_16x16x32_bf16 v[4:7], v[162:165], v[210:213], v[4:7]
	v_mfma_f32_16x16x32_bf16 v[4:7], v[170:173], v[214:217], v[4:7]
	v_mfma_f32_16x16x32_bf16 v[40:43], v[178:181], v[186:189], v[40:43]
	v_mfma_f32_16x16x32_bf16 v[40:43], v[182:185], v[190:193], v[40:43]
	v_mfma_f32_16x16x32_bf16 v[24:27], v[178:181], v[194:197], v[24:27]
	v_mfma_f32_16x16x32_bf16 v[24:27], v[182:185], v[198:201], v[24:27]
	v_mfma_f32_16x16x32_bf16 v[8:11], v[178:181], v[202:205], v[8:11]
	v_mfma_f32_16x16x32_bf16 v[8:11], v[182:185], v[206:209], v[8:11]
	v_mfma_f32_16x16x32_bf16 v[0:3], v[178:181], v[210:213], v[0:3]
	v_mfma_f32_16x16x32_bf16 v[0:3], v[182:185], v[214:217], v[0:3]
	s_barrier
	s_setprio 0
	s_add_i32 s2, s2, 2
	s_add_u32 s88, s88, 0x100
	s_addc_u32 s89, s89, 0
	s_add_u32 s42, s42, 0x100
	s_addc_u32 s43, s43, 0
	s_cmp_gt_u32 s2, 29
	s_cbranch_scc0 .LBB0_541
	s_and_b64 vcc, exec, s[76:77]
	s_cbranch_vccz .LBB0_544
	s_barrier

; #define PG8_STAGE(bufoff, gbase, voff) do { _Pragma("unroll") for (int _i = 0; _i < 2; ++_i) \
;         __builtin_amdgcn_global_load_lds((const unsigned*)((const char*)(gbase) + (voff)[_i]), (PG8_LAS unsigned*)(lds + (bufoff) + ldsw + _i * 8192), 16, 0, 0); } while (0)
; #define PG8_LDA(dst, b, h) do { _Pragma("unroll") for (int m = 0; m < 4; ++m) _Pragma("unroll") for (int k = 0; k < 2; ++k) dst[m][k] = *(const PG8_LAS bf16x8*)(lds + PG8_SA(b, h) + aoff + m * 2048 + k * 1024); } while (0)
; #define PG8_LDB(dst, b, h) do { _Pragma("unroll") for (int n = 0; n < 2; ++n) _Pragma("unroll") for (int k = 0; k < 2; ++k) dst[n][k] = *(const PG8_LAS bf16x8*)(lds + PG8_SB(b, h) + boff + n * 2048 + k * 1024); } while (0)
; #define PG8_MMA(ai, bj, At, Bt) do { __builtin_amdgcn_s_setprio(1); _Pragma("unroll") for (int m = 0; m < 4; ++m) _Pragma("unroll") for (int n = 0; n < 2; ++n) _Pragma("unroll") for (int k = 0; k < 2; ++k) \
;         acc[ai][bj][m][n] = __builtin_amdgcn_mfma_f32_16x16x32_bf16(Bt[n][k], At[m][k], acc[ai][bj][m][n], 0, 0, 0); __builtin_amdgcn_s_setprio(0); } while (0)
; #define PG8_WAIT_V(n) asm volatile("s_waitcnt vmcnt(" #n ")" ::: "memory")
; #define PG8_WAIT_L(n) asm volatile("s_waitcnt lgkmcnt(" #n ")" ::: "memory")
; #define PG8_BAR __builtin_amdgcn_s_barrier()
; #define PG8_SCHED __builtin_amdgcn_sched_barrier(0)
;     ...
;             const bool last = (t == nt - 2);
;             const char* a1 = PG8_KADV(cA, (size_t)(t + 1) * kstep);
;             const char* a2 = last ? nA : PG8_KADV(cA, (size_t)(t + 2) * kstep); const char* b2 = last ? nB : PG8_KADV(cB, (size_t)(t + 2) * kstep);
;             const char* a3 = PG8_KADV(a2, kstep); const char* b3 = PG8_KADV(b2, kstep);
;             if (last && has_next) S.a_ready(nxt);
;             if constexpr (SP2) {
;             PG8_LDB(B0, 0, 0); PG8_LDB(B1, 0, 1); PG8_SCHED; PG8_LDA(At, 0, 0); PG8_STAGE(PG8_SA(1, 1), a1 + hstep, voffA);
;             PG8_WAIT_V(8); PG8_WAIT_L(0); PG8_BAR; PG8_MMA(0, 0, At, B0); PG8_MMA(0, 1, At, B1); PG8_BAR; PG8_SCHED;
;             PG8_LDA(At, 0, 1); PG8_STAGE(PG8_SB(0, 0), b2, voffB); PG8_STAGE(PG8_SB(0, 1), b2 + hstep, voffB); PG8_STAGE(PG8_SA(0, 0), a2, voffA);
;             PG8_WAIT_V(8); PG8_WAIT_L(0); PG8_BAR; PG8_MMA(1, 0, At, B0); PG8_MMA(1, 1, At, B1); PG8_BAR; PG8_SCHED;
.LBB0_626:
	s_add_u32 s12, s86, 0xfffc0080
	s_addc_u32 s13, s87, -1
	s_add_i32 s96, 0, 0x10000
	s_cmp_eq_u32 s3, 12
	s_cselect_b32 s91, s75, s13
	s_cselect_b32 s90, s81, s12
	v_add_u32_e32 v143, s96, v140
	s_cselect_b32 s89, s79, s2
	s_cselect_b32 s88, vcc_lo, vcc_hi
	s_add_i32 s31, 0, 0x14000
	ds_read_b128 v[144:147], v143
	ds_read_b128 v[148:151], v143 offset:1024
	ds_read_b128 v[152:155], v143 offset:2048
	ds_read_b128 v[156:159], v143 offset:3072
	v_add_u32_e32 v143, s31, v140
	ds_read_b128 v[160:163], v143
	ds_read_b128 v[164:167], v143 offset:1024
	ds_read_b128 v[170:173], v143 offset:2048
	ds_read_b128 v[178:181], v143 offset:3072
	s_add_i32 m0, s97, 0xc000
	ds_read_b128 v[182:185], v142
	ds_read_b128 v[186:189], v142 offset:1024
	ds_read_b128 v[190:193], v142 offset:2048
	ds_read_b128 v[194:197], v142 offset:3072
	ds_read_b128 v[198:201], v142 offset:4096
	ds_read_b128 v[202:205], v142 offset:5120
	ds_read_b128 v[206:209], v142 offset:6144
	ds_read_b128 v[210:213], v142 offset:7168
	global_load_lds_dwordx4 v136, s[86:87]
	s_add_i32 m0, s97, 0xe000
	s_nop 0
	global_load_lds_dwordx4 v138, s[86:87]
	s_waitcnt vmcnt(8)
	s_waitcnt lgkmcnt(0)
	s_barrier
	s_setprio 1
	v_mfma_f32_16x16x32_bf16 v[124:127], v[144:147], v[182:185], v[124:127]
	v_mfma_f32_16x16x32_bf16 v[124:127], v[148:151], v[186:189], v[124:127]
	v_mfma_f32_16x16x32_bf16 v[116:119], v[144:147], v[190:193], v[116:119]
	v_mfma_f32_16x16x32_bf16 v[116:119], v[148:151], v[194:197], v[116:119]
	v_mfma_f32_16x16x32_bf16 v[100:103], v[144:147], v[198:201], v[100:103]
	v_mfma_f32_16x16x32_bf16 v[100:103], v[148:151], v[202:205], v[100:103]
	v_mfma_f32_16x16x32_bf16 v[84:87], v[144:147], v[206:209], v[84:87]
	v_mfma_f32_16x16x32_bf16 v[84:87], v[148:151], v[210:213], v[84:87]
	v_mfma_f32_16x16x32_bf16 v[120:123], v[152:155], v[182:185], v[120:123]
	v_mfma_f32_16x16x32_bf16 v[120:123], v[156:159], v[186:189], v[120:123]
	v_mfma_f32_16x16x32_bf16 v[112:115], v[152:155], v[190:193], v[112:115]
	v_mfma_f32_16x16x32_bf16 v[112:115], v[156:159], v[194:197], v[112:115]
	v_mfma_f32_16x16x32_bf16 v[96:99], v[152:155], v[198:201], v[96:99]
	v_mfma_f32_16x16x32_bf16 v[96:99], v[156:159], v[202:205], v[96:99]
	v_mfma_f32_16x16x32_bf16 v[80:83], v[152:155], v[206:209], v[80:83]
	v_mfma_f32_16x16x32_bf16 v[80:83], v[156:159], v[210:213], v[80:83]
	s_setprio 0
	s_setprio 1
	v_mfma_f32_16x16x32_bf16 v[108:111], v[160:163], v[182:185], v[108:111]
	v_mfma_f32_16x16x32_bf16 v[108:111], v[164:167], v[186:189], v[108:111]
	v_mfma_f32_16x16x32_bf16 v[92:95], v[160:163], v[190:193], v[92:95]
	v_mfma_f32_16x16x32_bf16 v[92:95], v[164:167], v[194:197], v[92:95]
	v_mfma_f32_16x16x32_bf16 v[76:79], v[160:163], v[198:201], v[76:79]
	v_mfma_f32_16x16x32_bf16 v[76:79], v[164:167], v[202:205], v[76:79]
	v_mfma_f32_16x16x32_bf16 v[68:71], v[160:163], v[206:209], v[68:71]
	v_mfma_f32_16x16x32_bf16 v[68:71], v[164:167], v[210:213], v[68:71]
	v_mfma_f32_16x16x32_bf16 v[104:107], v[170:173], v[182:185], v[104:107]
	v_mfma_f32_16x16x32_bf16 v[104:107], v[178:181], v[186:189], v[104:107]
	v_mfma_f32_16x16x32_bf16 v[88:91], v[170:173], v[190:193], v[88:91]
	v_mfma_f32_16x16x32_bf16 v[88:91], v[178:181], v[194:197], v[88:91]
	v_mfma_f32_16x16x32_bf16 v[72:75], v[170:173], v[198:201], v[72:75]
	v_mfma_f32_16x16x32_bf16 v[72:75], v[178:181], v[202:205], v[72:75]
	v_mfma_f32_16x16x32_bf16 v[64:67], v[170:173], v[206:209], v[64:67]
	v_mfma_f32_16x16x32_bf16 v[64:67], v[178:181], v[210:213], v[64:67]
	s_barrier
	s_setprio 0
	s_add_i32 s12, s96, s93
	s_mov_b32 m0, s12
	ds_read_b128 v[182:185], v142 offset:16384
	ds_read_b128 v[186:189], v142 offset:17408
	ds_read_b128 v[190:193], v142 offset:18432
	ds_read_b128 v[194:197], v142 offset:19456
	ds_read_b128 v[198:201], v142 offset:20480
	ds_read_b128 v[202:205], v142 offset:21504
	ds_read_b128 v[206:209], v142 offset:22528
	ds_read_b128 v[210:213], v142 offset:23552
	global_load_lds_dwordx4 v130, s[88:89]
	s_add_i32 m0, s12, 0x2000
	s_add_u32 s12, s88, 0x40000
	s_addc_u32 s13, s89, 0
	s_add_i32 s31, s31, s93
	global_load_lds_dwordx4 v134, s[88:89]
	s_mov_b32 m0, s31
	s_nop 0
	global_load_lds_dwordx4 v130, s[12:13]
	s_add_i32 m0, s31, 0x2000
	s_nop 0
	global_load_lds_dwordx4 v134, s[12:13]
	s_mov_b32 m0, s97
	s_nop 0
	global_load_lds_dwordx4 v128, s[90:91]
	s_mov_b32 m0, s40
	s_nop 0
	global_load_lds_dwordx4 v132, s[90:91]
	s_waitcnt vmcnt(8)
	s_waitcnt lgkmcnt(0)
	s_barrier
	s_setprio 1
	v_mfma_f32_16x16x32_bf16 v[60:63], v[144:147], v[182:185], v[60:63]
	v_mfma_f32_16x16x32_bf16 v[60:63], v[148:151], v[186:189], v[60:63]
	v_mfma_f32_16x16x32_bf16 v[52:55], v[144:147], v[190:193], v[52:55]
	v_mfma_f32_16x16x32_bf16 v[52:55], v[148:151], v[194:197], v[52:55]
	v_mfma_f32_16x16x32_bf16 v[36:39], v[144:147], v[198:201], v[36:39]
	v_mfma_f32_16x16x32_bf16 v[36:39], v[148:151], v[202:205], v[36:39]
	v_mfma_f32_16x16x32_bf16 v[20:23], v[144:147], v[206:209], v[20:23]
	v_mfma_f32_16x16x32_bf16 v[20:23], v[148:151], v[210:213], v[20:23]
	v_mfma_f32_16x16x32_bf16 v[56:59], v[152:155], v[182:185], v[56:59]
	v_mfma_f32_16x16x32_bf16 v[56:59], v[156:159], v[186:189], v[56:59]
	v_mfma_f32_16x16x32_bf16 v[48:51], v[152:155], v[190:193], v[48:51]
	v_mfma_f32_16x16x32_bf16 v[48:51], v[156:159], v[194:197], v[48:51]
	v_mfma_f32_16x16x32_bf16 v[32:35], v[152:155], v[198:201], v[32:35]
	v_mfma_f32_16x16x32_bf16 v[32:35], v[156:159], v[202:205], v[32:35]
	v_mfma_f32_16x16x32_bf16 v[16:19], v[152:155], v[206:209], v[16:19]
	v_mfma_f32_16x16x32_bf16 v[16:19], v[156:159], v[210:213], v[16:19]
	s_setprio 0
	s_setprio 1
	v_mfma_f32_16x16x32_bf16 v[44:47], v[160:163], v[182:185], v[44:47]
	v_mfma_f32_16x16x32_bf16 v[44:47], v[164:167], v[186:189], v[44:47]
	v_mfma_f32_16x16x32_bf16 v[28:31], v[160:163], v[190:193], v[28:31]
	v_mfma_f32_16x16x32_bf16 v[28:31], v[164:167], v[194:197], v[28:31]
	v_mfma_f32_16x16x32_bf16 v[12:15], v[160:163], v[198:201], v[12:15]
	v_mfma_f32_16x16x32_bf16 v[12:15], v[164:167], v[202:205], v[12:15]
	v_mfma_f32_16x16x32_bf16 v[4:7], v[160:163], v[206:209], v[4:7]
	v_mfma_f32_16x16x32_bf16 v[4:7], v[164:167], v[210:213], v[4:7]
	v_mfma_f32_16x16x32_bf16 v[40:43], v[170:173], v[182:185], v[40:43]
	v_mfma_f32_16x16x32_bf16 v[40:43], v[178:181], v[186:189], v[40:43]
	v_mfma_f32_16x16x32_bf16 v[24:27], v[170:173], v[190:193], v[24:27]
	v_mfma_f32_16x16x32_bf16 v[24:27], v[178:181], v[194:197], v[24:27]
	v_mfma_f32_16x16x32_bf16 v[8:11], v[170:173], v[198:201], v[8:11]
	v_mfma_f32_16x16x32_bf16 v[8:11], v[178:181], v[202:205], v[8:11]
	v_mfma_f32_16x16x32_bf16 v[0:3], v[170:173], v[206:209], v[0:3]
	v_mfma_f32_16x16x32_bf16 v[0:3], v[178:181], v[210:213], v[0:3]
	s_barrier
; #define PG8_STAGE(bufoff, gbase, voff) do { _Pragma("unroll") for (int _i = 0; _i < 2; ++_i) \
;         __builtin_amdgcn_global_load_lds((const unsigned*)((const char*)(gbase) + (voff)[_i]), (PG8_LAS unsigned*)(lds + (bufoff) + ldsw + _i * 8192), 16, 0, 0); } while (0)
; #define PG8_LDA(dst, b, h) do { _Pragma("unroll") for (int m = 0; m < 4; ++m) _Pragma("unroll") for (int k = 0; k < 2; ++k) dst[m][k] = *(const PG8_LAS bf16x8*)(lds + PG8_SA(b, h) + aoff + m * 2048 + k * 1024); } while (0)
; #define PG8_LDB(dst, b, h) do { _Pragma("unroll") for (int n = 0; n < 2; ++n) _Pragma("unroll") for (int k = 0; k < 2; ++k) dst[n][k] = *(const PG8_LAS bf16x8*)(lds + PG8_SB(b, h) + boff + n * 2048 + k * 1024); } while (0)
; #define PG8_MMA(ai, bj, At, Bt) do { __builtin_amdgcn_s_setprio(1); _Pragma("unroll") for (int m = 0; m < 4; ++m) _Pragma("unroll") for (int n = 0; n < 2; ++n) _Pragma("unroll") for (int k = 0; k < 2; ++k) \
;         acc[ai][bj][m][n] = __builtin_amdgcn_mfma_f32_16x16x32_bf16(Bt[n][k], At[m][k], acc[ai][bj][m][n], 0, 0, 0); __builtin_amdgcn_s_setprio(0); } while (0)
; #define PG8_WAIT_V(n) asm volatile("s_waitcnt vmcnt(" #n ")" ::: "memory")
; #define PG8_WAIT_L(n) asm volatile("s_waitcnt lgkmcnt(" #n ")" ::: "memory")
; #define PG8_BAR __builtin_amdgcn_s_barrier()
; #define PG8_SCHED __builtin_amdgcn_sched_barrier(0)
;     ...
;         for (int t = 0; t < nt; t += 2) {
;     ...
;             PG8_LDB(B0, 1, 0); PG8_LDB(B1, 1, 1); PG8_SCHED; PG8_LDA(At, 1, 0); PG8_STAGE(PG8_SA(0, 1), a2 + hstep, voffA);
;             PG8_WAIT_V(8); PG8_WAIT_L(0); PG8_BAR; PG8_MMA(0, 0, At, B0); PG8_MMA(0, 1, At, B1); PG8_BAR; PG8_SCHED;
;             PG8_LDA(At, 1, 1); PG8_STAGE(PG8_SB(1, 0), b3, voffB); PG8_STAGE(PG8_SB(1, 1), b3 + hstep, voffB); PG8_STAGE(PG8_SA(1, 0), a3, voffA);
;             PG8_WAIT_V(8); PG8_WAIT_L(0); PG8_BAR; PG8_MMA(1, 0, At, B0); PG8_MMA(1, 1, At, B1); PG8_BAR; PG8_SCHED;
	s_setprio 0
	s_add_i32 s31, 0, 0x18000
	v_add_u32_e32 v143, s31, v140
	s_add_i32 s96, 0, 0x1c000
	ds_read_b128 v[144:147], v143
	ds_read_b128 v[148:151], v143 offset:1024
	ds_read_b128 v[152:155], v143 offset:2048
	ds_read_b128 v[156:159], v143 offset:3072
	v_add_u32_e32 v143, s96, v140
	ds_read_b128 v[160:163], v143
	ds_read_b128 v[164:167], v143 offset:1024
	ds_read_b128 v[170:173], v143 offset:2048
	ds_read_b128 v[178:181], v143 offset:3072
	s_add_u32 s12, s90, 0x40000
	s_addc_u32 s13, s91, 0
	s_mov_b32 m0, s33
	ds_read_b128 v[182:185], v142 offset:32768
	ds_read_b128 v[186:189], v142 offset:33792
	ds_read_b128 v[190:193], v142 offset:34816
	ds_read_b128 v[194:197], v142 offset:35840
	ds_read_b128 v[198:201], v142 offset:36864
	ds_read_b128 v[202:205], v142 offset:37888
	ds_read_b128 v[206:209], v142 offset:38912
	ds_read_b128 v[210:213], v142 offset:39936
	global_load_lds_dwordx4 v128, s[12:13]
	s_mov_b32 m0, s30
	s_nop 0
	global_load_lds_dwordx4 v132, s[12:13]
	s_waitcnt vmcnt(8)
	s_waitcnt lgkmcnt(0)
	s_barrier
	s_setprio 1
	v_mfma_f32_16x16x32_bf16 v[124:127], v[144:147], v[182:185], v[124:127]
	v_mfma_f32_16x16x32_bf16 v[124:127], v[148:151], v[186:189], v[124:127]
	v_mfma_f32_16x16x32_bf16 v[116:119], v[144:147], v[190:193], v[116:119]
	v_mfma_f32_16x16x32_bf16 v[116:119], v[148:151], v[194:197], v[116:119]
	v_mfma_f32_16x16x32_bf16 v[100:103], v[144:147], v[198:201], v[100:103]
	v_mfma_f32_16x16x32_bf16 v[100:103], v[148:151], v[202:205], v[100:103]
	v_mfma_f32_16x16x32_bf16 v[84:87], v[144:147], v[206:209], v[84:87]
	v_mfma_f32_16x16x32_bf16 v[84:87], v[148:151], v[210:213], v[84:87]
	v_mfma_f32_16x16x32_bf16 v[120:123], v[152:155], v[182:185], v[120:123]
	v_mfma_f32_16x16x32_bf16 v[120:123], v[156:159], v[186:189], v[120:123]
	v_mfma_f32_16x16x32_bf16 v[112:115], v[152:155], v[190:193], v[112:115]
	v_mfma_f32_16x16x32_bf16 v[112:115], v[156:159], v[194:197], v[112:115]
	v_mfma_f32_16x16x32_bf16 v[96:99], v[152:155], v[198:201], v[96:99]
	v_mfma_f32_16x16x32_bf16 v[96:99], v[156:159], v[202:205], v[96:99]
	v_mfma_f32_16x16x32_bf16 v[80:83], v[152:155], v[206:209], v[80:83]
	v_mfma_f32_16x16x32_bf16 v[80:83], v[156:159], v[210:213], v[80:83]
	s_setprio 0
	s_setprio 1
	v_mfma_f32_16x16x32_bf16 v[108:111], v[160:163], v[182:185], v[108:111]
	v_mfma_f32_16x16x32_bf16 v[108:111], v[164:167], v[186:189], v[108:111]
	v_mfma_f32_16x16x32_bf16 v[92:95], v[160:163], v[190:193], v[92:95]
	v_mfma_f32_16x16x32_bf16 v[92:95], v[164:167], v[194:197], v[92:95]
	v_mfma_f32_16x16x32_bf16 v[76:79], v[160:163], v[198:201], v[76:79]
	v_mfma_f32_16x16x32_bf16 v[76:79], v[164:167], v[202:205], v[76:79]
	v_mfma_f32_16x16x32_bf16 v[68:71], v[160:163], v[206:209], v[68:71]
	v_mfma_f32_16x16x32_bf16 v[68:71], v[164:167], v[210:213], v[68:71]
	v_mfma_f32_16x16x32_bf16 v[104:107], v[170:173], v[182:185], v[104:107]
	v_mfma_f32_16x16x32_bf16 v[104:107], v[178:181], v[186:189], v[104:107]
	v_mfma_f32_16x16x32_bf16 v[88:91], v[170:173], v[190:193], v[88:91]
	v_mfma_f32_16x16x32_bf16 v[88:91], v[178:181], v[194:197], v[88:91]
	v_mfma_f32_16x16x32_bf16 v[72:75], v[170:173], v[198:201], v[72:75]
	v_mfma_f32_16x16x32_bf16 v[72:75], v[178:181], v[202:205], v[72:75]
	v_mfma_f32_16x16x32_bf16 v[64:67], v[170:173], v[206:209], v[64:67]
	v_mfma_f32_16x16x32_bf16 v[64:67], v[178:181], v[210:213], v[64:67]
	s_barrier
	s_setprio 0
	s_add_i32 s12, s31, s93
	s_mov_b32 m0, s12
	ds_read_b128 v[182:185], v142 offset:49152
	ds_read_b128 v[186:189], v142 offset:50176
	ds_read_b128 v[190:193], v142 offset:51200
	ds_read_b128 v[194:197], v142 offset:52224
	ds_read_b128 v[198:201], v142 offset:53248
	ds_read_b128 v[202:205], v142 offset:54272
	ds_read_b128 v[206:209], v142 offset:55296
	ds_read_b128 v[210:213], v142 offset:56320
	s_add_u32 s100, s88, s16
	s_addc_u32 s101, s89, s17
	global_load_lds_dwordx4 v130, s[100:101]
	s_add_i32 m0, s12, 0x2000
	s_add_u32 s12, s88, 0x40080
	s_addc_u32 s13, s89, 0
	s_add_i32 s31, s96, s93
	global_load_lds_dwordx4 v134, s[100:101]
	s_mov_b32 m0, s31
	s_nop 0
	global_load_lds_dwordx4 v130, s[12:13]
	s_add_i32 m0, s31, 0x2000
	s_nop 0
	global_load_lds_dwordx4 v134, s[12:13]
	s_mov_b32 m0, s14
	s_nop 0
	s_add_u32 s100, s90, s16
	s_addc_u32 s101, s91, s17
	global_load_lds_dwordx4 v128, s[100:101]
	s_mov_b32 m0, s15
	s_nop 0
	global_load_lds_dwordx4 v132, s[100:101]
	s_waitcnt vmcnt(8)
	s_waitcnt lgkmcnt(0)
	s_barrier
	s_setprio 1
	v_mfma_f32_16x16x32_bf16 v[60:63], v[144:147], v[182:185], v[60:63]
	v_mfma_f32_16x16x32_bf16 v[60:63], v[148:151], v[186:189], v[60:63]
	v_mfma_f32_16x16x32_bf16 v[52:55], v[144:147], v[190:193], v[52:55]
	v_mfma_f32_16x16x32_bf16 v[52:55], v[148:151], v[194:197], v[52:55]
	v_mfma_f32_16x16x32_bf16 v[36:39], v[144:147], v[198:201], v[36:39]
	v_mfma_f32_16x16x32_bf16 v[36:39], v[148:151], v[202:205], v[36:39]
	v_mfma_f32_16x16x32_bf16 v[20:23], v[144:147], v[206:209], v[20:23]
	v_mfma_f32_16x16x32_bf16 v[20:23], v[148:151], v[210:213], v[20:23]
	v_mfma_f32_16x16x32_bf16 v[56:59], v[152:155], v[182:185], v[56:59]
	v_mfma_f32_16x16x32_bf16 v[56:59], v[156:159], v[186:189], v[56:59]
	v_mfma_f32_16x16x32_bf16 v[48:51], v[152:155], v[190:193], v[48:51]
	v_mfma_f32_16x16x32_bf16 v[48:51], v[156:159], v[194:197], v[48:51]
	v_mfma_f32_16x16x32_bf16 v[32:35], v[152:155], v[198:201], v[32:35]
	v_mfma_f32_16x16x32_bf16 v[32:35], v[156:159], v[202:205], v[32:35]
	v_mfma_f32_16x16x32_bf16 v[16:19], v[152:155], v[206:209], v[16:19]
	v_mfma_f32_16x16x32_bf16 v[16:19], v[156:159], v[210:213], v[16:19]
	s_setprio 0
	s_setprio 1
	v_mfma_f32_16x16x32_bf16 v[44:47], v[160:163], v[182:185], v[44:47]
	v_mfma_f32_16x16x32_bf16 v[44:47], v[164:167], v[186:189], v[44:47]
	v_mfma_f32_16x16x32_bf16 v[28:31], v[160:163], v[190:193], v[28:31]
	v_mfma_f32_16x16x32_bf16 v[28:31], v[164:167], v[194:197], v[28:31]
	v_mfma_f32_16x16x32_bf16 v[12:15], v[160:163], v[198:201], v[12:15]
	v_mfma_f32_16x16x32_bf16 v[12:15], v[164:167], v[202:205], v[12:15]
	v_mfma_f32_16x16x32_bf16 v[4:7], v[160:163], v[206:209], v[4:7]
	v_mfma_f32_16x16x32_bf16 v[4:7], v[164:167], v[210:213], v[4:7]
	v_mfma_f32_16x16x32_bf16 v[40:43], v[170:173], v[182:185], v[40:43]
	v_mfma_f32_16x16x32_bf16 v[40:43], v[178:181], v[186:189], v[40:43]
	v_mfma_f32_16x16x32_bf16 v[24:27], v[170:173], v[190:193], v[24:27]
	v_mfma_f32_16x16x32_bf16 v[24:27], v[178:181], v[194:197], v[24:27]
	v_mfma_f32_16x16x32_bf16 v[8:11], v[170:173], v[198:201], v[8:11]
	v_mfma_f32_16x16x32_bf16 v[8:11], v[178:181], v[202:205], v[8:11]
	v_mfma_f32_16x16x32_bf16 v[0:3], v[170:173], v[206:209], v[0:3]
	v_mfma_f32_16x16x32_bf16 v[0:3], v[178:181], v[210:213], v[0:3]
	s_barrier
	s_setprio 0
	s_add_i32 s3, s3, 2
	s_add_u32 s86, s86, 0x100
	s_addc_u32 s87, s87, 0
	s_add_u32 vcc_hi, vcc_hi, 0x100
	s_addc_u32 s2, s2, 0
	s_cmp_gt_u32 s3, 13
	s_cbranch_scc0 .LBB0_626
	s_and_b64 vcc, exec, s[72:73]
	s_cbranch_vccz .LBB0_629
	s_barrier

; #define PG8_STAGE(bufoff, gbase, voff) do { _Pragma("unroll") for (int _i = 0; _i < 2; ++_i) \
;         __builtin_amdgcn_global_load_lds((const unsigned*)((const char*)(gbase) + (voff)[_i]), (PG8_LAS unsigned*)(lds + (bufoff) + ldsw + _i * 8192), 16, 0, 0); } while (0)
; #define PG8_LDA(dst, b, h) do { _Pragma("unroll") for (int m = 0; m < 4; ++m) _Pragma("unroll") for (int k = 0; k < 2; ++k) dst[m][k] = *(const PG8_LAS bf16x8*)(lds + PG8_SA(b, h) + aoff + m * 2048 + k * 1024); } while (0)
; #define PG8_LDB(dst, b, h) do { _Pragma("unroll") for (int n = 0; n < 2; ++n) _Pragma("unroll") for (int k = 0; k < 2; ++k) dst[n][k] = *(const PG8_LAS bf16x8*)(lds + PG8_SB(b, h) + boff + n * 2048 + k * 1024); } while (0)
; #define PG8_MMA(ai, bj, At, Bt) do { __builtin_amdgcn_s_setprio(1); _Pragma("unroll") for (int m = 0; m < 4; ++m) _Pragma("unroll") for (int n = 0; n < 2; ++n) _Pragma("unroll") for (int k = 0; k < 2; ++k) \
;         acc[ai][bj][m][n] = __builtin_amdgcn_mfma_f32_16x16x32_bf16(Bt[n][k], At[m][k], acc[ai][bj][m][n], 0, 0, 0); __builtin_amdgcn_s_setprio(0); } while (0)
; #define PG8_WAIT_V(n) asm volatile("s_waitcnt vmcnt(" #n ")" ::: "memory")
; #define PG8_WAIT_L(n) asm volatile("s_waitcnt lgkmcnt(" #n ")" ::: "memory")
; #define PG8_BAR __builtin_amdgcn_s_barrier()
; #define PG8_SCHED __builtin_amdgcn_sched_barrier(0)
;     ...
;             const bool last = (t == nt - 2);
;             const char* a1 = PG8_KADV(cA, (size_t)(t + 1) * kstep);
;             const char* a2 = last ? nA : PG8_KADV(cA, (size_t)(t + 2) * kstep); const char* b2 = last ? nB : PG8_KADV(cB, (size_t)(t + 2) * kstep);
;             const char* a3 = PG8_KADV(a2, kstep); const char* b3 = PG8_KADV(b2, kstep);
;             if (last && has_next) S.a_ready(nxt);
;             if constexpr (SP2) {
;             PG8_LDB(B0, 0, 0); PG8_LDB(B1, 0, 1); PG8_SCHED; PG8_LDA(At, 0, 0); PG8_STAGE(PG8_SA(1, 1), a1 + hstep, voffA);
;             PG8_WAIT_V(8); PG8_WAIT_L(0); PG8_BAR; PG8_MMA(0, 0, At, B0); PG8_MMA(0, 1, At, B1); PG8_BAR; PG8_SCHED;
;             PG8_LDA(At, 0, 1); PG8_STAGE(PG8_SB(0, 0), b2, voffB); PG8_STAGE(PG8_SB(0, 1), b2 + hstep, voffB); PG8_STAGE(PG8_SA(0, 0), a2, voffA);
;             PG8_WAIT_V(8); PG8_WAIT_L(0); PG8_BAR; PG8_MMA(1, 0, At, B0); PG8_MMA(1, 1, At, B1); PG8_BAR; PG8_SCHED;
.LBB0_856:
	s_add_u32 s12, s82, 0xfff80080
	s_addc_u32 s13, s83, -1
	s_add_i32 s31, 0, 0x10000
	s_cmp_eq_u32 s3, 28
	s_cselect_b32 s87, s15, s13
	s_cselect_b32 s86, s23, s12
	s_cselect_b32 s85, s25, s2
	s_cselect_b32 s84, s28, s30
	s_add_i32 s33, 0, 0x14000
	v_add_u32_e32 v140, s31, v166
	v_add_u32_e32 v164, s33, v166
	ds_read_b128 v[128:131], v140
	ds_read_b128 v[132:135], v140 offset:1024
	ds_read_b128 v[136:139], v140 offset:2048
	ds_read_b128 v[140:143], v140 offset:3072
	ds_read_b128 v[144:147], v164
	ds_read_b128 v[148:151], v164 offset:1024
	ds_read_b128 v[170:173], v164 offset:2048
	ds_read_b128 v[178:181], v164 offset:3072
	s_add_i32 m0, s9, 0xc000
	ds_read_b128 v[184:187], v183
	ds_read_b128 v[188:191], v183 offset:1024
	ds_read_b128 v[192:195], v183 offset:2048
	ds_read_b128 v[196:199], v183 offset:3072
	ds_read_b128 v[200:203], v183 offset:4096
	ds_read_b128 v[204:207], v183 offset:5120
	ds_read_b128 v[208:211], v183 offset:6144
	ds_read_b128 v[212:215], v183 offset:7168
	global_load_lds_dwordx4 v160, s[82:83]
	s_add_i32 m0, s9, 0xe000
	s_nop 0
	global_load_lds_dwordx4 v162, s[82:83]
	s_waitcnt vmcnt(8)
	s_waitcnt lgkmcnt(0)
	s_barrier
	s_setprio 1
	v_mfma_f32_16x16x32_bf16 v[124:127], v[128:131], v[184:187], v[124:127]
	v_mfma_f32_16x16x32_bf16 v[124:127], v[132:135], v[188:191], v[124:127]
	v_mfma_f32_16x16x32_bf16 v[112:115], v[128:131], v[192:195], v[112:115]
	v_mfma_f32_16x16x32_bf16 v[112:115], v[132:135], v[196:199], v[112:115]
	v_mfma_f32_16x16x32_bf16 v[92:95], v[128:131], v[200:203], v[92:95]
	v_mfma_f32_16x16x32_bf16 v[92:95], v[132:135], v[204:207], v[92:95]
	v_mfma_f32_16x16x32_bf16 v[80:83], v[128:131], v[208:211], v[80:83]
	v_mfma_f32_16x16x32_bf16 v[80:83], v[132:135], v[212:215], v[80:83]
	v_mfma_f32_16x16x32_bf16 v[120:123], v[136:139], v[184:187], v[120:123]
	v_mfma_f32_16x16x32_bf16 v[120:123], v[140:143], v[188:191], v[120:123]
	v_mfma_f32_16x16x32_bf16 v[104:107], v[136:139], v[192:195], v[104:107]
	v_mfma_f32_16x16x32_bf16 v[104:107], v[140:143], v[196:199], v[104:107]
	v_mfma_f32_16x16x32_bf16 v[88:91], v[136:139], v[200:203], v[88:91]
	v_mfma_f32_16x16x32_bf16 v[88:91], v[140:143], v[204:207], v[88:91]
	v_mfma_f32_16x16x32_bf16 v[72:75], v[136:139], v[208:211], v[72:75]
	v_mfma_f32_16x16x32_bf16 v[72:75], v[140:143], v[212:215], v[72:75]
	s_setprio 0
	s_setprio 1
	v_mfma_f32_16x16x32_bf16 v[116:119], v[144:147], v[184:187], v[116:119]
	v_mfma_f32_16x16x32_bf16 v[116:119], v[148:151], v[188:191], v[116:119]
	v_mfma_f32_16x16x32_bf16 v[100:103], v[144:147], v[192:195], v[100:103]
	v_mfma_f32_16x16x32_bf16 v[100:103], v[148:151], v[196:199], v[100:103]
	v_mfma_f32_16x16x32_bf16 v[84:87], v[144:147], v[200:203], v[84:87]
	v_mfma_f32_16x16x32_bf16 v[84:87], v[148:151], v[204:207], v[84:87]
	v_mfma_f32_16x16x32_bf16 v[68:71], v[144:147], v[208:211], v[68:71]
	v_mfma_f32_16x16x32_bf16 v[68:71], v[148:151], v[212:215], v[68:71]
	v_mfma_f32_16x16x32_bf16 v[108:111], v[170:173], v[184:187], v[108:111]
	v_mfma_f32_16x16x32_bf16 v[108:111], v[178:181], v[188:191], v[108:111]
	v_mfma_f32_16x16x32_bf16 v[96:99], v[170:173], v[192:195], v[96:99]
	v_mfma_f32_16x16x32_bf16 v[96:99], v[178:181], v[196:199], v[96:99]
	v_mfma_f32_16x16x32_bf16 v[76:79], v[170:173], v[200:203], v[76:79]
	v_mfma_f32_16x16x32_bf16 v[76:79], v[178:181], v[204:207], v[76:79]
	v_mfma_f32_16x16x32_bf16 v[64:67], v[170:173], v[208:211], v[64:67]
	v_mfma_f32_16x16x32_bf16 v[64:67], v[178:181], v[212:215], v[64:67]
	s_barrier
	s_setprio 0
	s_add_i32 s12, s31, s8
	s_mov_b32 m0, s12
	ds_read_b128 v[184:187], v183 offset:16384
	ds_read_b128 v[188:191], v183 offset:17408
	ds_read_b128 v[192:195], v183 offset:18432
	ds_read_b128 v[196:199], v183 offset:19456
	ds_read_b128 v[200:203], v183 offset:20480
	ds_read_b128 v[204:207], v183 offset:21504
	ds_read_b128 v[208:211], v183 offset:22528
	ds_read_b128 v[212:215], v183 offset:23552
	global_load_lds_dwordx4 v154, s[84:85]
	s_add_i32 m0, s12, 0x2000
	s_add_u32 s12, s84, 0x80000
	s_addc_u32 s13, s85, 0
	s_add_i32 s31, s33, s8
	global_load_lds_dwordx4 v158, s[84:85]
	s_mov_b32 m0, s31
	s_nop 0
	global_load_lds_dwordx4 v154, s[12:13]
	s_add_i32 m0, s31, 0x2000
	s_nop 0
	global_load_lds_dwordx4 v158, s[12:13]
	s_mov_b32 m0, s9
	s_nop 0
	global_load_lds_dwordx4 v152, s[86:87]
	s_mov_b32 m0, s10
	s_nop 0
	global_load_lds_dwordx4 v156, s[86:87]
	s_waitcnt vmcnt(8)
	s_waitcnt lgkmcnt(0)
	s_barrier
	s_setprio 1
	v_mfma_f32_16x16x32_bf16 v[60:63], v[128:131], v[184:187], v[60:63]
	v_mfma_f32_16x16x32_bf16 v[60:63], v[132:135], v[188:191], v[60:63]
	v_mfma_f32_16x16x32_bf16 v[48:51], v[128:131], v[192:195], v[48:51]
	v_mfma_f32_16x16x32_bf16 v[48:51], v[132:135], v[196:199], v[48:51]
	v_mfma_f32_16x16x32_bf16 v[28:31], v[128:131], v[200:203], v[28:31]
	v_mfma_f32_16x16x32_bf16 v[28:31], v[132:135], v[204:207], v[28:31]
	v_mfma_f32_16x16x32_bf16 v[16:19], v[128:131], v[208:211], v[16:19]
	v_mfma_f32_16x16x32_bf16 v[16:19], v[132:135], v[212:215], v[16:19]
	v_mfma_f32_16x16x32_bf16 v[56:59], v[136:139], v[184:187], v[56:59]
	v_mfma_f32_16x16x32_bf16 v[56:59], v[140:143], v[188:191], v[56:59]
	v_mfma_f32_16x16x32_bf16 v[40:43], v[136:139], v[192:195], v[40:43]
	v_mfma_f32_16x16x32_bf16 v[40:43], v[140:143], v[196:199], v[40:43]
	v_mfma_f32_16x16x32_bf16 v[24:27], v[136:139], v[200:203], v[24:27]
	v_mfma_f32_16x16x32_bf16 v[24:27], v[140:143], v[204:207], v[24:27]
	v_mfma_f32_16x16x32_bf16 v[8:11], v[136:139], v[208:211], v[8:11]
	v_mfma_f32_16x16x32_bf16 v[8:11], v[140:143], v[212:215], v[8:11]
	s_setprio 0
	s_setprio 1
	v_mfma_f32_16x16x32_bf16 v[52:55], v[144:147], v[184:187], v[52:55]
	v_mfma_f32_16x16x32_bf16 v[52:55], v[148:151], v[188:191], v[52:55]
	v_mfma_f32_16x16x32_bf16 v[36:39], v[144:147], v[192:195], v[36:39]
	v_mfma_f32_16x16x32_bf16 v[36:39], v[148:151], v[196:199], v[36:39]
	v_mfma_f32_16x16x32_bf16 v[20:23], v[144:147], v[200:203], v[20:23]
	v_mfma_f32_16x16x32_bf16 v[20:23], v[148:151], v[204:207], v[20:23]
	v_mfma_f32_16x16x32_bf16 v[4:7], v[144:147], v[208:211], v[4:7]
	v_mfma_f32_16x16x32_bf16 v[4:7], v[148:151], v[212:215], v[4:7]
	v_mfma_f32_16x16x32_bf16 v[44:47], v[170:173], v[184:187], v[44:47]
	v_mfma_f32_16x16x32_bf16 v[44:47], v[178:181], v[188:191], v[44:47]
	v_mfma_f32_16x16x32_bf16 v[32:35], v[170:173], v[192:195], v[32:35]
	v_mfma_f32_16x16x32_bf16 v[32:35], v[178:181], v[196:199], v[32:35]
	v_mfma_f32_16x16x32_bf16 v[12:15], v[170:173], v[200:203], v[12:15]
	v_mfma_f32_16x16x32_bf16 v[12:15], v[178:181], v[204:207], v[12:15]
	v_mfma_f32_16x16x32_bf16 v[0:3], v[170:173], v[208:211], v[0:3]
	v_mfma_f32_16x16x32_bf16 v[0:3], v[178:181], v[212:215], v[0:3]
	s_barrier
; #define PG8_STAGE(bufoff, gbase, voff) do { _Pragma("unroll") for (int _i = 0; _i < 2; ++_i) \
;         __builtin_amdgcn_global_load_lds((const unsigned*)((const char*)(gbase) + (voff)[_i]), (PG8_LAS unsigned*)(lds + (bufoff) + ldsw + _i * 8192), 16, 0, 0); } while (0)
; #define PG8_LDA(dst, b, h) do { _Pragma("unroll") for (int m = 0; m < 4; ++m) _Pragma("unroll") for (int k = 0; k < 2; ++k) dst[m][k] = *(const PG8_LAS bf16x8*)(lds + PG8_SA(b, h) + aoff + m * 2048 + k * 1024); } while (0)
; #define PG8_LDB(dst, b, h) do { _Pragma("unroll") for (int n = 0; n < 2; ++n) _Pragma("unroll") for (int k = 0; k < 2; ++k) dst[n][k] = *(const PG8_LAS bf16x8*)(lds + PG8_SB(b, h) + boff + n * 2048 + k * 1024); } while (0)
; #define PG8_MMA(ai, bj, At, Bt) do { __builtin_amdgcn_s_setprio(1); _Pragma("unroll") for (int m = 0; m < 4; ++m) _Pragma("unroll") for (int n = 0; n < 2; ++n) _Pragma("unroll") for (int k = 0; k < 2; ++k) \
;         acc[ai][bj][m][n] = __builtin_amdgcn_mfma_f32_16x16x32_bf16(Bt[n][k], At[m][k], acc[ai][bj][m][n], 0, 0, 0); __builtin_amdgcn_s_setprio(0); } while (0)
; #define PG8_WAIT_V(n) asm volatile("s_waitcnt vmcnt(" #n ")" ::: "memory")
; #define PG8_WAIT_L(n) asm volatile("s_waitcnt lgkmcnt(" #n ")" ::: "memory")
; #define PG8_BAR __builtin_amdgcn_s_barrier()
; #define PG8_SCHED __builtin_amdgcn_sched_barrier(0)
;     ...
;         for (int t = 0; t < nt; t += 2) {
;     ...
;             PG8_LDB(B0, 1, 0); PG8_LDB(B1, 1, 1); PG8_SCHED; PG8_LDA(At, 1, 0); PG8_STAGE(PG8_SA(0, 1), a2 + hstep, voffA);
;             PG8_WAIT_V(8); PG8_WAIT_L(0); PG8_BAR; PG8_MMA(0, 0, At, B0); PG8_MMA(0, 1, At, B1); PG8_BAR; PG8_SCHED;
;             PG8_LDA(At, 1, 1); PG8_STAGE(PG8_SB(1, 0), b3, voffB); PG8_STAGE(PG8_SB(1, 1), b3 + hstep, voffB); PG8_STAGE(PG8_SA(1, 0), a3, voffA);
;             PG8_WAIT_V(8); PG8_WAIT_L(0); PG8_BAR; PG8_MMA(1, 0, At, B0); PG8_MMA(1, 1, At, B1); PG8_BAR; PG8_SCHED;
	s_setprio 0
	s_add_i32 s31, 0, 0x18000
	s_add_i32 s33, 0, 0x1c000
	v_add_u32_e32 v140, s31, v166
	v_add_u32_e32 v168, s33, v166
	ds_read_b128 v[128:131], v140
	ds_read_b128 v[132:135], v140 offset:1024
	ds_read_b128 v[136:139], v140 offset:2048
	ds_read_b128 v[140:143], v140 offset:3072
	ds_read_b128 v[144:147], v168
	ds_read_b128 v[148:151], v168 offset:1024
	ds_read_b128 v[170:173], v168 offset:2048
	ds_read_b128 v[178:181], v168 offset:3072
	s_add_u32 s12, s86, 0x80000
	s_addc_u32 s13, s87, 0
	s_mov_b32 m0, s18
	ds_read_b128 v[184:187], v183 offset:32768
	ds_read_b128 v[188:191], v183 offset:33792
	ds_read_b128 v[192:195], v183 offset:34816
	ds_read_b128 v[196:199], v183 offset:35840
	ds_read_b128 v[200:203], v183 offset:36864
	ds_read_b128 v[204:207], v183 offset:37888
	ds_read_b128 v[208:211], v183 offset:38912
	ds_read_b128 v[212:215], v183 offset:39936
	global_load_lds_dwordx4 v152, s[12:13]
	s_mov_b32 m0, s19
	s_nop 0
	global_load_lds_dwordx4 v156, s[12:13]
	s_waitcnt vmcnt(8)
	s_waitcnt lgkmcnt(0)
	s_barrier
	s_setprio 1
	v_mfma_f32_16x16x32_bf16 v[124:127], v[128:131], v[184:187], v[124:127]
	v_mfma_f32_16x16x32_bf16 v[124:127], v[132:135], v[188:191], v[124:127]
	v_mfma_f32_16x16x32_bf16 v[112:115], v[128:131], v[192:195], v[112:115]
	v_mfma_f32_16x16x32_bf16 v[112:115], v[132:135], v[196:199], v[112:115]
	v_mfma_f32_16x16x32_bf16 v[92:95], v[128:131], v[200:203], v[92:95]
	v_mfma_f32_16x16x32_bf16 v[92:95], v[132:135], v[204:207], v[92:95]
	v_mfma_f32_16x16x32_bf16 v[80:83], v[128:131], v[208:211], v[80:83]
	v_mfma_f32_16x16x32_bf16 v[80:83], v[132:135], v[212:215], v[80:83]
	v_mfma_f32_16x16x32_bf16 v[120:123], v[136:139], v[184:187], v[120:123]
	v_mfma_f32_16x16x32_bf16 v[120:123], v[140:143], v[188:191], v[120:123]
	v_mfma_f32_16x16x32_bf16 v[104:107], v[136:139], v[192:195], v[104:107]
	v_mfma_f32_16x16x32_bf16 v[104:107], v[140:143], v[196:199], v[104:107]
	v_mfma_f32_16x16x32_bf16 v[88:91], v[136:139], v[200:203], v[88:91]
	v_mfma_f32_16x16x32_bf16 v[88:91], v[140:143], v[204:207], v[88:91]
	v_mfma_f32_16x16x32_bf16 v[72:75], v[136:139], v[208:211], v[72:75]
	v_mfma_f32_16x16x32_bf16 v[72:75], v[140:143], v[212:215], v[72:75]
	s_setprio 0
	s_setprio 1
	v_mfma_f32_16x16x32_bf16 v[116:119], v[144:147], v[184:187], v[116:119]
	v_mfma_f32_16x16x32_bf16 v[116:119], v[148:151], v[188:191], v[116:119]
	v_mfma_f32_16x16x32_bf16 v[100:103], v[144:147], v[192:195], v[100:103]
	v_mfma_f32_16x16x32_bf16 v[100:103], v[148:151], v[196:199], v[100:103]
	v_mfma_f32_16x16x32_bf16 v[84:87], v[144:147], v[200:203], v[84:87]
	v_mfma_f32_16x16x32_bf16 v[84:87], v[148:151], v[204:207], v[84:87]
	v_mfma_f32_16x16x32_bf16 v[68:71], v[144:147], v[208:211], v[68:71]
	v_mfma_f32_16x16x32_bf16 v[68:71], v[148:151], v[212:215], v[68:71]
	v_mfma_f32_16x16x32_bf16 v[108:111], v[170:173], v[184:187], v[108:111]
	v_mfma_f32_16x16x32_bf16 v[108:111], v[178:181], v[188:191], v[108:111]
	v_mfma_f32_16x16x32_bf16 v[96:99], v[170:173], v[192:195], v[96:99]
	v_mfma_f32_16x16x32_bf16 v[96:99], v[178:181], v[196:199], v[96:99]
	v_mfma_f32_16x16x32_bf16 v[76:79], v[170:173], v[200:203], v[76:79]
	v_mfma_f32_16x16x32_bf16 v[76:79], v[178:181], v[204:207], v[76:79]
	v_mfma_f32_16x16x32_bf16 v[64:67], v[170:173], v[208:211], v[64:67]
	v_mfma_f32_16x16x32_bf16 v[64:67], v[178:181], v[212:215], v[64:67]
	s_barrier
	s_setprio 0
	s_add_i32 s12, s31, s8
	s_mov_b32 m0, s12
	ds_read_b128 v[184:187], v183 offset:49152
	ds_read_b128 v[188:191], v183 offset:50176
	ds_read_b128 v[192:195], v183 offset:51200
	ds_read_b128 v[196:199], v183 offset:52224
	ds_read_b128 v[200:203], v183 offset:53248
	ds_read_b128 v[204:207], v183 offset:54272
	ds_read_b128 v[208:211], v183 offset:55296
	ds_read_b128 v[212:215], v183 offset:56320
	s_add_u32 s100, s84, s16
	s_addc_u32 s101, s85, s17
	global_load_lds_dwordx4 v154, s[100:101]
	s_add_i32 m0, s12, 0x2000
	s_add_u32 s12, s84, 0x80080
	s_addc_u32 s13, s85, 0
	s_add_i32 s31, s33, s8
	global_load_lds_dwordx4 v158, s[100:101]
	s_mov_b32 m0, s31
	s_nop 0
	global_load_lds_dwordx4 v154, s[12:13]
	s_add_i32 m0, s31, 0x2000
	s_nop 0
	global_load_lds_dwordx4 v158, s[12:13]
	s_mov_b32 m0, s20
	s_nop 0
	s_add_u32 s100, s86, s16
	s_addc_u32 s101, s87, s17
	global_load_lds_dwordx4 v152, s[100:101]
	s_mov_b32 m0, s21
	s_nop 0
	global_load_lds_dwordx4 v156, s[100:101]
	s_waitcnt vmcnt(8)
	s_waitcnt lgkmcnt(0)
	s_barrier
	s_setprio 1
	v_mfma_f32_16x16x32_bf16 v[60:63], v[128:131], v[184:187], v[60:63]
	v_mfma_f32_16x16x32_bf16 v[60:63], v[132:135], v[188:191], v[60:63]
	v_mfma_f32_16x16x32_bf16 v[48:51], v[128:131], v[192:195], v[48:51]
	v_mfma_f32_16x16x32_bf16 v[48:51], v[132:135], v[196:199], v[48:51]
	v_mfma_f32_16x16x32_bf16 v[28:31], v[128:131], v[200:203], v[28:31]
	v_mfma_f32_16x16x32_bf16 v[28:31], v[132:135], v[204:207], v[28:31]
	v_mfma_f32_16x16x32_bf16 v[16:19], v[128:131], v[208:211], v[16:19]
	v_mfma_f32_16x16x32_bf16 v[16:19], v[132:135], v[212:215], v[16:19]
	v_mfma_f32_16x16x32_bf16 v[56:59], v[136:139], v[184:187], v[56:59]
	v_mfma_f32_16x16x32_bf16 v[56:59], v[140:143], v[188:191], v[56:59]
	v_mfma_f32_16x16x32_bf16 v[40:43], v[136:139], v[192:195], v[40:43]
	v_mfma_f32_16x16x32_bf16 v[40:43], v[140:143], v[196:199], v[40:43]
	v_mfma_f32_16x16x32_bf16 v[24:27], v[136:139], v[200:203], v[24:27]
	v_mfma_f32_16x16x32_bf16 v[24:27], v[140:143], v[204:207], v[24:27]
	v_mfma_f32_16x16x32_bf16 v[8:11], v[136:139], v[208:211], v[8:11]
	v_mfma_f32_16x16x32_bf16 v[8:11], v[140:143], v[212:215], v[8:11]
	s_setprio 0
	s_setprio 1
	v_mfma_f32_16x16x32_bf16 v[52:55], v[144:147], v[184:187], v[52:55]
	v_mfma_f32_16x16x32_bf16 v[52:55], v[148:151], v[188:191], v[52:55]
	v_mfma_f32_16x16x32_bf16 v[36:39], v[144:147], v[192:195], v[36:39]
	v_mfma_f32_16x16x32_bf16 v[36:39], v[148:151], v[196:199], v[36:39]
	v_mfma_f32_16x16x32_bf16 v[20:23], v[144:147], v[200:203], v[20:23]
	v_mfma_f32_16x16x32_bf16 v[20:23], v[148:151], v[204:207], v[20:23]
	v_mfma_f32_16x16x32_bf16 v[4:7], v[144:147], v[208:211], v[4:7]
	v_mfma_f32_16x16x32_bf16 v[4:7], v[148:151], v[212:215], v[4:7]
	v_mfma_f32_16x16x32_bf16 v[44:47], v[170:173], v[184:187], v[44:47]
	v_mfma_f32_16x16x32_bf16 v[44:47], v[178:181], v[188:191], v[44:47]
	v_mfma_f32_16x16x32_bf16 v[32:35], v[170:173], v[192:195], v[32:35]
	v_mfma_f32_16x16x32_bf16 v[32:35], v[178:181], v[196:199], v[32:35]
	v_mfma_f32_16x16x32_bf16 v[12:15], v[170:173], v[200:203], v[12:15]
	v_mfma_f32_16x16x32_bf16 v[12:15], v[178:181], v[204:207], v[12:15]
	v_mfma_f32_16x16x32_bf16 v[0:3], v[170:173], v[208:211], v[0:3]
	v_mfma_f32_16x16x32_bf16 v[0:3], v[178:181], v[212:215], v[0:3]
	s_barrier
	s_setprio 0
	s_add_i32 s3, s3, 2
	s_add_u32 s82, s82, 0x100
	s_addc_u32 s83, s83, 0
	s_add_u32 s30, s30, 0x100
	s_addc_u32 s2, s2, 0
	s_cmp_gt_u32 s3, 29
	s_cbranch_scc0 .LBB0_856
	s_and_b64 vcc, exec, s[70:71]
	s_cbranch_vccz .LBB0_859
	s_barrier

; #define PG8_STAGE(bufoff, gbase, voff) do { _Pragma("unroll") for (int _i = 0; _i < 2; ++_i) \
;         __builtin_amdgcn_global_load_lds((const unsigned*)((const char*)(gbase) + (voff)[_i]), (PG8_LAS unsigned*)(lds + (bufoff) + ldsw + _i * 8192), 16, 0, 0); } while (0)
; #define PG8_LDA(dst, b, h) do { _Pragma("unroll") for (int m = 0; m < 4; ++m) _Pragma("unroll") for (int k = 0; k < 2; ++k) dst[m][k] = *(const PG8_LAS bf16x8*)(lds + PG8_SA(b, h) + aoff + m * 2048 + k * 1024); } while (0)
; #define PG8_LDB(dst, b, h) do { _Pragma("unroll") for (int n = 0; n < 2; ++n) _Pragma("unroll") for (int k = 0; k < 2; ++k) dst[n][k] = *(const PG8_LAS bf16x8*)(lds + PG8_SB(b, h) + boff + n * 2048 + k * 1024); } while (0)
; #define PG8_MMA(ai, bj, At, Bt) do { __builtin_amdgcn_s_setprio(1); _Pragma("unroll") for (int m = 0; m < 4; ++m) _Pragma("unroll") for (int n = 0; n < 2; ++n) _Pragma("unroll") for (int k = 0; k < 2; ++k) \
;         acc[ai][bj][m][n] = __builtin_amdgcn_mfma_f32_16x16x32_bf16(Bt[n][k], At[m][k], acc[ai][bj][m][n], 0, 0, 0); __builtin_amdgcn_s_setprio(0); } while (0)
; #define PG8_WAIT_V(n) asm volatile("s_waitcnt vmcnt(" #n ")" ::: "memory")
; #define PG8_WAIT_L(n) asm volatile("s_waitcnt lgkmcnt(" #n ")" ::: "memory")
; #define PG8_BAR __builtin_amdgcn_s_barrier()
; #define PG8_SCHED __builtin_amdgcn_sched_barrier(0)
;     ...
;             const bool last = (t == nt - 2);
;             const char* a1 = PG8_KADV(cA, (size_t)(t + 1) * kstep);
;             const char* a2 = last ? nA : PG8_KADV(cA, (size_t)(t + 2) * kstep); const char* b2 = last ? nB : PG8_KADV(cB, (size_t)(t + 2) * kstep);
;             const char* a3 = PG8_KADV(a2, kstep); const char* b3 = PG8_KADV(b2, kstep);
;             if (last && has_next) S.a_ready(nxt);
;             if constexpr (SP2) {
;             PG8_LDB(B0, 0, 0); PG8_LDB(B1, 0, 1); PG8_SCHED; PG8_LDA(At, 0, 0); PG8_STAGE(PG8_SA(1, 1), a1 + hstep, voffA);
;             PG8_WAIT_V(8); PG8_WAIT_L(0); PG8_BAR; PG8_MMA(0, 0, At, B0); PG8_MMA(0, 1, At, B1); PG8_BAR; PG8_SCHED;
;             PG8_LDA(At, 0, 1); PG8_STAGE(PG8_SB(0, 0), b2, voffB); PG8_STAGE(PG8_SB(0, 1), b2 + hstep, voffB); PG8_STAGE(PG8_SA(0, 0), a2, voffA);
;             PG8_WAIT_V(8); PG8_WAIT_L(0); PG8_BAR; PG8_MMA(1, 0, At, B0); PG8_MMA(1, 1, At, B1); PG8_BAR; PG8_SCHED;
.LBB0_983:
	s_add_u32 s12, s70, 0xfff80080
	s_addc_u32 s13, s71, -1
	s_add_i32 s31, 0, 0x10000
	s_cmp_eq_u32 s3, 28
	s_cselect_b32 s75, s15, s13
	s_cselect_b32 s74, s28, s12
	s_cselect_b32 s73, s30, s2
	s_cselect_b32 s72, s33, s40
	s_add_i32 s42, 0, 0x14000
	v_add_u32_e32 v156, s31, v141
	v_add_u32_e32 v168, s42, v141
	ds_read_b128 v[144:147], v156
	ds_read_b128 v[148:151], v156 offset:1024
	ds_read_b128 v[152:155], v156 offset:2048
	ds_read_b128 v[156:159], v156 offset:3072
	ds_read_b128 v[160:163], v168
	ds_read_b128 v[164:167], v168 offset:1024
	ds_read_b128 v[170:173], v168 offset:2048
	ds_read_b128 v[178:181], v168 offset:3072
	s_add_i32 m0, s18, 0xc000
	ds_read_b128 v[182:185], v143
	ds_read_b128 v[186:189], v143 offset:1024
	ds_read_b128 v[190:193], v143 offset:2048
	ds_read_b128 v[194:197], v143 offset:3072
	ds_read_b128 v[198:201], v143 offset:4096
	ds_read_b128 v[202:205], v143 offset:5120
	ds_read_b128 v[206:209], v143 offset:6144
	ds_read_b128 v[210:213], v143 offset:7168
	global_load_lds_dwordx4 v136, s[70:71]
	s_add_i32 m0, s18, 0xe000
	s_nop 0
	global_load_lds_dwordx4 v138, s[70:71]
	s_waitcnt vmcnt(8)
	s_waitcnt lgkmcnt(0)
	s_barrier
	s_setprio 1
	v_mfma_f32_16x16x32_bf16 v[124:127], v[144:147], v[182:185], v[124:127]
	v_mfma_f32_16x16x32_bf16 v[124:127], v[148:151], v[186:189], v[124:127]
	v_mfma_f32_16x16x32_bf16 v[108:111], v[144:147], v[190:193], v[108:111]
	v_mfma_f32_16x16x32_bf16 v[108:111], v[148:151], v[194:197], v[108:111]
	v_mfma_f32_16x16x32_bf16 v[92:95], v[144:147], v[198:201], v[92:95]
	v_mfma_f32_16x16x32_bf16 v[92:95], v[148:151], v[202:205], v[92:95]
	v_mfma_f32_16x16x32_bf16 v[76:79], v[144:147], v[206:209], v[76:79]
	v_mfma_f32_16x16x32_bf16 v[76:79], v[148:151], v[210:213], v[76:79]
	v_mfma_f32_16x16x32_bf16 v[120:123], v[152:155], v[182:185], v[120:123]
	v_mfma_f32_16x16x32_bf16 v[120:123], v[156:159], v[186:189], v[120:123]
	v_mfma_f32_16x16x32_bf16 v[104:107], v[152:155], v[190:193], v[104:107]
	v_mfma_f32_16x16x32_bf16 v[104:107], v[156:159], v[194:197], v[104:107]
	v_mfma_f32_16x16x32_bf16 v[88:91], v[152:155], v[198:201], v[88:91]
	v_mfma_f32_16x16x32_bf16 v[88:91], v[156:159], v[202:205], v[88:91]
	v_mfma_f32_16x16x32_bf16 v[72:75], v[152:155], v[206:209], v[72:75]
	v_mfma_f32_16x16x32_bf16 v[72:75], v[156:159], v[210:213], v[72:75]
	s_setprio 0
	s_setprio 1
	v_mfma_f32_16x16x32_bf16 v[116:119], v[160:163], v[182:185], v[116:119]
	v_mfma_f32_16x16x32_bf16 v[116:119], v[164:167], v[186:189], v[116:119]
	v_mfma_f32_16x16x32_bf16 v[100:103], v[160:163], v[190:193], v[100:103]
	v_mfma_f32_16x16x32_bf16 v[100:103], v[164:167], v[194:197], v[100:103]
	v_mfma_f32_16x16x32_bf16 v[84:87], v[160:163], v[198:201], v[84:87]
	v_mfma_f32_16x16x32_bf16 v[84:87], v[164:167], v[202:205], v[84:87]
	v_mfma_f32_16x16x32_bf16 v[68:71], v[160:163], v[206:209], v[68:71]
	v_mfma_f32_16x16x32_bf16 v[68:71], v[164:167], v[210:213], v[68:71]
	v_mfma_f32_16x16x32_bf16 v[112:115], v[170:173], v[182:185], v[112:115]
	v_mfma_f32_16x16x32_bf16 v[112:115], v[178:181], v[186:189], v[112:115]
	v_mfma_f32_16x16x32_bf16 v[96:99], v[170:173], v[190:193], v[96:99]
	v_mfma_f32_16x16x32_bf16 v[96:99], v[178:181], v[194:197], v[96:99]
	v_mfma_f32_16x16x32_bf16 v[80:83], v[170:173], v[198:201], v[80:83]
	v_mfma_f32_16x16x32_bf16 v[80:83], v[178:181], v[202:205], v[80:83]
	v_mfma_f32_16x16x32_bf16 v[64:67], v[170:173], v[206:209], v[64:67]
	v_mfma_f32_16x16x32_bf16 v[64:67], v[178:181], v[210:213], v[64:67]
	s_barrier
	s_setprio 0
	s_add_i32 s12, s31, s10
	s_mov_b32 m0, s12
	ds_read_b128 v[182:185], v143 offset:16384
	ds_read_b128 v[186:189], v143 offset:17408
	ds_read_b128 v[190:193], v143 offset:18432
	ds_read_b128 v[194:197], v143 offset:19456
	ds_read_b128 v[198:201], v143 offset:20480
	ds_read_b128 v[202:205], v143 offset:21504
	ds_read_b128 v[206:209], v143 offset:22528
	ds_read_b128 v[210:213], v143 offset:23552
	global_load_lds_dwordx4 v132, s[72:73]
	s_add_i32 m0, s12, 0x2000
	s_add_u32 s12, s72, 0x80000
	s_addc_u32 s13, s73, 0
	s_add_i32 s31, s42, s10
	global_load_lds_dwordx4 v128, s[72:73]
	s_mov_b32 m0, s31
	s_nop 0
	global_load_lds_dwordx4 v132, s[12:13]
	s_add_i32 m0, s31, 0x2000
	s_nop 0
	global_load_lds_dwordx4 v128, s[12:13]
	s_mov_b32 m0, s18
	s_nop 0
	global_load_lds_dwordx4 v134, s[74:75]
	s_mov_b32 m0, s19
	s_nop 0
	global_load_lds_dwordx4 v130, s[74:75]
	s_waitcnt vmcnt(8)
	s_waitcnt lgkmcnt(0)
	s_barrier
	s_setprio 1
	v_mfma_f32_16x16x32_bf16 v[60:63], v[144:147], v[182:185], v[60:63]
	v_mfma_f32_16x16x32_bf16 v[60:63], v[148:151], v[186:189], v[60:63]
	v_mfma_f32_16x16x32_bf16 v[44:47], v[144:147], v[190:193], v[44:47]
	v_mfma_f32_16x16x32_bf16 v[44:47], v[148:151], v[194:197], v[44:47]
	v_mfma_f32_16x16x32_bf16 v[28:31], v[144:147], v[198:201], v[28:31]
	v_mfma_f32_16x16x32_bf16 v[28:31], v[148:151], v[202:205], v[28:31]
	v_mfma_f32_16x16x32_bf16 v[12:15], v[144:147], v[206:209], v[12:15]
	v_mfma_f32_16x16x32_bf16 v[12:15], v[148:151], v[210:213], v[12:15]
	v_mfma_f32_16x16x32_bf16 v[56:59], v[152:155], v[182:185], v[56:59]
	v_mfma_f32_16x16x32_bf16 v[56:59], v[156:159], v[186:189], v[56:59]
	v_mfma_f32_16x16x32_bf16 v[40:43], v[152:155], v[190:193], v[40:43]
	v_mfma_f32_16x16x32_bf16 v[40:43], v[156:159], v[194:197], v[40:43]
	v_mfma_f32_16x16x32_bf16 v[24:27], v[152:155], v[198:201], v[24:27]
	v_mfma_f32_16x16x32_bf16 v[24:27], v[156:159], v[202:205], v[24:27]
	v_mfma_f32_16x16x32_bf16 v[8:11], v[152:155], v[206:209], v[8:11]
	v_mfma_f32_16x16x32_bf16 v[8:11], v[156:159], v[210:213], v[8:11]
	s_setprio 0
	s_setprio 1
	v_mfma_f32_16x16x32_bf16 v[52:55], v[160:163], v[182:185], v[52:55]
	v_mfma_f32_16x16x32_bf16 v[52:55], v[164:167], v[186:189], v[52:55]
	v_mfma_f32_16x16x32_bf16 v[36:39], v[160:163], v[190:193], v[36:39]
	v_mfma_f32_16x16x32_bf16 v[36:39], v[164:167], v[194:197], v[36:39]
	v_mfma_f32_16x16x32_bf16 v[20:23], v[160:163], v[198:201], v[20:23]
	v_mfma_f32_16x16x32_bf16 v[20:23], v[164:167], v[202:205], v[20:23]
	v_mfma_f32_16x16x32_bf16 v[4:7], v[160:163], v[206:209], v[4:7]
	v_mfma_f32_16x16x32_bf16 v[4:7], v[164:167], v[210:213], v[4:7]
	v_mfma_f32_16x16x32_bf16 v[48:51], v[170:173], v[182:185], v[48:51]
	v_mfma_f32_16x16x32_bf16 v[48:51], v[178:181], v[186:189], v[48:51]
	v_mfma_f32_16x16x32_bf16 v[32:35], v[170:173], v[190:193], v[32:35]
	v_mfma_f32_16x16x32_bf16 v[32:35], v[178:181], v[194:197], v[32:35]
	v_mfma_f32_16x16x32_bf16 v[16:19], v[170:173], v[198:201], v[16:19]
	v_mfma_f32_16x16x32_bf16 v[16:19], v[178:181], v[202:205], v[16:19]
	v_mfma_f32_16x16x32_bf16 v[0:3], v[170:173], v[206:209], v[0:3]
	v_mfma_f32_16x16x32_bf16 v[0:3], v[178:181], v[210:213], v[0:3]
	s_barrier
; #define PG8_STAGE(bufoff, gbase, voff) do { _Pragma("unroll") for (int _i = 0; _i < 2; ++_i) \
;         __builtin_amdgcn_global_load_lds((const unsigned*)((const char*)(gbase) + (voff)[_i]), (PG8_LAS unsigned*)(lds + (bufoff) + ldsw + _i * 8192), 16, 0, 0); } while (0)
; #define PG8_LDA(dst, b, h) do { _Pragma("unroll") for (int m = 0; m < 4; ++m) _Pragma("unroll") for (int k = 0; k < 2; ++k) dst[m][k] = *(const PG8_LAS bf16x8*)(lds + PG8_SA(b, h) + aoff + m * 2048 + k * 1024); } while (0)
; #define PG8_LDB(dst, b, h) do { _Pragma("unroll") for (int n = 0; n < 2; ++n) _Pragma("unroll") for (int k = 0; k < 2; ++k) dst[n][k] = *(const PG8_LAS bf16x8*)(lds + PG8_SB(b, h) + boff + n * 2048 + k * 1024); } while (0)
; #define PG8_MMA(ai, bj, At, Bt) do { __builtin_amdgcn_s_setprio(1); _Pragma("unroll") for (int m = 0; m < 4; ++m) _Pragma("unroll") for (int n = 0; n < 2; ++n) _Pragma("unroll") for (int k = 0; k < 2; ++k) \
;         acc[ai][bj][m][n] = __builtin_amdgcn_mfma_f32_16x16x32_bf16(Bt[n][k], At[m][k], acc[ai][bj][m][n], 0, 0, 0); __builtin_amdgcn_s_setprio(0); } while (0)
; #define PG8_WAIT_V(n) asm volatile("s_waitcnt vmcnt(" #n ")" ::: "memory")
; #define PG8_WAIT_L(n) asm volatile("s_waitcnt lgkmcnt(" #n ")" ::: "memory")
; #define PG8_BAR __builtin_amdgcn_s_barrier()
; #define PG8_SCHED __builtin_amdgcn_sched_barrier(0)
;     ...
;         for (int t = 0; t < nt; t += 2) {
;     ...
;             PG8_LDB(B0, 1, 0); PG8_LDB(B1, 1, 1); PG8_SCHED; PG8_LDA(At, 1, 0); PG8_STAGE(PG8_SA(0, 1), a2 + hstep, voffA);
;             PG8_WAIT_V(8); PG8_WAIT_L(0); PG8_BAR; PG8_MMA(0, 0, At, B0); PG8_MMA(0, 1, At, B1); PG8_BAR; PG8_SCHED;
;             PG8_LDA(At, 1, 1); PG8_STAGE(PG8_SB(1, 0), b3, voffB); PG8_STAGE(PG8_SB(1, 1), b3 + hstep, voffB); PG8_STAGE(PG8_SA(1, 0), a3, voffA);
;             PG8_WAIT_V(8); PG8_WAIT_L(0); PG8_BAR; PG8_MMA(1, 0, At, B0); PG8_MMA(1, 1, At, B1); PG8_BAR; PG8_SCHED;
	s_setprio 0
	s_add_i32 s31, 0, 0x18000
	s_add_i32 s42, 0, 0x1c000
	v_add_u32_e32 v156, s31, v141
	v_add_u32_e32 v168, s42, v141
	ds_read_b128 v[144:147], v156
	ds_read_b128 v[148:151], v156 offset:1024
	ds_read_b128 v[152:155], v156 offset:2048
	ds_read_b128 v[156:159], v156 offset:3072
	ds_read_b128 v[160:163], v168
	ds_read_b128 v[164:167], v168 offset:1024
	ds_read_b128 v[170:173], v168 offset:2048
	ds_read_b128 v[178:181], v168 offset:3072
	s_add_u32 s12, s74, 0x80000
	s_addc_u32 s13, s75, 0
	s_mov_b32 m0, s20
	ds_read_b128 v[182:185], v143 offset:32768
	ds_read_b128 v[186:189], v143 offset:33792
	ds_read_b128 v[190:193], v143 offset:34816
	ds_read_b128 v[194:197], v143 offset:35840
	ds_read_b128 v[198:201], v143 offset:36864
	ds_read_b128 v[202:205], v143 offset:37888
	ds_read_b128 v[206:209], v143 offset:38912
	ds_read_b128 v[210:213], v143 offset:39936
	global_load_lds_dwordx4 v134, s[12:13]
	s_mov_b32 m0, s21
	s_nop 0
	global_load_lds_dwordx4 v130, s[12:13]
	s_waitcnt vmcnt(8)
	s_waitcnt lgkmcnt(0)
	s_barrier
	s_setprio 1
	v_mfma_f32_16x16x32_bf16 v[124:127], v[144:147], v[182:185], v[124:127]
	v_mfma_f32_16x16x32_bf16 v[124:127], v[148:151], v[186:189], v[124:127]
	v_mfma_f32_16x16x32_bf16 v[108:111], v[144:147], v[190:193], v[108:111]
	v_mfma_f32_16x16x32_bf16 v[108:111], v[148:151], v[194:197], v[108:111]
	v_mfma_f32_16x16x32_bf16 v[92:95], v[144:147], v[198:201], v[92:95]
	v_mfma_f32_16x16x32_bf16 v[92:95], v[148:151], v[202:205], v[92:95]
	v_mfma_f32_16x16x32_bf16 v[76:79], v[144:147], v[206:209], v[76:79]
	v_mfma_f32_16x16x32_bf16 v[76:79], v[148:151], v[210:213], v[76:79]
	v_mfma_f32_16x16x32_bf16 v[120:123], v[152:155], v[182:185], v[120:123]
	v_mfma_f32_16x16x32_bf16 v[120:123], v[156:159], v[186:189], v[120:123]
	v_mfma_f32_16x16x32_bf16 v[104:107], v[152:155], v[190:193], v[104:107]
	v_mfma_f32_16x16x32_bf16 v[104:107], v[156:159], v[194:197], v[104:107]
	v_mfma_f32_16x16x32_bf16 v[88:91], v[152:155], v[198:201], v[88:91]
	v_mfma_f32_16x16x32_bf16 v[88:91], v[156:159], v[202:205], v[88:91]
	v_mfma_f32_16x16x32_bf16 v[72:75], v[152:155], v[206:209], v[72:75]
	v_mfma_f32_16x16x32_bf16 v[72:75], v[156:159], v[210:213], v[72:75]
	s_setprio 0
	s_setprio 1
	v_mfma_f32_16x16x32_bf16 v[116:119], v[160:163], v[182:185], v[116:119]
	v_mfma_f32_16x16x32_bf16 v[116:119], v[164:167], v[186:189], v[116:119]
	v_mfma_f32_16x16x32_bf16 v[100:103], v[160:163], v[190:193], v[100:103]
	v_mfma_f32_16x16x32_bf16 v[100:103], v[164:167], v[194:197], v[100:103]
	v_mfma_f32_16x16x32_bf16 v[84:87], v[160:163], v[198:201], v[84:87]
	v_mfma_f32_16x16x32_bf16 v[84:87], v[164:167], v[202:205], v[84:87]
	v_mfma_f32_16x16x32_bf16 v[68:71], v[160:163], v[206:209], v[68:71]
	v_mfma_f32_16x16x32_bf16 v[68:71], v[164:167], v[210:213], v[68:71]
	v_mfma_f32_16x16x32_bf16 v[112:115], v[170:173], v[182:185], v[112:115]
	v_mfma_f32_16x16x32_bf16 v[112:115], v[178:181], v[186:189], v[112:115]
	v_mfma_f32_16x16x32_bf16 v[96:99], v[170:173], v[190:193], v[96:99]
	v_mfma_f32_16x16x32_bf16 v[96:99], v[178:181], v[194:197], v[96:99]
	v_mfma_f32_16x16x32_bf16 v[80:83], v[170:173], v[198:201], v[80:83]
	v_mfma_f32_16x16x32_bf16 v[80:83], v[178:181], v[202:205], v[80:83]
	v_mfma_f32_16x16x32_bf16 v[64:67], v[170:173], v[206:209], v[64:67]
	v_mfma_f32_16x16x32_bf16 v[64:67], v[178:181], v[210:213], v[64:67]
	s_barrier
	s_setprio 0
	s_add_i32 s12, s31, s10
	s_mov_b32 m0, s12
	ds_read_b128 v[182:185], v143 offset:49152
	ds_read_b128 v[186:189], v143 offset:50176
	ds_read_b128 v[190:193], v143 offset:51200
	ds_read_b128 v[194:197], v143 offset:52224
	ds_read_b128 v[198:201], v143 offset:53248
	ds_read_b128 v[202:205], v143 offset:54272
	ds_read_b128 v[206:209], v143 offset:55296
	ds_read_b128 v[210:213], v143 offset:56320
	s_add_u32 s100, s72, s16
	s_addc_u32 s101, s73, s17
	global_load_lds_dwordx4 v132, s[100:101]
	s_add_i32 m0, s12, 0x2000
	s_add_u32 s12, s72, 0x80080
	s_addc_u32 s13, s73, 0
	s_add_i32 s31, s42, s10
	global_load_lds_dwordx4 v128, s[100:101]
	s_mov_b32 m0, s31
	s_nop 0
	global_load_lds_dwordx4 v132, s[12:13]
	s_add_i32 m0, s31, 0x2000
	s_nop 0
	global_load_lds_dwordx4 v128, s[12:13]
	s_mov_b32 m0, s22
	s_nop 0
	s_add_u32 s100, s74, s16
	s_addc_u32 s101, s75, s17
	global_load_lds_dwordx4 v134, s[100:101]
	s_mov_b32 m0, s23
	s_nop 0
	global_load_lds_dwordx4 v130, s[100:101]
	s_waitcnt vmcnt(8)
	s_waitcnt lgkmcnt(0)
	s_barrier
	s_setprio 1
	v_mfma_f32_16x16x32_bf16 v[60:63], v[144:147], v[182:185], v[60:63]
	v_mfma_f32_16x16x32_bf16 v[60:63], v[148:151], v[186:189], v[60:63]
	v_mfma_f32_16x16x32_bf16 v[44:47], v[144:147], v[190:193], v[44:47]
	v_mfma_f32_16x16x32_bf16 v[44:47], v[148:151], v[194:197], v[44:47]
	v_mfma_f32_16x16x32_bf16 v[28:31], v[144:147], v[198:201], v[28:31]
	v_mfma_f32_16x16x32_bf16 v[28:31], v[148:151], v[202:205], v[28:31]
	v_mfma_f32_16x16x32_bf16 v[12:15], v[144:147], v[206:209], v[12:15]
	v_mfma_f32_16x16x32_bf16 v[12:15], v[148:151], v[210:213], v[12:15]
	v_mfma_f32_16x16x32_bf16 v[56:59], v[152:155], v[182:185], v[56:59]
	v_mfma_f32_16x16x32_bf16 v[56:59], v[156:159], v[186:189], v[56:59]
	v_mfma_f32_16x16x32_bf16 v[40:43], v[152:155], v[190:193], v[40:43]
	v_mfma_f32_16x16x32_bf16 v[40:43], v[156:159], v[194:197], v[40:43]
	v_mfma_f32_16x16x32_bf16 v[24:27], v[152:155], v[198:201], v[24:27]
	v_mfma_f32_16x16x32_bf16 v[24:27], v[156:159], v[202:205], v[24:27]
	v_mfma_f32_16x16x32_bf16 v[8:11], v[152:155], v[206:209], v[8:11]
	v_mfma_f32_16x16x32_bf16 v[8:11], v[156:159], v[210:213], v[8:11]
	s_setprio 0
	s_setprio 1
	v_mfma_f32_16x16x32_bf16 v[52:55], v[160:163], v[182:185], v[52:55]
	v_mfma_f32_16x16x32_bf16 v[52:55], v[164:167], v[186:189], v[52:55]
	v_mfma_f32_16x16x32_bf16 v[36:39], v[160:163], v[190:193], v[36:39]
	v_mfma_f32_16x16x32_bf16 v[36:39], v[164:167], v[194:197], v[36:39]
	v_mfma_f32_16x16x32_bf16 v[20:23], v[160:163], v[198:201], v[20:23]
	v_mfma_f32_16x16x32_bf16 v[20:23], v[164:167], v[202:205], v[20:23]
	v_mfma_f32_16x16x32_bf16 v[4:7], v[160:163], v[206:209], v[4:7]
	v_mfma_f32_16x16x32_bf16 v[4:7], v[164:167], v[210:213], v[4:7]
	v_mfma_f32_16x16x32_bf16 v[48:51], v[170:173], v[182:185], v[48:51]
	v_mfma_f32_16x16x32_bf16 v[48:51], v[178:181], v[186:189], v[48:51]
	v_mfma_f32_16x16x32_bf16 v[32:35], v[170:173], v[190:193], v[32:35]
	v_mfma_f32_16x16x32_bf16 v[32:35], v[178:181], v[194:197], v[32:35]
	v_mfma_f32_16x16x32_bf16 v[16:19], v[170:173], v[198:201], v[16:19]
	v_mfma_f32_16x16x32_bf16 v[16:19], v[178:181], v[202:205], v[16:19]
	v_mfma_f32_16x16x32_bf16 v[0:3], v[170:173], v[206:209], v[0:3]
	v_mfma_f32_16x16x32_bf16 v[0:3], v[178:181], v[210:213], v[0:3]
	s_barrier
	s_setprio 0
	s_add_i32 s3, s3, 2
	s_add_u32 s70, s70, 0x100
	s_addc_u32 s71, s71, 0
	s_add_u32 s40, s40, 0x100
	s_addc_u32 s2, s2, 0
	s_cmp_gt_u32 s3, 29
	s_cbranch_scc0 .LBB0_983
	s_and_b64 vcc, exec, s[56:57]
	s_cbranch_vccz .LBB0_986
	s_barrier

; #define PG8_STAGE(bufoff, gbase, voff) do { _Pragma("unroll") for (int _i = 0; _i < 2; ++_i) \
;         __builtin_amdgcn_global_load_lds((const unsigned*)((const char*)(gbase) + (voff)[_i]), (PG8_LAS unsigned*)(lds + (bufoff) + ldsw + _i * 8192), 16, 0, 0); } while (0)
; #define PG8_LDA(dst, b, h) do { _Pragma("unroll") for (int m = 0; m < 4; ++m) _Pragma("unroll") for (int k = 0; k < 2; ++k) dst[m][k] = *(const PG8_LAS bf16x8*)(lds + PG8_SA(b, h) + aoff + m * 2048 + k * 1024); } while (0)
; #define PG8_LDB(dst, b, h) do { _Pragma("unroll") for (int n = 0; n < 2; ++n) _Pragma("unroll") for (int k = 0; k < 2; ++k) dst[n][k] = *(const PG8_LAS bf16x8*)(lds + PG8_SB(b, h) + boff + n * 2048 + k * 1024); } while (0)
; #define PG8_MMA(ai, bj, At, Bt) do { __builtin_amdgcn_s_setprio(1); _Pragma("unroll") for (int m = 0; m < 4; ++m) _Pragma("unroll") for (int n = 0; n < 2; ++n) _Pragma("unroll") for (int k = 0; k < 2; ++k) \
;         acc[ai][bj][m][n] = __builtin_amdgcn_mfma_f32_16x16x32_bf16(Bt[n][k], At[m][k], acc[ai][bj][m][n], 0, 0, 0); __builtin_amdgcn_s_setprio(0); } while (0)
; #define PG8_WAIT_V(n) asm volatile("s_waitcnt vmcnt(" #n ")" ::: "memory")
; #define PG8_WAIT_L(n) asm volatile("s_waitcnt lgkmcnt(" #n ")" ::: "memory")
; #define PG8_BAR __builtin_amdgcn_s_barrier()
; #define PG8_SCHED __builtin_amdgcn_sched_barrier(0)
;     ...
;             const bool last = (t == nt - 2);
;             const char* a1 = PG8_KADV(cA, (size_t)(t + 1) * kstep);
;             const char* a2 = last ? nA : PG8_KADV(cA, (size_t)(t + 2) * kstep); const char* b2 = last ? nB : PG8_KADV(cB, (size_t)(t + 2) * kstep);
;             const char* a3 = PG8_KADV(a2, kstep); const char* b3 = PG8_KADV(b2, kstep);
;             if (last && has_next) S.a_ready(nxt);
;             if constexpr (SP2) {
;             PG8_LDB(B0, 0, 0); PG8_LDB(B1, 0, 1); PG8_SCHED; PG8_LDA(At, 0, 0); PG8_STAGE(PG8_SA(1, 1), a1 + hstep, voffA);
;             PG8_WAIT_V(8); PG8_WAIT_L(0); PG8_BAR; PG8_MMA(0, 0, At, B0); PG8_MMA(0, 1, At, B1); PG8_BAR; PG8_SCHED;
;             PG8_LDA(At, 0, 1); PG8_STAGE(PG8_SB(0, 0), b2, voffB); PG8_STAGE(PG8_SB(0, 1), b2 + hstep, voffB); PG8_STAGE(PG8_SA(0, 0), a2, voffA);
;             PG8_WAIT_V(8); PG8_WAIT_L(0); PG8_BAR; PG8_MMA(1, 0, At, B0); PG8_MMA(1, 1, At, B1); PG8_BAR; PG8_SCHED;
.LBB0_1066:
	s_add_u32 s62, s60, 0xffffff00
	s_addc_u32 s63, s61, -1
	s_add_i32 s26, 0, 0x10000
	s_cmpk_eq_i32 s3, 0x54
	s_cselect_b32 s67, s5, s63
	s_cselect_b32 s66, s4, s62
	s_cselect_b32 s65, s59, s25
	s_cselect_b32 s64, s58, s2
	s_add_i32 s28, 0, 0x14000
	v_add_u32_e32 v152, s26, v166
	v_add_u32_e32 v164, s28, v166
	ds_read_b128 v[128:131], v152
	ds_read_b128 v[132:135], v152 offset:1024
	ds_read_b128 v[148:151], v152 offset:2048
	ds_read_b128 v[152:155], v152 offset:3072
	ds_read_b128 v[156:159], v164
	ds_read_b128 v[160:163], v164 offset:1024
	ds_read_b128 v[170:173], v164 offset:2048
	ds_read_b128 v[178:181], v164 offset:3072
	s_add_i32 m0, s13, 0xc000
	ds_read_b128 v[184:187], v183
	ds_read_b128 v[188:191], v183 offset:1024
	ds_read_b128 v[192:195], v183 offset:2048
	ds_read_b128 v[196:199], v183 offset:3072
	ds_read_b128 v[200:203], v183 offset:4096
	ds_read_b128 v[204:207], v183 offset:5120
	ds_read_b128 v[208:211], v183 offset:6144
	ds_read_b128 v[212:215], v183 offset:7168
	global_load_lds_dwordx4 v144, s[60:61]
	s_add_i32 m0, s13, 0xe000
	s_nop 0
	global_load_lds_dwordx4 v146, s[60:61]
	s_waitcnt vmcnt(8)
	s_waitcnt lgkmcnt(0)
	s_barrier
	s_setprio 1
	v_mfma_f32_16x16x32_bf16 v[124:127], v[128:131], v[184:187], v[124:127]
	v_mfma_f32_16x16x32_bf16 v[124:127], v[132:135], v[188:191], v[124:127]
	v_mfma_f32_16x16x32_bf16 v[112:115], v[128:131], v[192:195], v[112:115]
	v_mfma_f32_16x16x32_bf16 v[112:115], v[132:135], v[196:199], v[112:115]
	v_mfma_f32_16x16x32_bf16 v[92:95], v[128:131], v[200:203], v[92:95]
	v_mfma_f32_16x16x32_bf16 v[92:95], v[132:135], v[204:207], v[92:95]
	v_mfma_f32_16x16x32_bf16 v[80:83], v[128:131], v[208:211], v[80:83]
	v_mfma_f32_16x16x32_bf16 v[80:83], v[132:135], v[212:215], v[80:83]
	v_mfma_f32_16x16x32_bf16 v[120:123], v[148:151], v[184:187], v[120:123]
	v_mfma_f32_16x16x32_bf16 v[120:123], v[152:155], v[188:191], v[120:123]
	v_mfma_f32_16x16x32_bf16 v[104:107], v[148:151], v[192:195], v[104:107]
	v_mfma_f32_16x16x32_bf16 v[104:107], v[152:155], v[196:199], v[104:107]
	v_mfma_f32_16x16x32_bf16 v[88:91], v[148:151], v[200:203], v[88:91]
	v_mfma_f32_16x16x32_bf16 v[88:91], v[152:155], v[204:207], v[88:91]
	v_mfma_f32_16x16x32_bf16 v[72:75], v[148:151], v[208:211], v[72:75]
	v_mfma_f32_16x16x32_bf16 v[72:75], v[152:155], v[212:215], v[72:75]
	s_setprio 0
	s_setprio 1
	v_mfma_f32_16x16x32_bf16 v[116:119], v[156:159], v[184:187], v[116:119]
	v_mfma_f32_16x16x32_bf16 v[116:119], v[160:163], v[188:191], v[116:119]
	v_mfma_f32_16x16x32_bf16 v[100:103], v[156:159], v[192:195], v[100:103]
	v_mfma_f32_16x16x32_bf16 v[100:103], v[160:163], v[196:199], v[100:103]
	v_mfma_f32_16x16x32_bf16 v[84:87], v[156:159], v[200:203], v[84:87]
	v_mfma_f32_16x16x32_bf16 v[84:87], v[160:163], v[204:207], v[84:87]
	v_mfma_f32_16x16x32_bf16 v[68:71], v[156:159], v[208:211], v[68:71]
	v_mfma_f32_16x16x32_bf16 v[68:71], v[160:163], v[212:215], v[68:71]
	v_mfma_f32_16x16x32_bf16 v[108:111], v[170:173], v[184:187], v[108:111]
	v_mfma_f32_16x16x32_bf16 v[108:111], v[178:181], v[188:191], v[108:111]
	v_mfma_f32_16x16x32_bf16 v[96:99], v[170:173], v[192:195], v[96:99]
	v_mfma_f32_16x16x32_bf16 v[96:99], v[178:181], v[196:199], v[96:99]
	v_mfma_f32_16x16x32_bf16 v[76:79], v[170:173], v[200:203], v[76:79]
	v_mfma_f32_16x16x32_bf16 v[76:79], v[178:181], v[204:207], v[76:79]
	v_mfma_f32_16x16x32_bf16 v[64:67], v[170:173], v[208:211], v[64:67]
	v_mfma_f32_16x16x32_bf16 v[64:67], v[178:181], v[212:215], v[64:67]
	s_barrier
	s_setprio 0
	s_add_i32 s26, s26, s10
	s_mov_b32 m0, s26
	ds_read_b128 v[184:187], v183 offset:16384
	ds_read_b128 v[188:191], v183 offset:17408
	ds_read_b128 v[192:195], v183 offset:18432
	ds_read_b128 v[196:199], v183 offset:19456
	ds_read_b128 v[200:203], v183 offset:20480
	ds_read_b128 v[204:207], v183 offset:21504
	ds_read_b128 v[208:211], v183 offset:22528
	ds_read_b128 v[212:215], v183 offset:23552
	global_load_lds_dwordx4 v138, s[64:65]
	s_add_i32 m0, s26, 0x2000
	s_add_u32 s42, s64, 0x160000
	s_addc_u32 s43, s65, 0
	s_add_i32 s26, s28, s10
	global_load_lds_dwordx4 v142, s[64:65]
	s_mov_b32 m0, s26
	s_nop 0
	global_load_lds_dwordx4 v138, s[42:43]
	s_add_i32 m0, s26, 0x2000
	s_nop 0
	global_load_lds_dwordx4 v142, s[42:43]
	s_mov_b32 m0, s13
	s_nop 0
	global_load_lds_dwordx4 v136, s[66:67]
	s_mov_b32 m0, s18
	s_nop 0
	global_load_lds_dwordx4 v140, s[66:67]
	s_waitcnt vmcnt(8)
	s_waitcnt lgkmcnt(0)
	s_barrier
	s_setprio 1
	v_mfma_f32_16x16x32_bf16 v[60:63], v[128:131], v[184:187], v[60:63]
	v_mfma_f32_16x16x32_bf16 v[60:63], v[132:135], v[188:191], v[60:63]
	v_mfma_f32_16x16x32_bf16 v[48:51], v[128:131], v[192:195], v[48:51]
	v_mfma_f32_16x16x32_bf16 v[48:51], v[132:135], v[196:199], v[48:51]
	v_mfma_f32_16x16x32_bf16 v[28:31], v[128:131], v[200:203], v[28:31]
	v_mfma_f32_16x16x32_bf16 v[28:31], v[132:135], v[204:207], v[28:31]
	v_mfma_f32_16x16x32_bf16 v[16:19], v[128:131], v[208:211], v[16:19]
	v_mfma_f32_16x16x32_bf16 v[16:19], v[132:135], v[212:215], v[16:19]
	v_mfma_f32_16x16x32_bf16 v[56:59], v[148:151], v[184:187], v[56:59]
	v_mfma_f32_16x16x32_bf16 v[56:59], v[152:155], v[188:191], v[56:59]
	v_mfma_f32_16x16x32_bf16 v[40:43], v[148:151], v[192:195], v[40:43]
	v_mfma_f32_16x16x32_bf16 v[40:43], v[152:155], v[196:199], v[40:43]
	v_mfma_f32_16x16x32_bf16 v[24:27], v[148:151], v[200:203], v[24:27]
	v_mfma_f32_16x16x32_bf16 v[24:27], v[152:155], v[204:207], v[24:27]
	v_mfma_f32_16x16x32_bf16 v[8:11], v[148:151], v[208:211], v[8:11]
	v_mfma_f32_16x16x32_bf16 v[8:11], v[152:155], v[212:215], v[8:11]
	s_setprio 0
	s_setprio 1
	v_mfma_f32_16x16x32_bf16 v[52:55], v[156:159], v[184:187], v[52:55]
	v_mfma_f32_16x16x32_bf16 v[52:55], v[160:163], v[188:191], v[52:55]
	v_mfma_f32_16x16x32_bf16 v[36:39], v[156:159], v[192:195], v[36:39]
	v_mfma_f32_16x16x32_bf16 v[36:39], v[160:163], v[196:199], v[36:39]
	v_mfma_f32_16x16x32_bf16 v[20:23], v[156:159], v[200:203], v[20:23]
	v_mfma_f32_16x16x32_bf16 v[20:23], v[160:163], v[204:207], v[20:23]
	v_mfma_f32_16x16x32_bf16 v[4:7], v[156:159], v[208:211], v[4:7]
	v_mfma_f32_16x16x32_bf16 v[4:7], v[160:163], v[212:215], v[4:7]
	v_mfma_f32_16x16x32_bf16 v[44:47], v[170:173], v[184:187], v[44:47]
	v_mfma_f32_16x16x32_bf16 v[44:47], v[178:181], v[188:191], v[44:47]
	v_mfma_f32_16x16x32_bf16 v[32:35], v[170:173], v[192:195], v[32:35]
	v_mfma_f32_16x16x32_bf16 v[32:35], v[178:181], v[196:199], v[32:35]
	v_mfma_f32_16x16x32_bf16 v[12:15], v[170:173], v[200:203], v[12:15]
	v_mfma_f32_16x16x32_bf16 v[12:15], v[178:181], v[204:207], v[12:15]
	v_mfma_f32_16x16x32_bf16 v[0:3], v[170:173], v[208:211], v[0:3]
	v_mfma_f32_16x16x32_bf16 v[0:3], v[178:181], v[212:215], v[0:3]
	s_barrier
; #define PG8_STAGE(bufoff, gbase, voff) do { _Pragma("unroll") for (int _i = 0; _i < 2; ++_i) \
;         __builtin_amdgcn_global_load_lds((const unsigned*)((const char*)(gbase) + (voff)[_i]), (PG8_LAS unsigned*)(lds + (bufoff) + ldsw + _i * 8192), 16, 0, 0); } while (0)
; #define PG8_LDA(dst, b, h) do { _Pragma("unroll") for (int m = 0; m < 4; ++m) _Pragma("unroll") for (int k = 0; k < 2; ++k) dst[m][k] = *(const PG8_LAS bf16x8*)(lds + PG8_SA(b, h) + aoff + m * 2048 + k * 1024); } while (0)
; #define PG8_LDB(dst, b, h) do { _Pragma("unroll") for (int n = 0; n < 2; ++n) _Pragma("unroll") for (int k = 0; k < 2; ++k) dst[n][k] = *(const PG8_LAS bf16x8*)(lds + PG8_SB(b, h) + boff + n * 2048 + k * 1024); } while (0)
; #define PG8_MMA(ai, bj, At, Bt) do { __builtin_amdgcn_s_setprio(1); _Pragma("unroll") for (int m = 0; m < 4; ++m) _Pragma("unroll") for (int n = 0; n < 2; ++n) _Pragma("unroll") for (int k = 0; k < 2; ++k) \
;         acc[ai][bj][m][n] = __builtin_amdgcn_mfma_f32_16x16x32_bf16(Bt[n][k], At[m][k], acc[ai][bj][m][n], 0, 0, 0); __builtin_amdgcn_s_setprio(0); } while (0)
; #define PG8_WAIT_V(n) asm volatile("s_waitcnt vmcnt(" #n ")" ::: "memory")
; #define PG8_WAIT_L(n) asm volatile("s_waitcnt lgkmcnt(" #n ")" ::: "memory")
; #define PG8_BAR __builtin_amdgcn_s_barrier()
; #define PG8_SCHED __builtin_amdgcn_sched_barrier(0)
;     ...
;         for (int t = 0; t < nt; t += 2) {
;     ...
;             PG8_LDB(B0, 1, 0); PG8_LDB(B1, 1, 1); PG8_SCHED; PG8_LDA(At, 1, 0); PG8_STAGE(PG8_SA(0, 1), a2 + hstep, voffA);
;             PG8_WAIT_V(8); PG8_WAIT_L(0); PG8_BAR; PG8_MMA(0, 0, At, B0); PG8_MMA(0, 1, At, B1); PG8_BAR; PG8_SCHED;
;             PG8_LDA(At, 1, 1); PG8_STAGE(PG8_SB(1, 0), b3, voffB); PG8_STAGE(PG8_SB(1, 1), b3 + hstep, voffB); PG8_STAGE(PG8_SA(1, 0), a3, voffA);
;             PG8_WAIT_V(8); PG8_WAIT_L(0); PG8_BAR; PG8_MMA(1, 0, At, B0); PG8_MMA(1, 1, At, B1); PG8_BAR; PG8_SCHED;
	s_setprio 0
	s_add_i32 s26, 0, 0x18000
	s_add_i32 s28, 0, 0x1c000
	v_add_u32_e32 v152, s26, v166
	v_add_u32_e32 v168, s28, v166
	ds_read_b128 v[128:131], v152
	ds_read_b128 v[132:135], v152 offset:1024
	ds_read_b128 v[148:151], v152 offset:2048
	ds_read_b128 v[152:155], v152 offset:3072
	ds_read_b128 v[156:159], v168
	ds_read_b128 v[160:163], v168 offset:1024
	ds_read_b128 v[170:173], v168 offset:2048
	ds_read_b128 v[178:181], v168 offset:3072
	s_add_u32 s42, s66, 0x160000
	s_addc_u32 s43, s67, 0
	s_mov_b32 m0, s19
	ds_read_b128 v[184:187], v183 offset:32768
	ds_read_b128 v[188:191], v183 offset:33792
	ds_read_b128 v[192:195], v183 offset:34816
	ds_read_b128 v[196:199], v183 offset:35840
	ds_read_b128 v[200:203], v183 offset:36864
	ds_read_b128 v[204:207], v183 offset:37888
	ds_read_b128 v[208:211], v183 offset:38912
	ds_read_b128 v[212:215], v183 offset:39936
	global_load_lds_dwordx4 v136, s[42:43]
	s_mov_b32 m0, s20
	s_nop 0
	global_load_lds_dwordx4 v140, s[42:43]
	s_waitcnt vmcnt(8)
	s_waitcnt lgkmcnt(0)
	s_barrier
	s_setprio 1
	v_mfma_f32_16x16x32_bf16 v[124:127], v[128:131], v[184:187], v[124:127]
	v_mfma_f32_16x16x32_bf16 v[124:127], v[132:135], v[188:191], v[124:127]
	v_mfma_f32_16x16x32_bf16 v[112:115], v[128:131], v[192:195], v[112:115]
	v_mfma_f32_16x16x32_bf16 v[112:115], v[132:135], v[196:199], v[112:115]
	v_mfma_f32_16x16x32_bf16 v[92:95], v[128:131], v[200:203], v[92:95]
	v_mfma_f32_16x16x32_bf16 v[92:95], v[132:135], v[204:207], v[92:95]
	v_mfma_f32_16x16x32_bf16 v[80:83], v[128:131], v[208:211], v[80:83]
	v_mfma_f32_16x16x32_bf16 v[80:83], v[132:135], v[212:215], v[80:83]
	v_mfma_f32_16x16x32_bf16 v[120:123], v[148:151], v[184:187], v[120:123]
	v_mfma_f32_16x16x32_bf16 v[120:123], v[152:155], v[188:191], v[120:123]
	v_mfma_f32_16x16x32_bf16 v[104:107], v[148:151], v[192:195], v[104:107]
	v_mfma_f32_16x16x32_bf16 v[104:107], v[152:155], v[196:199], v[104:107]
	v_mfma_f32_16x16x32_bf16 v[88:91], v[148:151], v[200:203], v[88:91]
	v_mfma_f32_16x16x32_bf16 v[88:91], v[152:155], v[204:207], v[88:91]
	v_mfma_f32_16x16x32_bf16 v[72:75], v[148:151], v[208:211], v[72:75]
	v_mfma_f32_16x16x32_bf16 v[72:75], v[152:155], v[212:215], v[72:75]
	s_setprio 0
	s_setprio 1
	v_mfma_f32_16x16x32_bf16 v[116:119], v[156:159], v[184:187], v[116:119]
	v_mfma_f32_16x16x32_bf16 v[116:119], v[160:163], v[188:191], v[116:119]
	v_mfma_f32_16x16x32_bf16 v[100:103], v[156:159], v[192:195], v[100:103]
	v_mfma_f32_16x16x32_bf16 v[100:103], v[160:163], v[196:199], v[100:103]
	v_mfma_f32_16x16x32_bf16 v[84:87], v[156:159], v[200:203], v[84:87]
	v_mfma_f32_16x16x32_bf16 v[84:87], v[160:163], v[204:207], v[84:87]
	v_mfma_f32_16x16x32_bf16 v[68:71], v[156:159], v[208:211], v[68:71]
	v_mfma_f32_16x16x32_bf16 v[68:71], v[160:163], v[212:215], v[68:71]
	v_mfma_f32_16x16x32_bf16 v[108:111], v[170:173], v[184:187], v[108:111]
	v_mfma_f32_16x16x32_bf16 v[108:111], v[178:181], v[188:191], v[108:111]
	v_mfma_f32_16x16x32_bf16 v[96:99], v[170:173], v[192:195], v[96:99]
	v_mfma_f32_16x16x32_bf16 v[96:99], v[178:181], v[196:199], v[96:99]
	v_mfma_f32_16x16x32_bf16 v[76:79], v[170:173], v[200:203], v[76:79]
	v_mfma_f32_16x16x32_bf16 v[76:79], v[178:181], v[204:207], v[76:79]
	v_mfma_f32_16x16x32_bf16 v[64:67], v[170:173], v[208:211], v[64:67]
	v_mfma_f32_16x16x32_bf16 v[64:67], v[178:181], v[212:215], v[64:67]
	s_barrier
	s_setprio 0
	s_add_i32 s26, s26, s10
	s_mov_b32 m0, s26
	ds_read_b128 v[184:187], v183 offset:49152
	ds_read_b128 v[188:191], v183 offset:50176
	ds_read_b128 v[192:195], v183 offset:51200
	ds_read_b128 v[196:199], v183 offset:52224
	ds_read_b128 v[200:203], v183 offset:53248
	ds_read_b128 v[204:207], v183 offset:54272
	ds_read_b128 v[208:211], v183 offset:55296
	ds_read_b128 v[212:215], v183 offset:56320
	s_add_u32 s100, s64, s38
	s_addc_u32 s101, s65, s39
	global_load_lds_dwordx4 v138, s[100:101]
	s_add_i32 m0, s26, 0x2000
	s_add_u32 s42, s64, 0x15ff80
	s_addc_u32 s43, s65, 0
	s_add_i32 s26, s28, s10
	global_load_lds_dwordx4 v142, s[100:101]
	s_mov_b32 m0, s26
	s_nop 0
	global_load_lds_dwordx4 v138, s[42:43]
	s_add_i32 m0, s26, 0x2000
	s_nop 0
	global_load_lds_dwordx4 v142, s[42:43]
	s_mov_b32 m0, s12
	s_nop 0
	s_add_u32 s100, s66, s38
	s_addc_u32 s101, s67, s39
	global_load_lds_dwordx4 v136, s[100:101]
	s_mov_b32 m0, s21
	s_nop 0
	global_load_lds_dwordx4 v140, s[100:101]
	s_waitcnt vmcnt(8)
	s_waitcnt lgkmcnt(0)
	s_barrier
	s_setprio 1
	v_mfma_f32_16x16x32_bf16 v[60:63], v[128:131], v[184:187], v[60:63]
	v_mfma_f32_16x16x32_bf16 v[60:63], v[132:135], v[188:191], v[60:63]
	v_mfma_f32_16x16x32_bf16 v[48:51], v[128:131], v[192:195], v[48:51]
	v_mfma_f32_16x16x32_bf16 v[48:51], v[132:135], v[196:199], v[48:51]
	v_mfma_f32_16x16x32_bf16 v[28:31], v[128:131], v[200:203], v[28:31]
	v_mfma_f32_16x16x32_bf16 v[28:31], v[132:135], v[204:207], v[28:31]
	v_mfma_f32_16x16x32_bf16 v[16:19], v[128:131], v[208:211], v[16:19]
	v_mfma_f32_16x16x32_bf16 v[16:19], v[132:135], v[212:215], v[16:19]
	v_mfma_f32_16x16x32_bf16 v[56:59], v[148:151], v[184:187], v[56:59]
	v_mfma_f32_16x16x32_bf16 v[56:59], v[152:155], v[188:191], v[56:59]
	v_mfma_f32_16x16x32_bf16 v[40:43], v[148:151], v[192:195], v[40:43]
	v_mfma_f32_16x16x32_bf16 v[40:43], v[152:155], v[196:199], v[40:43]
	v_mfma_f32_16x16x32_bf16 v[24:27], v[148:151], v[200:203], v[24:27]
	v_mfma_f32_16x16x32_bf16 v[24:27], v[152:155], v[204:207], v[24:27]
	v_mfma_f32_16x16x32_bf16 v[8:11], v[148:151], v[208:211], v[8:11]
	v_mfma_f32_16x16x32_bf16 v[8:11], v[152:155], v[212:215], v[8:11]
	s_setprio 0
	s_setprio 1
	v_mfma_f32_16x16x32_bf16 v[52:55], v[156:159], v[184:187], v[52:55]
	v_mfma_f32_16x16x32_bf16 v[52:55], v[160:163], v[188:191], v[52:55]
	v_mfma_f32_16x16x32_bf16 v[36:39], v[156:159], v[192:195], v[36:39]
	v_mfma_f32_16x16x32_bf16 v[36:39], v[160:163], v[196:199], v[36:39]
	v_mfma_f32_16x16x32_bf16 v[20:23], v[156:159], v[200:203], v[20:23]
	v_mfma_f32_16x16x32_bf16 v[20:23], v[160:163], v[204:207], v[20:23]
	v_mfma_f32_16x16x32_bf16 v[4:7], v[156:159], v[208:211], v[4:7]
	v_mfma_f32_16x16x32_bf16 v[4:7], v[160:163], v[212:215], v[4:7]
	v_mfma_f32_16x16x32_bf16 v[44:47], v[170:173], v[184:187], v[44:47]
	v_mfma_f32_16x16x32_bf16 v[44:47], v[178:181], v[188:191], v[44:47]
	v_mfma_f32_16x16x32_bf16 v[32:35], v[170:173], v[192:195], v[32:35]
	v_mfma_f32_16x16x32_bf16 v[32:35], v[178:181], v[196:199], v[32:35]
	v_mfma_f32_16x16x32_bf16 v[12:15], v[170:173], v[200:203], v[12:15]
	v_mfma_f32_16x16x32_bf16 v[12:15], v[178:181], v[204:207], v[12:15]
	v_mfma_f32_16x16x32_bf16 v[0:3], v[170:173], v[208:211], v[0:3]
	v_mfma_f32_16x16x32_bf16 v[0:3], v[178:181], v[212:215], v[0:3]
	s_barrier
	s_setprio 0
	s_add_i32 s3, s3, 2
	s_add_u32 s2, s2, 0xffffff00
	s_addc_u32 s25, s25, -1
	s_cmpk_gt_u32 s3, 0x55
	s_mov_b64 s[60:61], s[62:63]
	s_cbranch_scc0 .LBB0_1066
	s_and_b64 vcc, exec, s[56:57]
	s_cbranch_vccz .LBB0_1069
	s_barrier
